# GEMM k-loops on v_mfma_f32_16x16x32_bf16 (same bf16 operands, f32 accumulate) with a per-tile accumulator re-layout through LDS to the 32x32 layout
# baseline (speedup 1.0000x reference)
.LBB0_258:
	s_mul_hi_i32 s4, s3, 0x2aaaaaab
	s_lshr_b32 s5, s4, 31
	s_ashr_i32 s4, s4, 3
	s_add_i32 s4, s4, s5
	s_mul_i32 s95, s4, 0xffffffd0
	s_add_i32 s95, s95, s3
	s_lshl_b32 s5, s4, 3
	s_ashr_i32 s4, s95, 31
	s_lshr_b32 s4, s4, 29
	s_add_i32 s4, s95, s4
	s_ashr_i32 s10, s4, 3
	s_and_b32 s4, s4, -8
	s_sub_i32 s8, s95, s4
	s_add_i32 s8, s8, s5
	s_lshl_b32 s76, s8, 7
	s_ashr_i32 s77, s76, 31
	s_lshl_b32 s78, s10, 7
	s_lshl_b64 s[4:5], s[76:77], 11
	s_ashr_i32 s79, s78, 31
	s_lshl_b32 s56, s76, 11
	s_add_u32 s38, s14, s56
	s_addc_u32 s39, s15, 0
	s_add_u32 s38, s38, 0x679f000
	s_addc_u32 s39, s39, 0
	s_add_u32 s40, s38, 0x10000
	s_addc_u32 s41, s39, 0
	s_add_u32 s42, s40, 0x10000
	s_addc_u32 s43, s41, 0
	s_add_u32 s44, s42, 0x10000
	s_addc_u32 s45, s43, 0
	s_lshl_b32 s56, s78, 11
	s_add_u32 s46, s14, s56
	s_addc_u32 s47, s15, 0
	s_add_u32 s46, s46, 0x0
	s_addc_u32 s47, s47, 0
	s_add_u32 s48, s46, 0x10000
	s_addc_u32 s49, s47, 0
	s_add_u32 s50, s48, 0x10000
	s_addc_u32 s51, s49, 0
	s_add_u32 s52, s50, 0x10000
	s_addc_u32 s53, s51, 0
	v_and_b32_e32 v64, 15, v199
	v_bfe_u32 v65, v199, 4, 2
	v_lshrrev_b32_e32 v66, 1, v64
	v_xor_b32_e32 v65, v65, v66
	v_lshlrev_b32_e32 v65, 4, v65
	v_lshl_or_b32 v65, v64, 7, v65
	v_lshrrev_b32_e32 v66, 6, v199
	v_lshl_add_u32 v221, v66, 12, v65
	v_xor_b32_e32 v226, 64, v221
	v_add_u32_e32 v227, 0x4000, v65
	v_xor_b32_e32 v229, 64, v227
	v_readfirstlane_b32 s54, v192
	v_mov_b32_e32 v254, v158
	s_mov_b32 m0, s54
	s_nop 0
	global_load_lds_dwordx4 v254, s[38:39]
	s_add_u32 m0, m0, 0x1000
	s_nop 0
	global_load_lds_dwordx4 v254, s[40:41]
	s_add_u32 m0, m0, 0x1000
	s_nop 0
	global_load_lds_dwordx4 v254, s[42:43]
	s_add_u32 m0, m0, 0x1000
	s_nop 0
	global_load_lds_dwordx4 v254, s[44:45]
	s_add_u32 m0, m0, 0x1000
	s_nop 0
	global_load_lds_dwordx4 v254, s[46:47]
	s_add_u32 m0, m0, 0x1000
	s_nop 0
	global_load_lds_dwordx4 v254, s[48:49]
	s_add_u32 m0, m0, 0x1000
	s_nop 0
	global_load_lds_dwordx4 v254, s[50:51]
	s_add_u32 m0, m0, 0x1000
	s_nop 0
	global_load_lds_dwordx4 v254, s[52:53]
	v_add_u32_e32 v254, 0x80, v254
	s_add_u32 m0, s54, 0x8000
	s_nop 0
	global_load_lds_dwordx4 v254, s[38:39]
	s_add_u32 m0, m0, 0x1000
	s_nop 0
	global_load_lds_dwordx4 v254, s[40:41]
	s_add_u32 m0, m0, 0x1000
	s_nop 0
	global_load_lds_dwordx4 v254, s[42:43]
	s_add_u32 m0, m0, 0x1000
	s_nop 0
	global_load_lds_dwordx4 v254, s[44:45]
	s_add_u32 m0, m0, 0x1000
	s_nop 0
	global_load_lds_dwordx4 v254, s[46:47]
	s_add_u32 m0, m0, 0x1000
	s_nop 0
	global_load_lds_dwordx4 v254, s[48:49]
	s_add_u32 m0, m0, 0x1000
	s_nop 0
	global_load_lds_dwordx4 v254, s[50:51]
	s_add_u32 m0, m0, 0x1000
	s_nop 0
	global_load_lds_dwordx4 v254, s[52:53]
	v_add_u32_e32 v254, 0x80, v254
	v_mov_b32_e32 v48, 0
	v_mov_b32_e32 v49, 0
	v_mov_b32_e32 v50, 0
	v_mov_b32_e32 v51, 0
	v_mov_b32_e32 v52, 0
	v_mov_b32_e32 v53, 0
	v_mov_b32_e32 v54, 0
	v_mov_b32_e32 v55, 0
	v_mov_b32_e32 v56, 0
	v_mov_b32_e32 v57, 0
	v_mov_b32_e32 v58, 0
	v_mov_b32_e32 v59, 0
	v_mov_b32_e32 v60, 0
	v_mov_b32_e32 v61, 0
	v_mov_b32_e32 v62, 0
	v_mov_b32_e32 v63, 0
	v_mov_b32_e32 v32, 0
	v_mov_b32_e32 v33, 0
	v_mov_b32_e32 v34, 0
	v_mov_b32_e32 v35, 0
	v_mov_b32_e32 v36, 0
	v_mov_b32_e32 v37, 0
	v_mov_b32_e32 v38, 0
	v_mov_b32_e32 v39, 0
	v_mov_b32_e32 v40, 0
	v_mov_b32_e32 v41, 0
	v_mov_b32_e32 v42, 0
	v_mov_b32_e32 v43, 0
	v_mov_b32_e32 v44, 0
	v_mov_b32_e32 v45, 0
	v_mov_b32_e32 v46, 0
	v_mov_b32_e32 v47, 0
	v_mov_b32_e32 v16, 0
	v_mov_b32_e32 v17, 0
	v_mov_b32_e32 v18, 0
	v_mov_b32_e32 v19, 0
	v_mov_b32_e32 v20, 0
	v_mov_b32_e32 v21, 0
	v_mov_b32_e32 v22, 0
	v_mov_b32_e32 v23, 0
	v_mov_b32_e32 v24, 0
	v_mov_b32_e32 v25, 0
	v_mov_b32_e32 v26, 0
	v_mov_b32_e32 v27, 0
	v_mov_b32_e32 v28, 0
	v_mov_b32_e32 v29, 0
	v_mov_b32_e32 v30, 0
	v_mov_b32_e32 v31, 0
	v_mov_b32_e32 v0, 0
	v_mov_b32_e32 v1, 0
	v_mov_b32_e32 v2, 0
	v_mov_b32_e32 v3, 0
	v_mov_b32_e32 v4, 0
	v_mov_b32_e32 v5, 0
	v_mov_b32_e32 v6, 0
	v_mov_b32_e32 v7, 0
	v_mov_b32_e32 v8, 0
	v_mov_b32_e32 v9, 0
	v_mov_b32_e32 v10, 0
	v_mov_b32_e32 v11, 0
	v_mov_b32_e32 v12, 0
	v_mov_b32_e32 v13, 0
	v_mov_b32_e32 v14, 0
	v_mov_b32_e32 v15, 0
	s_mov_b32 s55, 7
.Lgk_loop_p2:
	s_waitcnt vmcnt(8)
	s_barrier
	ds_read_b128 v[64:67], v221
	ds_read_b128 v[68:71], v221 offset:2048
	ds_read_b128 v[80:83], v227
	ds_read_b128 v[84:87], v227 offset:2048
	ds_read_b128 v[88:91], v227 offset:4096
	ds_read_b128 v[92:95], v227 offset:6144
	ds_read_b128 v[96:99], v227 offset:8192
	ds_read_b128 v[100:103], v227 offset:10240
	ds_read_b128 v[104:107], v227 offset:12288
	ds_read_b128 v[108:111], v227 offset:14336
	ds_read_b128 v[72:75], v226
	ds_read_b128 v[76:79], v226 offset:2048
	ds_read_b128 v[112:115], v229
	ds_read_b128 v[222:225], v229 offset:2048
	ds_read_b128 v[230:233], v229 offset:4096
	ds_read_b128 v[234:237], v229 offset:6144
	ds_read_b128 v[238:241], v229 offset:8192
	ds_read_b128 v[242:245], v229 offset:10240
	ds_read_b128 v[246:249], v229 offset:12288
	ds_read_b128 v[250:253], v229 offset:14336
	s_waitcnt lgkmcnt(0)
	s_barrier
	s_mov_b32 m0, s54
	s_setprio 1
	v_mfma_f32_16x16x32_bf16 v[0:3], v[64:67], v[80:83], v[0:3]
	v_mfma_f32_16x16x32_bf16 v[4:7], v[64:67], v[84:87], v[4:7]
	v_mfma_f32_16x16x32_bf16 v[8:11], v[64:67], v[88:91], v[8:11]
	v_mfma_f32_16x16x32_bf16 v[12:15], v[64:67], v[92:95], v[12:15]
	global_load_lds_dwordx4 v254, s[38:39]
	s_add_u32 m0, m0, 0x1000
	v_mfma_f32_16x16x32_bf16 v[16:19], v[64:67], v[96:99], v[16:19]
	v_mfma_f32_16x16x32_bf16 v[20:23], v[64:67], v[100:103], v[20:23]
	v_mfma_f32_16x16x32_bf16 v[24:27], v[64:67], v[104:107], v[24:27]
	v_mfma_f32_16x16x32_bf16 v[28:31], v[64:67], v[108:111], v[28:31]
	global_load_lds_dwordx4 v254, s[40:41]
	s_add_u32 m0, m0, 0x1000
	v_mfma_f32_16x16x32_bf16 v[32:35], v[68:71], v[80:83], v[32:35]
	v_mfma_f32_16x16x32_bf16 v[36:39], v[68:71], v[84:87], v[36:39]
	v_mfma_f32_16x16x32_bf16 v[40:43], v[68:71], v[88:91], v[40:43]
	v_mfma_f32_16x16x32_bf16 v[44:47], v[68:71], v[92:95], v[44:47]
	global_load_lds_dwordx4 v254, s[42:43]
	s_add_u32 m0, m0, 0x1000
	v_mfma_f32_16x16x32_bf16 v[48:51], v[68:71], v[96:99], v[48:51]
	v_mfma_f32_16x16x32_bf16 v[52:55], v[68:71], v[100:103], v[52:55]
	v_mfma_f32_16x16x32_bf16 v[56:59], v[68:71], v[104:107], v[56:59]
	v_mfma_f32_16x16x32_bf16 v[60:63], v[68:71], v[108:111], v[60:63]
	global_load_lds_dwordx4 v254, s[44:45]
	s_add_u32 m0, m0, 0x1000
	v_mfma_f32_16x16x32_bf16 v[0:3], v[72:75], v[112:115], v[0:3]
	v_mfma_f32_16x16x32_bf16 v[4:7], v[72:75], v[222:225], v[4:7]
	v_mfma_f32_16x16x32_bf16 v[8:11], v[72:75], v[230:233], v[8:11]
	v_mfma_f32_16x16x32_bf16 v[12:15], v[72:75], v[234:237], v[12:15]
	global_load_lds_dwordx4 v254, s[46:47]
	s_add_u32 m0, m0, 0x1000
	v_mfma_f32_16x16x32_bf16 v[16:19], v[72:75], v[238:241], v[16:19]
	v_mfma_f32_16x16x32_bf16 v[20:23], v[72:75], v[242:245], v[20:23]
	v_mfma_f32_16x16x32_bf16 v[24:27], v[72:75], v[246:249], v[24:27]
	v_mfma_f32_16x16x32_bf16 v[28:31], v[72:75], v[250:253], v[28:31]
	global_load_lds_dwordx4 v254, s[48:49]
	s_add_u32 m0, m0, 0x1000
	v_mfma_f32_16x16x32_bf16 v[32:35], v[76:79], v[112:115], v[32:35]
	v_mfma_f32_16x16x32_bf16 v[36:39], v[76:79], v[222:225], v[36:39]
	v_mfma_f32_16x16x32_bf16 v[40:43], v[76:79], v[230:233], v[40:43]
	v_mfma_f32_16x16x32_bf16 v[44:47], v[76:79], v[234:237], v[44:47]
	global_load_lds_dwordx4 v254, s[50:51]
	s_add_u32 m0, m0, 0x1000
	v_mfma_f32_16x16x32_bf16 v[48:51], v[76:79], v[238:241], v[48:51]
	v_mfma_f32_16x16x32_bf16 v[52:55], v[76:79], v[242:245], v[52:55]
	v_mfma_f32_16x16x32_bf16 v[56:59], v[76:79], v[246:249], v[56:59]
	v_mfma_f32_16x16x32_bf16 v[60:63], v[76:79], v[250:253], v[60:63]
	global_load_lds_dwordx4 v254, s[52:53]
	s_setprio 0
	v_add_u32_e32 v254, 0x80, v254
	s_waitcnt vmcnt(8)
	s_barrier
	ds_read_b128 v[64:67], v221 offset:32768
	ds_read_b128 v[68:71], v221 offset:34816
	ds_read_b128 v[80:83], v227 offset:32768
	ds_read_b128 v[84:87], v227 offset:34816
	ds_read_b128 v[88:91], v227 offset:36864
	ds_read_b128 v[92:95], v227 offset:38912
	ds_read_b128 v[96:99], v227 offset:40960
	ds_read_b128 v[100:103], v227 offset:43008
	ds_read_b128 v[104:107], v227 offset:45056
	ds_read_b128 v[108:111], v227 offset:47104
	ds_read_b128 v[72:75], v226 offset:32768
	ds_read_b128 v[76:79], v226 offset:34816
	ds_read_b128 v[112:115], v229 offset:32768
	ds_read_b128 v[222:225], v229 offset:34816
	ds_read_b128 v[230:233], v229 offset:36864
	ds_read_b128 v[234:237], v229 offset:38912
	ds_read_b128 v[238:241], v229 offset:40960
	ds_read_b128 v[242:245], v229 offset:43008
	ds_read_b128 v[246:249], v229 offset:45056
	ds_read_b128 v[250:253], v229 offset:47104
	s_waitcnt lgkmcnt(0)
	s_barrier
	s_add_u32 m0, s54, 0x8000
	s_setprio 1
	v_mfma_f32_16x16x32_bf16 v[0:3], v[64:67], v[80:83], v[0:3]
	v_mfma_f32_16x16x32_bf16 v[4:7], v[64:67], v[84:87], v[4:7]
	v_mfma_f32_16x16x32_bf16 v[8:11], v[64:67], v[88:91], v[8:11]
	v_mfma_f32_16x16x32_bf16 v[12:15], v[64:67], v[92:95], v[12:15]
	global_load_lds_dwordx4 v254, s[38:39]
	s_add_u32 m0, m0, 0x1000
	v_mfma_f32_16x16x32_bf16 v[16:19], v[64:67], v[96:99], v[16:19]
	v_mfma_f32_16x16x32_bf16 v[20:23], v[64:67], v[100:103], v[20:23]
	v_mfma_f32_16x16x32_bf16 v[24:27], v[64:67], v[104:107], v[24:27]
	v_mfma_f32_16x16x32_bf16 v[28:31], v[64:67], v[108:111], v[28:31]
	global_load_lds_dwordx4 v254, s[40:41]
	s_add_u32 m0, m0, 0x1000
	v_mfma_f32_16x16x32_bf16 v[32:35], v[68:71], v[80:83], v[32:35]
	v_mfma_f32_16x16x32_bf16 v[36:39], v[68:71], v[84:87], v[36:39]
	v_mfma_f32_16x16x32_bf16 v[40:43], v[68:71], v[88:91], v[40:43]
	v_mfma_f32_16x16x32_bf16 v[44:47], v[68:71], v[92:95], v[44:47]
	global_load_lds_dwordx4 v254, s[42:43]
	s_add_u32 m0, m0, 0x1000
	v_mfma_f32_16x16x32_bf16 v[48:51], v[68:71], v[96:99], v[48:51]
	v_mfma_f32_16x16x32_bf16 v[52:55], v[68:71], v[100:103], v[52:55]
	v_mfma_f32_16x16x32_bf16 v[56:59], v[68:71], v[104:107], v[56:59]
	v_mfma_f32_16x16x32_bf16 v[60:63], v[68:71], v[108:111], v[60:63]
	global_load_lds_dwordx4 v254, s[44:45]
	s_add_u32 m0, m0, 0x1000
	v_mfma_f32_16x16x32_bf16 v[0:3], v[72:75], v[112:115], v[0:3]
	v_mfma_f32_16x16x32_bf16 v[4:7], v[72:75], v[222:225], v[4:7]
	v_mfma_f32_16x16x32_bf16 v[8:11], v[72:75], v[230:233], v[8:11]
	v_mfma_f32_16x16x32_bf16 v[12:15], v[72:75], v[234:237], v[12:15]
	global_load_lds_dwordx4 v254, s[46:47]
	s_add_u32 m0, m0, 0x1000
	v_mfma_f32_16x16x32_bf16 v[16:19], v[72:75], v[238:241], v[16:19]
	v_mfma_f32_16x16x32_bf16 v[20:23], v[72:75], v[242:245], v[20:23]
	v_mfma_f32_16x16x32_bf16 v[24:27], v[72:75], v[246:249], v[24:27]
	v_mfma_f32_16x16x32_bf16 v[28:31], v[72:75], v[250:253], v[28:31]
	global_load_lds_dwordx4 v254, s[48:49]
	s_add_u32 m0, m0, 0x1000
	v_mfma_f32_16x16x32_bf16 v[32:35], v[76:79], v[112:115], v[32:35]
	v_mfma_f32_16x16x32_bf16 v[36:39], v[76:79], v[222:225], v[36:39]
	v_mfma_f32_16x16x32_bf16 v[40:43], v[76:79], v[230:233], v[40:43]
	v_mfma_f32_16x16x32_bf16 v[44:47], v[76:79], v[234:237], v[44:47]
	global_load_lds_dwordx4 v254, s[50:51]
	s_add_u32 m0, m0, 0x1000
	v_mfma_f32_16x16x32_bf16 v[48:51], v[76:79], v[238:241], v[48:51]
	v_mfma_f32_16x16x32_bf16 v[52:55], v[76:79], v[242:245], v[52:55]
	v_mfma_f32_16x16x32_bf16 v[56:59], v[76:79], v[246:249], v[56:59]
	v_mfma_f32_16x16x32_bf16 v[60:63], v[76:79], v[250:253], v[60:63]
	global_load_lds_dwordx4 v254, s[52:53]
	s_setprio 0
	v_add_u32_e32 v254, 0x80, v254
	s_sub_u32 s55, s55, 1
	s_cmp_lg_u32 s55, 0
	s_cbranch_scc1 .Lgk_loop_p2
	s_waitcnt vmcnt(8)
	s_barrier
	ds_read_b128 v[64:67], v221
	ds_read_b128 v[68:71], v221 offset:2048
	ds_read_b128 v[80:83], v227
	ds_read_b128 v[84:87], v227 offset:2048
	ds_read_b128 v[88:91], v227 offset:4096
	ds_read_b128 v[92:95], v227 offset:6144
	ds_read_b128 v[96:99], v227 offset:8192
	ds_read_b128 v[100:103], v227 offset:10240
	ds_read_b128 v[104:107], v227 offset:12288
	ds_read_b128 v[108:111], v227 offset:14336
	ds_read_b128 v[72:75], v226
	ds_read_b128 v[76:79], v226 offset:2048
	ds_read_b128 v[112:115], v229
	ds_read_b128 v[222:225], v229 offset:2048
	ds_read_b128 v[230:233], v229 offset:4096
	ds_read_b128 v[234:237], v229 offset:6144
	ds_read_b128 v[238:241], v229 offset:8192
	ds_read_b128 v[242:245], v229 offset:10240
	ds_read_b128 v[246:249], v229 offset:12288
	ds_read_b128 v[250:253], v229 offset:14336
	s_waitcnt lgkmcnt(0)
	s_barrier
	s_setprio 1
	v_mfma_f32_16x16x32_bf16 v[0:3], v[64:67], v[80:83], v[0:3]
	v_mfma_f32_16x16x32_bf16 v[4:7], v[64:67], v[84:87], v[4:7]
	v_mfma_f32_16x16x32_bf16 v[8:11], v[64:67], v[88:91], v[8:11]
	v_mfma_f32_16x16x32_bf16 v[12:15], v[64:67], v[92:95], v[12:15]
	v_mfma_f32_16x16x32_bf16 v[16:19], v[64:67], v[96:99], v[16:19]
	v_mfma_f32_16x16x32_bf16 v[20:23], v[64:67], v[100:103], v[20:23]
	v_mfma_f32_16x16x32_bf16 v[24:27], v[64:67], v[104:107], v[24:27]
	v_mfma_f32_16x16x32_bf16 v[28:31], v[64:67], v[108:111], v[28:31]
	v_mfma_f32_16x16x32_bf16 v[32:35], v[68:71], v[80:83], v[32:35]
	v_mfma_f32_16x16x32_bf16 v[36:39], v[68:71], v[84:87], v[36:39]
	v_mfma_f32_16x16x32_bf16 v[40:43], v[68:71], v[88:91], v[40:43]
	v_mfma_f32_16x16x32_bf16 v[44:47], v[68:71], v[92:95], v[44:47]
	v_mfma_f32_16x16x32_bf16 v[48:51], v[68:71], v[96:99], v[48:51]
	v_mfma_f32_16x16x32_bf16 v[52:55], v[68:71], v[100:103], v[52:55]
	v_mfma_f32_16x16x32_bf16 v[56:59], v[68:71], v[104:107], v[56:59]
	v_mfma_f32_16x16x32_bf16 v[60:63], v[68:71], v[108:111], v[60:63]
	v_mfma_f32_16x16x32_bf16 v[0:3], v[72:75], v[112:115], v[0:3]
	v_mfma_f32_16x16x32_bf16 v[4:7], v[72:75], v[222:225], v[4:7]
	v_mfma_f32_16x16x32_bf16 v[8:11], v[72:75], v[230:233], v[8:11]
	v_mfma_f32_16x16x32_bf16 v[12:15], v[72:75], v[234:237], v[12:15]
	v_mfma_f32_16x16x32_bf16 v[16:19], v[72:75], v[238:241], v[16:19]
	v_mfma_f32_16x16x32_bf16 v[20:23], v[72:75], v[242:245], v[20:23]
	v_mfma_f32_16x16x32_bf16 v[24:27], v[72:75], v[246:249], v[24:27]
	v_mfma_f32_16x16x32_bf16 v[28:31], v[72:75], v[250:253], v[28:31]
	v_mfma_f32_16x16x32_bf16 v[32:35], v[76:79], v[112:115], v[32:35]
	v_mfma_f32_16x16x32_bf16 v[36:39], v[76:79], v[222:225], v[36:39]
	v_mfma_f32_16x16x32_bf16 v[40:43], v[76:79], v[230:233], v[40:43]
	v_mfma_f32_16x16x32_bf16 v[44:47], v[76:79], v[234:237], v[44:47]
	v_mfma_f32_16x16x32_bf16 v[48:51], v[76:79], v[238:241], v[48:51]
	v_mfma_f32_16x16x32_bf16 v[52:55], v[76:79], v[242:245], v[52:55]
	v_mfma_f32_16x16x32_bf16 v[56:59], v[76:79], v[246:249], v[56:59]
	v_mfma_f32_16x16x32_bf16 v[60:63], v[76:79], v[250:253], v[60:63]
	s_setprio 0
	s_waitcnt vmcnt(0)
	s_barrier
	ds_read_b128 v[64:67], v221 offset:32768
	ds_read_b128 v[68:71], v221 offset:34816
	ds_read_b128 v[80:83], v227 offset:32768
	ds_read_b128 v[84:87], v227 offset:34816
	ds_read_b128 v[88:91], v227 offset:36864
	ds_read_b128 v[92:95], v227 offset:38912
	ds_read_b128 v[96:99], v227 offset:40960
	ds_read_b128 v[100:103], v227 offset:43008
	ds_read_b128 v[104:107], v227 offset:45056
	ds_read_b128 v[108:111], v227 offset:47104
	ds_read_b128 v[72:75], v226 offset:32768
	ds_read_b128 v[76:79], v226 offset:34816
	ds_read_b128 v[112:115], v229 offset:32768
	ds_read_b128 v[222:225], v229 offset:34816
	ds_read_b128 v[230:233], v229 offset:36864
	ds_read_b128 v[234:237], v229 offset:38912
	ds_read_b128 v[238:241], v229 offset:40960
	ds_read_b128 v[242:245], v229 offset:43008
	ds_read_b128 v[246:249], v229 offset:45056
	ds_read_b128 v[250:253], v229 offset:47104
	s_waitcnt lgkmcnt(0)
	s_barrier
	s_setprio 1
	v_mfma_f32_16x16x32_bf16 v[0:3], v[64:67], v[80:83], v[0:3]
	v_mfma_f32_16x16x32_bf16 v[4:7], v[64:67], v[84:87], v[4:7]
	v_mfma_f32_16x16x32_bf16 v[8:11], v[64:67], v[88:91], v[8:11]
	v_mfma_f32_16x16x32_bf16 v[12:15], v[64:67], v[92:95], v[12:15]
	v_mfma_f32_16x16x32_bf16 v[16:19], v[64:67], v[96:99], v[16:19]
	v_mfma_f32_16x16x32_bf16 v[20:23], v[64:67], v[100:103], v[20:23]
	v_mfma_f32_16x16x32_bf16 v[24:27], v[64:67], v[104:107], v[24:27]
	v_mfma_f32_16x16x32_bf16 v[28:31], v[64:67], v[108:111], v[28:31]
	v_mfma_f32_16x16x32_bf16 v[32:35], v[68:71], v[80:83], v[32:35]
	v_mfma_f32_16x16x32_bf16 v[36:39], v[68:71], v[84:87], v[36:39]
	v_mfma_f32_16x16x32_bf16 v[40:43], v[68:71], v[88:91], v[40:43]
	v_mfma_f32_16x16x32_bf16 v[44:47], v[68:71], v[92:95], v[44:47]
	v_mfma_f32_16x16x32_bf16 v[48:51], v[68:71], v[96:99], v[48:51]
	v_mfma_f32_16x16x32_bf16 v[52:55], v[68:71], v[100:103], v[52:55]
	v_mfma_f32_16x16x32_bf16 v[56:59], v[68:71], v[104:107], v[56:59]
	v_mfma_f32_16x16x32_bf16 v[60:63], v[68:71], v[108:111], v[60:63]
	v_mfma_f32_16x16x32_bf16 v[0:3], v[72:75], v[112:115], v[0:3]
	v_mfma_f32_16x16x32_bf16 v[4:7], v[72:75], v[222:225], v[4:7]
	v_mfma_f32_16x16x32_bf16 v[8:11], v[72:75], v[230:233], v[8:11]
	v_mfma_f32_16x16x32_bf16 v[12:15], v[72:75], v[234:237], v[12:15]
	v_mfma_f32_16x16x32_bf16 v[16:19], v[72:75], v[238:241], v[16:19]
	v_mfma_f32_16x16x32_bf16 v[20:23], v[72:75], v[242:245], v[20:23]
	v_mfma_f32_16x16x32_bf16 v[24:27], v[72:75], v[246:249], v[24:27]
	v_mfma_f32_16x16x32_bf16 v[28:31], v[72:75], v[250:253], v[28:31]
	v_mfma_f32_16x16x32_bf16 v[32:35], v[76:79], v[112:115], v[32:35]
	v_mfma_f32_16x16x32_bf16 v[36:39], v[76:79], v[222:225], v[36:39]
	v_mfma_f32_16x16x32_bf16 v[40:43], v[76:79], v[230:233], v[40:43]
	v_mfma_f32_16x16x32_bf16 v[44:47], v[76:79], v[234:237], v[44:47]
	v_mfma_f32_16x16x32_bf16 v[48:51], v[76:79], v[238:241], v[48:51]
	v_mfma_f32_16x16x32_bf16 v[52:55], v[76:79], v[242:245], v[52:55]
	v_mfma_f32_16x16x32_bf16 v[56:59], v[76:79], v[246:249], v[56:59]
	v_mfma_f32_16x16x32_bf16 v[60:63], v[76:79], v[250:253], v[60:63]
	s_setprio 0
	s_nop 7
	s_nop 7
	v_and_b32_e32 v66, 63, v199
	v_lshrrev_b32_e32 v67, 6, v199
	v_lshlrev_b32_e32 v67, 14, v67
	v_lshl_add_u32 v64, v66, 4, v67
	v_and_b32_e32 v65, 15, v66
	v_lshl_add_u32 v65, v65, 4, v67
	v_bfe_u32 v67, v66, 4, 1
	v_lshl_add_u32 v65, v67, 10, v65
	v_bfe_u32 v67, v66, 5, 1
	v_lshl_add_u32 v65, v67, 8, v65
	ds_write_b128 v64, v[0:3]
	ds_write_b128 v64, v[4:7] offset:1024
	ds_write_b128 v64, v[8:11] offset:2048
	ds_write_b128 v64, v[12:15] offset:3072
	ds_write_b128 v64, v[16:19] offset:4096
	ds_write_b128 v64, v[20:23] offset:5120
	ds_write_b128 v64, v[24:27] offset:6144
	ds_write_b128 v64, v[28:31] offset:7168
	ds_write_b128 v64, v[32:35] offset:8192
	ds_write_b128 v64, v[36:39] offset:9216
	ds_write_b128 v64, v[40:43] offset:10240
	ds_write_b128 v64, v[44:47] offset:11264
	ds_write_b128 v64, v[48:51] offset:12288
	ds_write_b128 v64, v[52:55] offset:13312
	ds_write_b128 v64, v[56:59] offset:14336
	ds_write_b128 v64, v[60:63] offset:15360
	s_waitcnt lgkmcnt(0)
	ds_read_b128 v[48:51], v65
	ds_read_b128 v[52:55], v65 offset:512
	ds_read_b128 v[56:59], v65 offset:8192
	ds_read_b128 v[60:63], v65 offset:8704
	ds_read_b128 v[32:35], v65 offset:2048
	ds_read_b128 v[36:39], v65 offset:2560
	ds_read_b128 v[40:43], v65 offset:10240
	ds_read_b128 v[44:47], v65 offset:10752
	ds_read_b128 v[16:19], v65 offset:4096
	ds_read_b128 v[20:23], v65 offset:4608
	ds_read_b128 v[24:27], v65 offset:12288
	ds_read_b128 v[28:31], v65 offset:12800
	ds_read_b128 v[0:3], v65 offset:6144
	ds_read_b128 v[4:7], v65 offset:6656
	ds_read_b128 v[8:11], v65 offset:14336
	ds_read_b128 v[12:15], v65 offset:14848
	s_waitcnt lgkmcnt(0)
	s_barrier
	s_branch .LBB0_262

.LBB0_703:
	s_ashr_i32 s6, s3, 31
	s_lshr_b32 s6, s6, 26
	s_add_i32 s6, s3, s6
	s_ashr_i32 s58, s6, 6
	s_andn2_b32 s6, s6, 63
	s_sub_i32 s6, s3, s6
	s_ashr_i32 s59, s6, 31
	s_lshr_b32 s59, s59, 29
	s_add_i32 s59, s6, s59
	s_ashr_i32 s69, s59, 3
	s_and_b32 s59, s59, -8
	s_lshl_b32 s58, s58, 3
	s_sub_i32 s6, s6, s59
	s_add_i32 s6, s6, s58
	s_lshl_b32 s64, s6, 7
	s_ashr_i32 s65, s64, 31
	s_lshl_b32 s66, s69, 7
	s_lshl_b64 s[58:59], s[64:65], 11
	s_ashr_i32 s67, s66, 31
	s_lshl_b32 s38, s64, 11
	s_add_u32 s18, s14, s38
	s_addc_u32 s19, s15, 0
	s_add_u32 s18, s18, 0xb79f000
	s_addc_u32 s19, s19, 0
	s_add_u32 s20, s18, 0x10000
	s_addc_u32 s21, s19, 0
	s_add_u32 s22, s20, 0x10000
	s_addc_u32 s23, s21, 0
	s_add_u32 s24, s22, 0x10000
	s_addc_u32 s25, s23, 0
	s_lshl_b32 s38, s66, 11
	s_add_u32 s26, s14, s38
	s_addc_u32 s27, s15, 0
	s_add_u32 s26, s26, 0x3a0000
	s_addc_u32 s27, s27, 0
	s_add_u32 s28, s26, 0x10000
	s_addc_u32 s29, s27, 0
	s_add_u32 s30, s28, 0x10000
	s_addc_u32 s31, s29, 0
	s_add_u32 s34, s30, 0x10000
	s_addc_u32 s35, s31, 0
	v_and_b32_e32 v70, 15, v199
	v_bfe_u32 v71, v199, 4, 2
	v_lshrrev_b32_e32 v72, 1, v70
	v_xor_b32_e32 v71, v71, v72
	v_lshlrev_b32_e32 v71, 4, v71
	v_lshl_or_b32 v71, v70, 7, v71
	v_lshrrev_b32_e32 v72, 6, v199
	v_lshl_add_u32 v205, v72, 12, v71
	v_xor_b32_e32 v242, 64, v205
	v_add_u32_e32 v243, 0x4000, v71
	v_xor_b32_e32 v244, 64, v243
	v_readfirstlane_b32 s36, v142
	v_mov_b32_e32 v254, v64
	s_mov_b32 m0, s36
	s_nop 0
	global_load_lds_dwordx4 v254, s[18:19]
	s_add_u32 m0, m0, 0x1000
	s_nop 0
	global_load_lds_dwordx4 v254, s[20:21]
	s_add_u32 m0, m0, 0x1000
	s_nop 0
	global_load_lds_dwordx4 v254, s[22:23]
	s_add_u32 m0, m0, 0x1000
	s_nop 0
	global_load_lds_dwordx4 v254, s[24:25]
	s_add_u32 m0, m0, 0x1000
	s_nop 0
	global_load_lds_dwordx4 v254, s[26:27]
	s_add_u32 m0, m0, 0x1000
	s_nop 0
	global_load_lds_dwordx4 v254, s[28:29]
	s_add_u32 m0, m0, 0x1000
	s_nop 0
	global_load_lds_dwordx4 v254, s[30:31]
	s_add_u32 m0, m0, 0x1000
	s_nop 0
	global_load_lds_dwordx4 v254, s[34:35]
	v_add_u32_e32 v254, 0x80, v254
	s_add_u32 m0, s36, 0x8000
	s_nop 0
	global_load_lds_dwordx4 v254, s[18:19]
	s_add_u32 m0, m0, 0x1000
	s_nop 0
	global_load_lds_dwordx4 v254, s[20:21]
	s_add_u32 m0, m0, 0x1000
	s_nop 0
	global_load_lds_dwordx4 v254, s[22:23]
	s_add_u32 m0, m0, 0x1000
	s_nop 0
	global_load_lds_dwordx4 v254, s[24:25]
	s_add_u32 m0, m0, 0x1000
	s_nop 0
	global_load_lds_dwordx4 v254, s[26:27]
	s_add_u32 m0, m0, 0x1000
	s_nop 0
	global_load_lds_dwordx4 v254, s[28:29]
	s_add_u32 m0, m0, 0x1000
	s_nop 0
	global_load_lds_dwordx4 v254, s[30:31]
	s_add_u32 m0, m0, 0x1000
	s_nop 0
	global_load_lds_dwordx4 v254, s[34:35]
	v_add_u32_e32 v254, 0x80, v254
	v_mov_b32_e32 v48, 0
	v_mov_b32_e32 v49, 0
	v_mov_b32_e32 v50, 0
	v_mov_b32_e32 v51, 0
	v_mov_b32_e32 v52, 0
	v_mov_b32_e32 v53, 0
	v_mov_b32_e32 v54, 0
	v_mov_b32_e32 v55, 0
	v_mov_b32_e32 v56, 0
	v_mov_b32_e32 v57, 0
	v_mov_b32_e32 v58, 0
	v_mov_b32_e32 v59, 0
	v_mov_b32_e32 v60, 0
	v_mov_b32_e32 v61, 0
	v_mov_b32_e32 v62, 0
	v_mov_b32_e32 v63, 0
	v_mov_b32_e32 v32, 0
	v_mov_b32_e32 v33, 0
	v_mov_b32_e32 v34, 0
	v_mov_b32_e32 v35, 0
	v_mov_b32_e32 v36, 0
	v_mov_b32_e32 v37, 0
	v_mov_b32_e32 v38, 0
	v_mov_b32_e32 v39, 0
	v_mov_b32_e32 v40, 0
	v_mov_b32_e32 v41, 0
	v_mov_b32_e32 v42, 0
	v_mov_b32_e32 v43, 0
	v_mov_b32_e32 v44, 0
	v_mov_b32_e32 v45, 0
	v_mov_b32_e32 v46, 0
	v_mov_b32_e32 v47, 0
	v_mov_b32_e32 v16, 0
	v_mov_b32_e32 v17, 0
	v_mov_b32_e32 v18, 0
	v_mov_b32_e32 v19, 0
	v_mov_b32_e32 v20, 0
	v_mov_b32_e32 v21, 0
	v_mov_b32_e32 v22, 0
	v_mov_b32_e32 v23, 0
	v_mov_b32_e32 v24, 0
	v_mov_b32_e32 v25, 0
	v_mov_b32_e32 v26, 0
	v_mov_b32_e32 v27, 0
	v_mov_b32_e32 v28, 0
	v_mov_b32_e32 v29, 0
	v_mov_b32_e32 v30, 0
	v_mov_b32_e32 v31, 0
	v_mov_b32_e32 v0, 0
	v_mov_b32_e32 v1, 0
	v_mov_b32_e32 v2, 0
	v_mov_b32_e32 v3, 0
	v_mov_b32_e32 v4, 0
	v_mov_b32_e32 v5, 0
	v_mov_b32_e32 v6, 0
	v_mov_b32_e32 v7, 0
	v_mov_b32_e32 v8, 0
	v_mov_b32_e32 v9, 0
	v_mov_b32_e32 v10, 0
	v_mov_b32_e32 v11, 0
	v_mov_b32_e32 v12, 0
	v_mov_b32_e32 v13, 0
	v_mov_b32_e32 v14, 0
	v_mov_b32_e32 v15, 0
	s_mov_b32 s37, 7
.Lgk_loop_p6:
	s_waitcnt vmcnt(8)
	s_barrier
	ds_read_b128 v[70:73], v205
	ds_read_b128 v[74:77], v205 offset:2048
	ds_read_b128 v[86:89], v243
	ds_read_b128 v[90:93], v243 offset:2048
	ds_read_b128 v[94:97], v243 offset:4096
	ds_read_b128 v[98:101], v243 offset:6144
	ds_read_b128 v[102:105], v243 offset:8192
	ds_read_b128 v[106:109], v243 offset:10240
	ds_read_b128 v[110:113], v243 offset:12288
	ds_read_b128 v[206:209], v243 offset:14336
	ds_read_b128 v[78:81], v242
	ds_read_b128 v[82:85], v242 offset:2048
	ds_read_b128 v[210:213], v244
	ds_read_b128 v[214:217], v244 offset:2048
	ds_read_b128 v[218:221], v244 offset:4096
	ds_read_b128 v[222:225], v244 offset:6144
	ds_read_b128 v[226:229], v244 offset:8192
	ds_read_b128 v[230:233], v244 offset:10240
	ds_read_b128 v[234:237], v244 offset:12288
	ds_read_b128 v[238:241], v244 offset:14336
	s_waitcnt lgkmcnt(0)
	s_barrier
	s_mov_b32 m0, s36
	s_setprio 1
	v_mfma_f32_16x16x32_bf16 v[0:3], v[70:73], v[86:89], v[0:3]
	v_mfma_f32_16x16x32_bf16 v[4:7], v[70:73], v[90:93], v[4:7]
	v_mfma_f32_16x16x32_bf16 v[8:11], v[70:73], v[94:97], v[8:11]
	v_mfma_f32_16x16x32_bf16 v[12:15], v[70:73], v[98:101], v[12:15]
	global_load_lds_dwordx4 v254, s[18:19]
	s_add_u32 m0, m0, 0x1000
	v_mfma_f32_16x16x32_bf16 v[16:19], v[70:73], v[102:105], v[16:19]
	v_mfma_f32_16x16x32_bf16 v[20:23], v[70:73], v[106:109], v[20:23]
	v_mfma_f32_16x16x32_bf16 v[24:27], v[70:73], v[110:113], v[24:27]
	v_mfma_f32_16x16x32_bf16 v[28:31], v[70:73], v[206:209], v[28:31]
	global_load_lds_dwordx4 v254, s[20:21]
	s_add_u32 m0, m0, 0x1000
	v_mfma_f32_16x16x32_bf16 v[32:35], v[74:77], v[86:89], v[32:35]
	v_mfma_f32_16x16x32_bf16 v[36:39], v[74:77], v[90:93], v[36:39]
	v_mfma_f32_16x16x32_bf16 v[40:43], v[74:77], v[94:97], v[40:43]
	v_mfma_f32_16x16x32_bf16 v[44:47], v[74:77], v[98:101], v[44:47]
	global_load_lds_dwordx4 v254, s[22:23]
	s_add_u32 m0, m0, 0x1000
	v_mfma_f32_16x16x32_bf16 v[48:51], v[74:77], v[102:105], v[48:51]
	v_mfma_f32_16x16x32_bf16 v[52:55], v[74:77], v[106:109], v[52:55]
	v_mfma_f32_16x16x32_bf16 v[56:59], v[74:77], v[110:113], v[56:59]
	v_mfma_f32_16x16x32_bf16 v[60:63], v[74:77], v[206:209], v[60:63]
	global_load_lds_dwordx4 v254, s[24:25]
	s_add_u32 m0, m0, 0x1000
	v_mfma_f32_16x16x32_bf16 v[0:3], v[78:81], v[210:213], v[0:3]
	v_mfma_f32_16x16x32_bf16 v[4:7], v[78:81], v[214:217], v[4:7]
	v_mfma_f32_16x16x32_bf16 v[8:11], v[78:81], v[218:221], v[8:11]
	v_mfma_f32_16x16x32_bf16 v[12:15], v[78:81], v[222:225], v[12:15]
	global_load_lds_dwordx4 v254, s[26:27]
	s_add_u32 m0, m0, 0x1000
	v_mfma_f32_16x16x32_bf16 v[16:19], v[78:81], v[226:229], v[16:19]
	v_mfma_f32_16x16x32_bf16 v[20:23], v[78:81], v[230:233], v[20:23]
	v_mfma_f32_16x16x32_bf16 v[24:27], v[78:81], v[234:237], v[24:27]
	v_mfma_f32_16x16x32_bf16 v[28:31], v[78:81], v[238:241], v[28:31]
	global_load_lds_dwordx4 v254, s[28:29]
	s_add_u32 m0, m0, 0x1000
	v_mfma_f32_16x16x32_bf16 v[32:35], v[82:85], v[210:213], v[32:35]
	v_mfma_f32_16x16x32_bf16 v[36:39], v[82:85], v[214:217], v[36:39]
	v_mfma_f32_16x16x32_bf16 v[40:43], v[82:85], v[218:221], v[40:43]
	v_mfma_f32_16x16x32_bf16 v[44:47], v[82:85], v[222:225], v[44:47]
	global_load_lds_dwordx4 v254, s[30:31]
	s_add_u32 m0, m0, 0x1000
	v_mfma_f32_16x16x32_bf16 v[48:51], v[82:85], v[226:229], v[48:51]
	v_mfma_f32_16x16x32_bf16 v[52:55], v[82:85], v[230:233], v[52:55]
	v_mfma_f32_16x16x32_bf16 v[56:59], v[82:85], v[234:237], v[56:59]
	v_mfma_f32_16x16x32_bf16 v[60:63], v[82:85], v[238:241], v[60:63]
	global_load_lds_dwordx4 v254, s[34:35]
	s_setprio 0
	v_add_u32_e32 v254, 0x80, v254
	s_waitcnt vmcnt(8)
	s_barrier
	ds_read_b128 v[70:73], v205 offset:32768
	ds_read_b128 v[74:77], v205 offset:34816
	ds_read_b128 v[86:89], v243 offset:32768
	ds_read_b128 v[90:93], v243 offset:34816
	ds_read_b128 v[94:97], v243 offset:36864
	ds_read_b128 v[98:101], v243 offset:38912
	ds_read_b128 v[102:105], v243 offset:40960
	ds_read_b128 v[106:109], v243 offset:43008
	ds_read_b128 v[110:113], v243 offset:45056
	ds_read_b128 v[206:209], v243 offset:47104
	ds_read_b128 v[78:81], v242 offset:32768
	ds_read_b128 v[82:85], v242 offset:34816
	ds_read_b128 v[210:213], v244 offset:32768
	ds_read_b128 v[214:217], v244 offset:34816
	ds_read_b128 v[218:221], v244 offset:36864
	ds_read_b128 v[222:225], v244 offset:38912
	ds_read_b128 v[226:229], v244 offset:40960
	ds_read_b128 v[230:233], v244 offset:43008
	ds_read_b128 v[234:237], v244 offset:45056
	ds_read_b128 v[238:241], v244 offset:47104
	s_waitcnt lgkmcnt(0)
	s_barrier
	s_add_u32 m0, s36, 0x8000
	s_setprio 1
	v_mfma_f32_16x16x32_bf16 v[0:3], v[70:73], v[86:89], v[0:3]
	v_mfma_f32_16x16x32_bf16 v[4:7], v[70:73], v[90:93], v[4:7]
	v_mfma_f32_16x16x32_bf16 v[8:11], v[70:73], v[94:97], v[8:11]
	v_mfma_f32_16x16x32_bf16 v[12:15], v[70:73], v[98:101], v[12:15]
	global_load_lds_dwordx4 v254, s[18:19]
	s_add_u32 m0, m0, 0x1000
	v_mfma_f32_16x16x32_bf16 v[16:19], v[70:73], v[102:105], v[16:19]
	v_mfma_f32_16x16x32_bf16 v[20:23], v[70:73], v[106:109], v[20:23]
	v_mfma_f32_16x16x32_bf16 v[24:27], v[70:73], v[110:113], v[24:27]
	v_mfma_f32_16x16x32_bf16 v[28:31], v[70:73], v[206:209], v[28:31]
	global_load_lds_dwordx4 v254, s[20:21]
	s_add_u32 m0, m0, 0x1000
	v_mfma_f32_16x16x32_bf16 v[32:35], v[74:77], v[86:89], v[32:35]
	v_mfma_f32_16x16x32_bf16 v[36:39], v[74:77], v[90:93], v[36:39]
	v_mfma_f32_16x16x32_bf16 v[40:43], v[74:77], v[94:97], v[40:43]
	v_mfma_f32_16x16x32_bf16 v[44:47], v[74:77], v[98:101], v[44:47]
	global_load_lds_dwordx4 v254, s[22:23]
	s_add_u32 m0, m0, 0x1000
	v_mfma_f32_16x16x32_bf16 v[48:51], v[74:77], v[102:105], v[48:51]
	v_mfma_f32_16x16x32_bf16 v[52:55], v[74:77], v[106:109], v[52:55]
	v_mfma_f32_16x16x32_bf16 v[56:59], v[74:77], v[110:113], v[56:59]
	v_mfma_f32_16x16x32_bf16 v[60:63], v[74:77], v[206:209], v[60:63]
	global_load_lds_dwordx4 v254, s[24:25]
	s_add_u32 m0, m0, 0x1000
	v_mfma_f32_16x16x32_bf16 v[0:3], v[78:81], v[210:213], v[0:3]
	v_mfma_f32_16x16x32_bf16 v[4:7], v[78:81], v[214:217], v[4:7]
	v_mfma_f32_16x16x32_bf16 v[8:11], v[78:81], v[218:221], v[8:11]
	v_mfma_f32_16x16x32_bf16 v[12:15], v[78:81], v[222:225], v[12:15]
	global_load_lds_dwordx4 v254, s[26:27]
	s_add_u32 m0, m0, 0x1000
	v_mfma_f32_16x16x32_bf16 v[16:19], v[78:81], v[226:229], v[16:19]
	v_mfma_f32_16x16x32_bf16 v[20:23], v[78:81], v[230:233], v[20:23]
	v_mfma_f32_16x16x32_bf16 v[24:27], v[78:81], v[234:237], v[24:27]
	v_mfma_f32_16x16x32_bf16 v[28:31], v[78:81], v[238:241], v[28:31]
	global_load_lds_dwordx4 v254, s[28:29]
	s_add_u32 m0, m0, 0x1000
	v_mfma_f32_16x16x32_bf16 v[32:35], v[82:85], v[210:213], v[32:35]
	v_mfma_f32_16x16x32_bf16 v[36:39], v[82:85], v[214:217], v[36:39]
	v_mfma_f32_16x16x32_bf16 v[40:43], v[82:85], v[218:221], v[40:43]
	v_mfma_f32_16x16x32_bf16 v[44:47], v[82:85], v[222:225], v[44:47]
	global_load_lds_dwordx4 v254, s[30:31]
	s_add_u32 m0, m0, 0x1000
	v_mfma_f32_16x16x32_bf16 v[48:51], v[82:85], v[226:229], v[48:51]
	v_mfma_f32_16x16x32_bf16 v[52:55], v[82:85], v[230:233], v[52:55]
	v_mfma_f32_16x16x32_bf16 v[56:59], v[82:85], v[234:237], v[56:59]
	v_mfma_f32_16x16x32_bf16 v[60:63], v[82:85], v[238:241], v[60:63]
	global_load_lds_dwordx4 v254, s[34:35]
	s_setprio 0
	v_add_u32_e32 v254, 0x80, v254
	s_sub_u32 s37, s37, 1
	s_cmp_lg_u32 s37, 0
	s_cbranch_scc1 .Lgk_loop_p6
	s_waitcnt vmcnt(8)
	s_barrier
	ds_read_b128 v[70:73], v205
	ds_read_b128 v[74:77], v205 offset:2048
	ds_read_b128 v[86:89], v243
	ds_read_b128 v[90:93], v243 offset:2048
	ds_read_b128 v[94:97], v243 offset:4096
	ds_read_b128 v[98:101], v243 offset:6144
	ds_read_b128 v[102:105], v243 offset:8192
	ds_read_b128 v[106:109], v243 offset:10240
	ds_read_b128 v[110:113], v243 offset:12288
	ds_read_b128 v[206:209], v243 offset:14336
	ds_read_b128 v[78:81], v242
	ds_read_b128 v[82:85], v242 offset:2048
	ds_read_b128 v[210:213], v244
	ds_read_b128 v[214:217], v244 offset:2048
	ds_read_b128 v[218:221], v244 offset:4096
	ds_read_b128 v[222:225], v244 offset:6144
	ds_read_b128 v[226:229], v244 offset:8192
	ds_read_b128 v[230:233], v244 offset:10240
	ds_read_b128 v[234:237], v244 offset:12288
	ds_read_b128 v[238:241], v244 offset:14336
	s_waitcnt lgkmcnt(0)
	s_barrier
	s_setprio 1
	v_mfma_f32_16x16x32_bf16 v[0:3], v[70:73], v[86:89], v[0:3]
	v_mfma_f32_16x16x32_bf16 v[4:7], v[70:73], v[90:93], v[4:7]
	v_mfma_f32_16x16x32_bf16 v[8:11], v[70:73], v[94:97], v[8:11]
	v_mfma_f32_16x16x32_bf16 v[12:15], v[70:73], v[98:101], v[12:15]
	v_mfma_f32_16x16x32_bf16 v[16:19], v[70:73], v[102:105], v[16:19]
	v_mfma_f32_16x16x32_bf16 v[20:23], v[70:73], v[106:109], v[20:23]
	v_mfma_f32_16x16x32_bf16 v[24:27], v[70:73], v[110:113], v[24:27]
	v_mfma_f32_16x16x32_bf16 v[28:31], v[70:73], v[206:209], v[28:31]
	v_mfma_f32_16x16x32_bf16 v[32:35], v[74:77], v[86:89], v[32:35]
	v_mfma_f32_16x16x32_bf16 v[36:39], v[74:77], v[90:93], v[36:39]
	v_mfma_f32_16x16x32_bf16 v[40:43], v[74:77], v[94:97], v[40:43]
	v_mfma_f32_16x16x32_bf16 v[44:47], v[74:77], v[98:101], v[44:47]
	v_mfma_f32_16x16x32_bf16 v[48:51], v[74:77], v[102:105], v[48:51]
	v_mfma_f32_16x16x32_bf16 v[52:55], v[74:77], v[106:109], v[52:55]
	v_mfma_f32_16x16x32_bf16 v[56:59], v[74:77], v[110:113], v[56:59]
	v_mfma_f32_16x16x32_bf16 v[60:63], v[74:77], v[206:209], v[60:63]
	v_mfma_f32_16x16x32_bf16 v[0:3], v[78:81], v[210:213], v[0:3]
	v_mfma_f32_16x16x32_bf16 v[4:7], v[78:81], v[214:217], v[4:7]
	v_mfma_f32_16x16x32_bf16 v[8:11], v[78:81], v[218:221], v[8:11]
	v_mfma_f32_16x16x32_bf16 v[12:15], v[78:81], v[222:225], v[12:15]
	v_mfma_f32_16x16x32_bf16 v[16:19], v[78:81], v[226:229], v[16:19]
	v_mfma_f32_16x16x32_bf16 v[20:23], v[78:81], v[230:233], v[20:23]
	v_mfma_f32_16x16x32_bf16 v[24:27], v[78:81], v[234:237], v[24:27]
	v_mfma_f32_16x16x32_bf16 v[28:31], v[78:81], v[238:241], v[28:31]
	v_mfma_f32_16x16x32_bf16 v[32:35], v[82:85], v[210:213], v[32:35]
	v_mfma_f32_16x16x32_bf16 v[36:39], v[82:85], v[214:217], v[36:39]
	v_mfma_f32_16x16x32_bf16 v[40:43], v[82:85], v[218:221], v[40:43]
	v_mfma_f32_16x16x32_bf16 v[44:47], v[82:85], v[222:225], v[44:47]
	v_mfma_f32_16x16x32_bf16 v[48:51], v[82:85], v[226:229], v[48:51]
	v_mfma_f32_16x16x32_bf16 v[52:55], v[82:85], v[230:233], v[52:55]
	v_mfma_f32_16x16x32_bf16 v[56:59], v[82:85], v[234:237], v[56:59]
	v_mfma_f32_16x16x32_bf16 v[60:63], v[82:85], v[238:241], v[60:63]
	s_setprio 0
	s_waitcnt vmcnt(0)
	s_barrier
	ds_read_b128 v[70:73], v205 offset:32768
	ds_read_b128 v[74:77], v205 offset:34816
	ds_read_b128 v[86:89], v243 offset:32768
	ds_read_b128 v[90:93], v243 offset:34816
	ds_read_b128 v[94:97], v243 offset:36864
	ds_read_b128 v[98:101], v243 offset:38912
	ds_read_b128 v[102:105], v243 offset:40960
	ds_read_b128 v[106:109], v243 offset:43008
	ds_read_b128 v[110:113], v243 offset:45056
	ds_read_b128 v[206:209], v243 offset:47104
	ds_read_b128 v[78:81], v242 offset:32768
	ds_read_b128 v[82:85], v242 offset:34816
	ds_read_b128 v[210:213], v244 offset:32768
	ds_read_b128 v[214:217], v244 offset:34816
	ds_read_b128 v[218:221], v244 offset:36864
	ds_read_b128 v[222:225], v244 offset:38912
	ds_read_b128 v[226:229], v244 offset:40960
	ds_read_b128 v[230:233], v244 offset:43008
	ds_read_b128 v[234:237], v244 offset:45056
	ds_read_b128 v[238:241], v244 offset:47104
	s_waitcnt lgkmcnt(0)
	s_barrier
	s_setprio 1
	v_mfma_f32_16x16x32_bf16 v[0:3], v[70:73], v[86:89], v[0:3]
	v_mfma_f32_16x16x32_bf16 v[4:7], v[70:73], v[90:93], v[4:7]
	v_mfma_f32_16x16x32_bf16 v[8:11], v[70:73], v[94:97], v[8:11]
	v_mfma_f32_16x16x32_bf16 v[12:15], v[70:73], v[98:101], v[12:15]
	v_mfma_f32_16x16x32_bf16 v[16:19], v[70:73], v[102:105], v[16:19]
	v_mfma_f32_16x16x32_bf16 v[20:23], v[70:73], v[106:109], v[20:23]
	v_mfma_f32_16x16x32_bf16 v[24:27], v[70:73], v[110:113], v[24:27]
	v_mfma_f32_16x16x32_bf16 v[28:31], v[70:73], v[206:209], v[28:31]
	v_mfma_f32_16x16x32_bf16 v[32:35], v[74:77], v[86:89], v[32:35]
	v_mfma_f32_16x16x32_bf16 v[36:39], v[74:77], v[90:93], v[36:39]
	v_mfma_f32_16x16x32_bf16 v[40:43], v[74:77], v[94:97], v[40:43]
	v_mfma_f32_16x16x32_bf16 v[44:47], v[74:77], v[98:101], v[44:47]
	v_mfma_f32_16x16x32_bf16 v[48:51], v[74:77], v[102:105], v[48:51]
	v_mfma_f32_16x16x32_bf16 v[52:55], v[74:77], v[106:109], v[52:55]
	v_mfma_f32_16x16x32_bf16 v[56:59], v[74:77], v[110:113], v[56:59]
	v_mfma_f32_16x16x32_bf16 v[60:63], v[74:77], v[206:209], v[60:63]
	v_mfma_f32_16x16x32_bf16 v[0:3], v[78:81], v[210:213], v[0:3]
	v_mfma_f32_16x16x32_bf16 v[4:7], v[78:81], v[214:217], v[4:7]
	v_mfma_f32_16x16x32_bf16 v[8:11], v[78:81], v[218:221], v[8:11]
	v_mfma_f32_16x16x32_bf16 v[12:15], v[78:81], v[222:225], v[12:15]
	v_mfma_f32_16x16x32_bf16 v[16:19], v[78:81], v[226:229], v[16:19]
	v_mfma_f32_16x16x32_bf16 v[20:23], v[78:81], v[230:233], v[20:23]
	v_mfma_f32_16x16x32_bf16 v[24:27], v[78:81], v[234:237], v[24:27]
	v_mfma_f32_16x16x32_bf16 v[28:31], v[78:81], v[238:241], v[28:31]
	v_mfma_f32_16x16x32_bf16 v[32:35], v[82:85], v[210:213], v[32:35]
	v_mfma_f32_16x16x32_bf16 v[36:39], v[82:85], v[214:217], v[36:39]
	v_mfma_f32_16x16x32_bf16 v[40:43], v[82:85], v[218:221], v[40:43]
	v_mfma_f32_16x16x32_bf16 v[44:47], v[82:85], v[222:225], v[44:47]
	v_mfma_f32_16x16x32_bf16 v[48:51], v[82:85], v[226:229], v[48:51]
	v_mfma_f32_16x16x32_bf16 v[52:55], v[82:85], v[230:233], v[52:55]
	v_mfma_f32_16x16x32_bf16 v[56:59], v[82:85], v[234:237], v[56:59]
	v_mfma_f32_16x16x32_bf16 v[60:63], v[82:85], v[238:241], v[60:63]
	s_setprio 0
	s_nop 7
	s_nop 7
	v_and_b32_e32 v72, 63, v199
	v_lshrrev_b32_e32 v73, 6, v199
	v_lshlrev_b32_e32 v73, 14, v73
	v_lshl_add_u32 v70, v72, 4, v73
	v_and_b32_e32 v71, 15, v72
	v_lshl_add_u32 v71, v71, 4, v73
	v_bfe_u32 v73, v72, 4, 1
	v_lshl_add_u32 v71, v73, 10, v71
	v_bfe_u32 v73, v72, 5, 1
	v_lshl_add_u32 v71, v73, 8, v71
	ds_write_b128 v70, v[0:3]
	ds_write_b128 v70, v[4:7] offset:1024
	ds_write_b128 v70, v[8:11] offset:2048
	ds_write_b128 v70, v[12:15] offset:3072
	ds_write_b128 v70, v[16:19] offset:4096
	ds_write_b128 v70, v[20:23] offset:5120
	ds_write_b128 v70, v[24:27] offset:6144
	ds_write_b128 v70, v[28:31] offset:7168
	ds_write_b128 v70, v[32:35] offset:8192
	ds_write_b128 v70, v[36:39] offset:9216
	ds_write_b128 v70, v[40:43] offset:10240
	ds_write_b128 v70, v[44:47] offset:11264
	ds_write_b128 v70, v[48:51] offset:12288
	ds_write_b128 v70, v[52:55] offset:13312
	ds_write_b128 v70, v[56:59] offset:14336
	ds_write_b128 v70, v[60:63] offset:15360
	s_waitcnt lgkmcnt(0)
	ds_read_b128 v[48:51], v71
	ds_read_b128 v[52:55], v71 offset:512
	ds_read_b128 v[56:59], v71 offset:8192
	ds_read_b128 v[60:63], v71 offset:8704
	ds_read_b128 v[32:35], v71 offset:2048
	ds_read_b128 v[36:39], v71 offset:2560
	ds_read_b128 v[40:43], v71 offset:10240
	ds_read_b128 v[44:47], v71 offset:10752
	ds_read_b128 v[16:19], v71 offset:4096
	ds_read_b128 v[20:23], v71 offset:4608
	ds_read_b128 v[24:27], v71 offset:12288
	ds_read_b128 v[28:31], v71 offset:12800
	ds_read_b128 v[0:3], v71 offset:6144
	ds_read_b128 v[4:7], v71 offset:6656
	ds_read_b128 v[8:11], v71 offset:14336
	ds_read_b128 v[12:15], v71 offset:14848
	s_waitcnt lgkmcnt(0)
	s_barrier
	s_branch .LBB0_707

.Lmap_done_0:
	s_lshl_b32 s60, s4, 7
	s_lshl_b32 s58, s76, 7
	s_ashr_i32 s61, s60, 31
	s_ashr_i32 s59, s58, 31
	s_lshl_b64 s[62:63], s[60:61], 11
	s_lshl_b64 s[64:65], s[58:59], 11
	s_lshl_b32 s38, s60, 11
	s_add_u32 s18, s14, s38
	s_addc_u32 s19, s15, 0
	s_add_u32 s18, s18, 0x679f000
	s_addc_u32 s19, s19, 0
	s_add_u32 s20, s18, 0x10000
	s_addc_u32 s21, s19, 0
	s_add_u32 s22, s20, 0x10000
	s_addc_u32 s23, s21, 0
	s_add_u32 s24, s22, 0x10000
	s_addc_u32 s25, s23, 0
	s_lshl_b32 s38, s58, 11
	s_add_u32 s26, s14, s38
	s_addc_u32 s27, s15, 0
	s_add_u32 s26, s26, 0x19a0000
	s_addc_u32 s27, s27, 0
	s_add_u32 s28, s26, 0x10000
	s_addc_u32 s29, s27, 0
	s_add_u32 s30, s28, 0x10000
	s_addc_u32 s31, s29, 0
	s_add_u32 s34, s30, 0x10000
	s_addc_u32 s35, s31, 0
	v_and_b32_e32 v64, 15, v199
	v_bfe_u32 v65, v199, 4, 2
	v_lshrrev_b32_e32 v66, 1, v64
	v_xor_b32_e32 v65, v65, v66
	v_lshlrev_b32_e32 v65, 4, v65
	v_lshl_or_b32 v65, v64, 7, v65
	v_lshrrev_b32_e32 v66, 6, v199
	v_lshl_add_u32 v217, v66, 12, v65
	v_xor_b32_e32 v255, 64, v217
	v_add_u32_e32 v78, 0x4000, v65
	v_xor_b32_e32 v79, 64, v78
	v_readfirstlane_b32 s36, v94
	v_mov_b32_e32 v254, v76
	s_mov_b32 m0, s36
	s_nop 0
	global_load_lds_dwordx4 v254, s[18:19]
	s_add_u32 m0, m0, 0x1000
	s_nop 0
	global_load_lds_dwordx4 v254, s[20:21]
	s_add_u32 m0, m0, 0x1000
	s_nop 0
	global_load_lds_dwordx4 v254, s[22:23]
	s_add_u32 m0, m0, 0x1000
	s_nop 0
	global_load_lds_dwordx4 v254, s[24:25]
	s_add_u32 m0, m0, 0x1000
	s_nop 0
	global_load_lds_dwordx4 v254, s[26:27]
	s_add_u32 m0, m0, 0x1000
	s_nop 0
	global_load_lds_dwordx4 v254, s[28:29]
	s_add_u32 m0, m0, 0x1000
	s_nop 0
	global_load_lds_dwordx4 v254, s[30:31]
	s_add_u32 m0, m0, 0x1000
	s_nop 0
	global_load_lds_dwordx4 v254, s[34:35]
	v_add_u32_e32 v254, 0x80, v254
	s_add_u32 m0, s36, 0x8000
	s_nop 0
	global_load_lds_dwordx4 v254, s[18:19]
	s_add_u32 m0, m0, 0x1000
	s_nop 0
	global_load_lds_dwordx4 v254, s[20:21]
	s_add_u32 m0, m0, 0x1000
	s_nop 0
	global_load_lds_dwordx4 v254, s[22:23]
	s_add_u32 m0, m0, 0x1000
	s_nop 0
	global_load_lds_dwordx4 v254, s[24:25]
	s_add_u32 m0, m0, 0x1000
	s_nop 0
	global_load_lds_dwordx4 v254, s[26:27]
	s_add_u32 m0, m0, 0x1000
	s_nop 0
	global_load_lds_dwordx4 v254, s[28:29]
	s_add_u32 m0, m0, 0x1000
	s_nop 0
	global_load_lds_dwordx4 v254, s[30:31]
	s_add_u32 m0, m0, 0x1000
	s_nop 0
	global_load_lds_dwordx4 v254, s[34:35]
	v_add_u32_e32 v254, 0x80, v254
	v_mov_b32_e32 v48, 0
	v_mov_b32_e32 v49, 0
	v_mov_b32_e32 v50, 0
	v_mov_b32_e32 v51, 0
	v_mov_b32_e32 v52, 0
	v_mov_b32_e32 v53, 0
	v_mov_b32_e32 v54, 0
	v_mov_b32_e32 v55, 0
	v_mov_b32_e32 v56, 0
	v_mov_b32_e32 v57, 0
	v_mov_b32_e32 v58, 0
	v_mov_b32_e32 v59, 0
	v_mov_b32_e32 v60, 0
	v_mov_b32_e32 v61, 0
	v_mov_b32_e32 v62, 0
	v_mov_b32_e32 v63, 0
	v_mov_b32_e32 v32, 0
	v_mov_b32_e32 v33, 0
	v_mov_b32_e32 v34, 0
	v_mov_b32_e32 v35, 0
	v_mov_b32_e32 v36, 0
	v_mov_b32_e32 v37, 0
	v_mov_b32_e32 v38, 0
	v_mov_b32_e32 v39, 0
	v_mov_b32_e32 v40, 0
	v_mov_b32_e32 v41, 0
	v_mov_b32_e32 v42, 0
	v_mov_b32_e32 v43, 0
	v_mov_b32_e32 v44, 0
	v_mov_b32_e32 v45, 0
	v_mov_b32_e32 v46, 0
	v_mov_b32_e32 v47, 0
	v_mov_b32_e32 v16, 0
	v_mov_b32_e32 v17, 0
	v_mov_b32_e32 v18, 0
	v_mov_b32_e32 v19, 0
	v_mov_b32_e32 v20, 0
	v_mov_b32_e32 v21, 0
	v_mov_b32_e32 v22, 0
	v_mov_b32_e32 v23, 0
	v_mov_b32_e32 v24, 0
	v_mov_b32_e32 v25, 0
	v_mov_b32_e32 v26, 0
	v_mov_b32_e32 v27, 0
	v_mov_b32_e32 v28, 0
	v_mov_b32_e32 v29, 0
	v_mov_b32_e32 v30, 0
	v_mov_b32_e32 v31, 0
	v_mov_b32_e32 v0, 0
	v_mov_b32_e32 v1, 0
	v_mov_b32_e32 v2, 0
	v_mov_b32_e32 v3, 0
	v_mov_b32_e32 v4, 0
	v_mov_b32_e32 v5, 0
	v_mov_b32_e32 v6, 0
	v_mov_b32_e32 v7, 0
	v_mov_b32_e32 v8, 0
	v_mov_b32_e32 v9, 0
	v_mov_b32_e32 v10, 0
	v_mov_b32_e32 v11, 0
	v_mov_b32_e32 v12, 0
	v_mov_b32_e32 v13, 0
	v_mov_b32_e32 v14, 0
	v_mov_b32_e32 v15, 0
	s_mov_b32 s37, 7
.Lgk_loop_p7:
	s_waitcnt vmcnt(8)
	s_barrier
	ds_read_b128 v[64:67], v217
	ds_read_b128 v[68:71], v217 offset:2048
	ds_read_b128 v[86:89], v78
	ds_read_b128 v[120:123], v78 offset:2048
	ds_read_b128 v[124:127], v78 offset:4096
	ds_read_b128 v[128:131], v78 offset:6144
	ds_read_b128 v[132:135], v78 offset:8192
	ds_read_b128 v[136:139], v78 offset:10240
	ds_read_b128 v[140:143], v78 offset:12288
	ds_read_b128 v[218:221], v78 offset:14336
	ds_read_b128 v[72:75], v255
	ds_read_b128 v[82:85], v255 offset:2048
	ds_read_b128 v[222:225], v79
	ds_read_b128 v[226:229], v79 offset:2048
	ds_read_b128 v[230:233], v79 offset:4096
	ds_read_b128 v[234:237], v79 offset:6144
	ds_read_b128 v[238:241], v79 offset:8192
	ds_read_b128 v[242:245], v79 offset:10240
	ds_read_b128 v[246:249], v79 offset:12288
	ds_read_b128 v[250:253], v79 offset:14336
	s_waitcnt lgkmcnt(0)
	s_barrier
	s_mov_b32 m0, s36
	s_setprio 1
	v_mfma_f32_16x16x32_bf16 v[0:3], v[64:67], v[86:89], v[0:3]
	v_mfma_f32_16x16x32_bf16 v[4:7], v[64:67], v[120:123], v[4:7]
	v_mfma_f32_16x16x32_bf16 v[8:11], v[64:67], v[124:127], v[8:11]
	v_mfma_f32_16x16x32_bf16 v[12:15], v[64:67], v[128:131], v[12:15]
	global_load_lds_dwordx4 v254, s[18:19]
	s_add_u32 m0, m0, 0x1000
	v_mfma_f32_16x16x32_bf16 v[16:19], v[64:67], v[132:135], v[16:19]
	v_mfma_f32_16x16x32_bf16 v[20:23], v[64:67], v[136:139], v[20:23]
	v_mfma_f32_16x16x32_bf16 v[24:27], v[64:67], v[140:143], v[24:27]
	v_mfma_f32_16x16x32_bf16 v[28:31], v[64:67], v[218:221], v[28:31]
	global_load_lds_dwordx4 v254, s[20:21]
	s_add_u32 m0, m0, 0x1000
	v_mfma_f32_16x16x32_bf16 v[32:35], v[68:71], v[86:89], v[32:35]
	v_mfma_f32_16x16x32_bf16 v[36:39], v[68:71], v[120:123], v[36:39]
	v_mfma_f32_16x16x32_bf16 v[40:43], v[68:71], v[124:127], v[40:43]
	v_mfma_f32_16x16x32_bf16 v[44:47], v[68:71], v[128:131], v[44:47]
	global_load_lds_dwordx4 v254, s[22:23]
	s_add_u32 m0, m0, 0x1000
	v_mfma_f32_16x16x32_bf16 v[48:51], v[68:71], v[132:135], v[48:51]
	v_mfma_f32_16x16x32_bf16 v[52:55], v[68:71], v[136:139], v[52:55]
	v_mfma_f32_16x16x32_bf16 v[56:59], v[68:71], v[140:143], v[56:59]
	v_mfma_f32_16x16x32_bf16 v[60:63], v[68:71], v[218:221], v[60:63]
	global_load_lds_dwordx4 v254, s[24:25]
	s_add_u32 m0, m0, 0x1000
	v_mfma_f32_16x16x32_bf16 v[0:3], v[72:75], v[222:225], v[0:3]
	v_mfma_f32_16x16x32_bf16 v[4:7], v[72:75], v[226:229], v[4:7]
	v_mfma_f32_16x16x32_bf16 v[8:11], v[72:75], v[230:233], v[8:11]
	v_mfma_f32_16x16x32_bf16 v[12:15], v[72:75], v[234:237], v[12:15]
	global_load_lds_dwordx4 v254, s[26:27]
	s_add_u32 m0, m0, 0x1000
	v_mfma_f32_16x16x32_bf16 v[16:19], v[72:75], v[238:241], v[16:19]
	v_mfma_f32_16x16x32_bf16 v[20:23], v[72:75], v[242:245], v[20:23]
	v_mfma_f32_16x16x32_bf16 v[24:27], v[72:75], v[246:249], v[24:27]
	v_mfma_f32_16x16x32_bf16 v[28:31], v[72:75], v[250:253], v[28:31]
	global_load_lds_dwordx4 v254, s[28:29]
	s_add_u32 m0, m0, 0x1000
	v_mfma_f32_16x16x32_bf16 v[32:35], v[82:85], v[222:225], v[32:35]
	v_mfma_f32_16x16x32_bf16 v[36:39], v[82:85], v[226:229], v[36:39]
	v_mfma_f32_16x16x32_bf16 v[40:43], v[82:85], v[230:233], v[40:43]
	v_mfma_f32_16x16x32_bf16 v[44:47], v[82:85], v[234:237], v[44:47]
	global_load_lds_dwordx4 v254, s[30:31]
	s_add_u32 m0, m0, 0x1000
	v_mfma_f32_16x16x32_bf16 v[48:51], v[82:85], v[238:241], v[48:51]
	v_mfma_f32_16x16x32_bf16 v[52:55], v[82:85], v[242:245], v[52:55]
	v_mfma_f32_16x16x32_bf16 v[56:59], v[82:85], v[246:249], v[56:59]
	v_mfma_f32_16x16x32_bf16 v[60:63], v[82:85], v[250:253], v[60:63]
	global_load_lds_dwordx4 v254, s[34:35]
	s_setprio 0
	v_add_u32_e32 v254, 0x80, v254
	s_waitcnt vmcnt(8)
	s_barrier
	ds_read_b128 v[64:67], v217 offset:32768
	ds_read_b128 v[68:71], v217 offset:34816
	ds_read_b128 v[86:89], v78 offset:32768
	ds_read_b128 v[120:123], v78 offset:34816
	ds_read_b128 v[124:127], v78 offset:36864
	ds_read_b128 v[128:131], v78 offset:38912
	ds_read_b128 v[132:135], v78 offset:40960
	ds_read_b128 v[136:139], v78 offset:43008
	ds_read_b128 v[140:143], v78 offset:45056
	ds_read_b128 v[218:221], v78 offset:47104
	ds_read_b128 v[72:75], v255 offset:32768
	ds_read_b128 v[82:85], v255 offset:34816
	ds_read_b128 v[222:225], v79 offset:32768
	ds_read_b128 v[226:229], v79 offset:34816
	ds_read_b128 v[230:233], v79 offset:36864
	ds_read_b128 v[234:237], v79 offset:38912
	ds_read_b128 v[238:241], v79 offset:40960
	ds_read_b128 v[242:245], v79 offset:43008
	ds_read_b128 v[246:249], v79 offset:45056
	ds_read_b128 v[250:253], v79 offset:47104
	s_waitcnt lgkmcnt(0)
	s_barrier
	s_add_u32 m0, s36, 0x8000
	s_setprio 1
	v_mfma_f32_16x16x32_bf16 v[0:3], v[64:67], v[86:89], v[0:3]
	v_mfma_f32_16x16x32_bf16 v[4:7], v[64:67], v[120:123], v[4:7]
	v_mfma_f32_16x16x32_bf16 v[8:11], v[64:67], v[124:127], v[8:11]
	v_mfma_f32_16x16x32_bf16 v[12:15], v[64:67], v[128:131], v[12:15]
	global_load_lds_dwordx4 v254, s[18:19]
	s_add_u32 m0, m0, 0x1000
	v_mfma_f32_16x16x32_bf16 v[16:19], v[64:67], v[132:135], v[16:19]
	v_mfma_f32_16x16x32_bf16 v[20:23], v[64:67], v[136:139], v[20:23]
	v_mfma_f32_16x16x32_bf16 v[24:27], v[64:67], v[140:143], v[24:27]
	v_mfma_f32_16x16x32_bf16 v[28:31], v[64:67], v[218:221], v[28:31]
	global_load_lds_dwordx4 v254, s[20:21]
	s_add_u32 m0, m0, 0x1000
	v_mfma_f32_16x16x32_bf16 v[32:35], v[68:71], v[86:89], v[32:35]
	v_mfma_f32_16x16x32_bf16 v[36:39], v[68:71], v[120:123], v[36:39]
	v_mfma_f32_16x16x32_bf16 v[40:43], v[68:71], v[124:127], v[40:43]
	v_mfma_f32_16x16x32_bf16 v[44:47], v[68:71], v[128:131], v[44:47]
	global_load_lds_dwordx4 v254, s[22:23]
	s_add_u32 m0, m0, 0x1000
	v_mfma_f32_16x16x32_bf16 v[48:51], v[68:71], v[132:135], v[48:51]
	v_mfma_f32_16x16x32_bf16 v[52:55], v[68:71], v[136:139], v[52:55]
	v_mfma_f32_16x16x32_bf16 v[56:59], v[68:71], v[140:143], v[56:59]
	v_mfma_f32_16x16x32_bf16 v[60:63], v[68:71], v[218:221], v[60:63]
	global_load_lds_dwordx4 v254, s[24:25]
	s_add_u32 m0, m0, 0x1000
	v_mfma_f32_16x16x32_bf16 v[0:3], v[72:75], v[222:225], v[0:3]
	v_mfma_f32_16x16x32_bf16 v[4:7], v[72:75], v[226:229], v[4:7]
	v_mfma_f32_16x16x32_bf16 v[8:11], v[72:75], v[230:233], v[8:11]
	v_mfma_f32_16x16x32_bf16 v[12:15], v[72:75], v[234:237], v[12:15]
	global_load_lds_dwordx4 v254, s[26:27]
	s_add_u32 m0, m0, 0x1000
	v_mfma_f32_16x16x32_bf16 v[16:19], v[72:75], v[238:241], v[16:19]
	v_mfma_f32_16x16x32_bf16 v[20:23], v[72:75], v[242:245], v[20:23]
	v_mfma_f32_16x16x32_bf16 v[24:27], v[72:75], v[246:249], v[24:27]
	v_mfma_f32_16x16x32_bf16 v[28:31], v[72:75], v[250:253], v[28:31]
	global_load_lds_dwordx4 v254, s[28:29]
	s_add_u32 m0, m0, 0x1000
	v_mfma_f32_16x16x32_bf16 v[32:35], v[82:85], v[222:225], v[32:35]
	v_mfma_f32_16x16x32_bf16 v[36:39], v[82:85], v[226:229], v[36:39]
	v_mfma_f32_16x16x32_bf16 v[40:43], v[82:85], v[230:233], v[40:43]
	v_mfma_f32_16x16x32_bf16 v[44:47], v[82:85], v[234:237], v[44:47]
	global_load_lds_dwordx4 v254, s[30:31]
	s_add_u32 m0, m0, 0x1000
	v_mfma_f32_16x16x32_bf16 v[48:51], v[82:85], v[238:241], v[48:51]
	v_mfma_f32_16x16x32_bf16 v[52:55], v[82:85], v[242:245], v[52:55]
	v_mfma_f32_16x16x32_bf16 v[56:59], v[82:85], v[246:249], v[56:59]
	v_mfma_f32_16x16x32_bf16 v[60:63], v[82:85], v[250:253], v[60:63]
	global_load_lds_dwordx4 v254, s[34:35]
	s_setprio 0
	v_add_u32_e32 v254, 0x80, v254
	s_sub_u32 s37, s37, 1
	s_cmp_lg_u32 s37, 0
	s_cbranch_scc1 .Lgk_loop_p7
	s_waitcnt vmcnt(8)
	s_barrier
	ds_read_b128 v[64:67], v217
	ds_read_b128 v[68:71], v217 offset:2048
	ds_read_b128 v[86:89], v78
	ds_read_b128 v[120:123], v78 offset:2048
	ds_read_b128 v[124:127], v78 offset:4096
	ds_read_b128 v[128:131], v78 offset:6144
	ds_read_b128 v[132:135], v78 offset:8192
	ds_read_b128 v[136:139], v78 offset:10240
	ds_read_b128 v[140:143], v78 offset:12288
	ds_read_b128 v[218:221], v78 offset:14336
	ds_read_b128 v[72:75], v255
	ds_read_b128 v[82:85], v255 offset:2048
	ds_read_b128 v[222:225], v79
	ds_read_b128 v[226:229], v79 offset:2048
	ds_read_b128 v[230:233], v79 offset:4096
	ds_read_b128 v[234:237], v79 offset:6144
	ds_read_b128 v[238:241], v79 offset:8192
	ds_read_b128 v[242:245], v79 offset:10240
	ds_read_b128 v[246:249], v79 offset:12288
	ds_read_b128 v[250:253], v79 offset:14336
	s_waitcnt lgkmcnt(0)
	s_barrier
	s_setprio 1
	v_mfma_f32_16x16x32_bf16 v[0:3], v[64:67], v[86:89], v[0:3]
	v_mfma_f32_16x16x32_bf16 v[4:7], v[64:67], v[120:123], v[4:7]
	v_mfma_f32_16x16x32_bf16 v[8:11], v[64:67], v[124:127], v[8:11]
	v_mfma_f32_16x16x32_bf16 v[12:15], v[64:67], v[128:131], v[12:15]
	v_mfma_f32_16x16x32_bf16 v[16:19], v[64:67], v[132:135], v[16:19]
	v_mfma_f32_16x16x32_bf16 v[20:23], v[64:67], v[136:139], v[20:23]
	v_mfma_f32_16x16x32_bf16 v[24:27], v[64:67], v[140:143], v[24:27]
	v_mfma_f32_16x16x32_bf16 v[28:31], v[64:67], v[218:221], v[28:31]
	v_mfma_f32_16x16x32_bf16 v[32:35], v[68:71], v[86:89], v[32:35]
	v_mfma_f32_16x16x32_bf16 v[36:39], v[68:71], v[120:123], v[36:39]
	v_mfma_f32_16x16x32_bf16 v[40:43], v[68:71], v[124:127], v[40:43]
	v_mfma_f32_16x16x32_bf16 v[44:47], v[68:71], v[128:131], v[44:47]
	v_mfma_f32_16x16x32_bf16 v[48:51], v[68:71], v[132:135], v[48:51]
	v_mfma_f32_16x16x32_bf16 v[52:55], v[68:71], v[136:139], v[52:55]
	v_mfma_f32_16x16x32_bf16 v[56:59], v[68:71], v[140:143], v[56:59]
	v_mfma_f32_16x16x32_bf16 v[60:63], v[68:71], v[218:221], v[60:63]
	v_mfma_f32_16x16x32_bf16 v[0:3], v[72:75], v[222:225], v[0:3]
	v_mfma_f32_16x16x32_bf16 v[4:7], v[72:75], v[226:229], v[4:7]
	v_mfma_f32_16x16x32_bf16 v[8:11], v[72:75], v[230:233], v[8:11]
	v_mfma_f32_16x16x32_bf16 v[12:15], v[72:75], v[234:237], v[12:15]
	v_mfma_f32_16x16x32_bf16 v[16:19], v[72:75], v[238:241], v[16:19]
	v_mfma_f32_16x16x32_bf16 v[20:23], v[72:75], v[242:245], v[20:23]
	v_mfma_f32_16x16x32_bf16 v[24:27], v[72:75], v[246:249], v[24:27]
	v_mfma_f32_16x16x32_bf16 v[28:31], v[72:75], v[250:253], v[28:31]
	v_mfma_f32_16x16x32_bf16 v[32:35], v[82:85], v[222:225], v[32:35]
	v_mfma_f32_16x16x32_bf16 v[36:39], v[82:85], v[226:229], v[36:39]
	v_mfma_f32_16x16x32_bf16 v[40:43], v[82:85], v[230:233], v[40:43]
	v_mfma_f32_16x16x32_bf16 v[44:47], v[82:85], v[234:237], v[44:47]
	v_mfma_f32_16x16x32_bf16 v[48:51], v[82:85], v[238:241], v[48:51]
	v_mfma_f32_16x16x32_bf16 v[52:55], v[82:85], v[242:245], v[52:55]
	v_mfma_f32_16x16x32_bf16 v[56:59], v[82:85], v[246:249], v[56:59]
	v_mfma_f32_16x16x32_bf16 v[60:63], v[82:85], v[250:253], v[60:63]
	s_setprio 0
	s_waitcnt vmcnt(0)
	s_barrier
	ds_read_b128 v[64:67], v217 offset:32768
	ds_read_b128 v[68:71], v217 offset:34816
	ds_read_b128 v[86:89], v78 offset:32768
	ds_read_b128 v[120:123], v78 offset:34816
	ds_read_b128 v[124:127], v78 offset:36864
	ds_read_b128 v[128:131], v78 offset:38912
	ds_read_b128 v[132:135], v78 offset:40960
	ds_read_b128 v[136:139], v78 offset:43008
	ds_read_b128 v[140:143], v78 offset:45056
	ds_read_b128 v[218:221], v78 offset:47104
	ds_read_b128 v[72:75], v255 offset:32768
	ds_read_b128 v[82:85], v255 offset:34816
	ds_read_b128 v[222:225], v79 offset:32768
	ds_read_b128 v[226:229], v79 offset:34816
	ds_read_b128 v[230:233], v79 offset:36864
	ds_read_b128 v[234:237], v79 offset:38912
	ds_read_b128 v[238:241], v79 offset:40960
	ds_read_b128 v[242:245], v79 offset:43008
	ds_read_b128 v[246:249], v79 offset:45056
	ds_read_b128 v[250:253], v79 offset:47104
	s_waitcnt lgkmcnt(0)
	s_barrier
	s_setprio 1
	v_mfma_f32_16x16x32_bf16 v[0:3], v[64:67], v[86:89], v[0:3]
	v_mfma_f32_16x16x32_bf16 v[4:7], v[64:67], v[120:123], v[4:7]
	v_mfma_f32_16x16x32_bf16 v[8:11], v[64:67], v[124:127], v[8:11]
	v_mfma_f32_16x16x32_bf16 v[12:15], v[64:67], v[128:131], v[12:15]
	v_mfma_f32_16x16x32_bf16 v[16:19], v[64:67], v[132:135], v[16:19]
	v_mfma_f32_16x16x32_bf16 v[20:23], v[64:67], v[136:139], v[20:23]
	v_mfma_f32_16x16x32_bf16 v[24:27], v[64:67], v[140:143], v[24:27]
	v_mfma_f32_16x16x32_bf16 v[28:31], v[64:67], v[218:221], v[28:31]
	v_mfma_f32_16x16x32_bf16 v[32:35], v[68:71], v[86:89], v[32:35]
	v_mfma_f32_16x16x32_bf16 v[36:39], v[68:71], v[120:123], v[36:39]
	v_mfma_f32_16x16x32_bf16 v[40:43], v[68:71], v[124:127], v[40:43]
	v_mfma_f32_16x16x32_bf16 v[44:47], v[68:71], v[128:131], v[44:47]
	v_mfma_f32_16x16x32_bf16 v[48:51], v[68:71], v[132:135], v[48:51]
	v_mfma_f32_16x16x32_bf16 v[52:55], v[68:71], v[136:139], v[52:55]
	v_mfma_f32_16x16x32_bf16 v[56:59], v[68:71], v[140:143], v[56:59]
	v_mfma_f32_16x16x32_bf16 v[60:63], v[68:71], v[218:221], v[60:63]
	v_mfma_f32_16x16x32_bf16 v[0:3], v[72:75], v[222:225], v[0:3]
	v_mfma_f32_16x16x32_bf16 v[4:7], v[72:75], v[226:229], v[4:7]
	v_mfma_f32_16x16x32_bf16 v[8:11], v[72:75], v[230:233], v[8:11]
	v_mfma_f32_16x16x32_bf16 v[12:15], v[72:75], v[234:237], v[12:15]
	v_mfma_f32_16x16x32_bf16 v[16:19], v[72:75], v[238:241], v[16:19]
	v_mfma_f32_16x16x32_bf16 v[20:23], v[72:75], v[242:245], v[20:23]
	v_mfma_f32_16x16x32_bf16 v[24:27], v[72:75], v[246:249], v[24:27]
	v_mfma_f32_16x16x32_bf16 v[28:31], v[72:75], v[250:253], v[28:31]
	v_mfma_f32_16x16x32_bf16 v[32:35], v[82:85], v[222:225], v[32:35]
	v_mfma_f32_16x16x32_bf16 v[36:39], v[82:85], v[226:229], v[36:39]
	v_mfma_f32_16x16x32_bf16 v[40:43], v[82:85], v[230:233], v[40:43]
	v_mfma_f32_16x16x32_bf16 v[44:47], v[82:85], v[234:237], v[44:47]
	v_mfma_f32_16x16x32_bf16 v[48:51], v[82:85], v[238:241], v[48:51]
	v_mfma_f32_16x16x32_bf16 v[52:55], v[82:85], v[242:245], v[52:55]
	v_mfma_f32_16x16x32_bf16 v[56:59], v[82:85], v[246:249], v[56:59]
	v_mfma_f32_16x16x32_bf16 v[60:63], v[82:85], v[250:253], v[60:63]
	s_setprio 0
	s_nop 7
	s_nop 7
	v_and_b32_e32 v66, 63, v199
	v_lshrrev_b32_e32 v67, 6, v199
	v_lshlrev_b32_e32 v67, 14, v67
	v_lshl_add_u32 v64, v66, 4, v67
	v_and_b32_e32 v65, 15, v66
	v_lshl_add_u32 v65, v65, 4, v67
	v_bfe_u32 v67, v66, 4, 1
	v_lshl_add_u32 v65, v67, 10, v65
	v_bfe_u32 v67, v66, 5, 1
	v_lshl_add_u32 v65, v67, 8, v65
	ds_write_b128 v64, v[0:3]
	ds_write_b128 v64, v[4:7] offset:1024
	ds_write_b128 v64, v[8:11] offset:2048
	ds_write_b128 v64, v[12:15] offset:3072
	ds_write_b128 v64, v[16:19] offset:4096
	ds_write_b128 v64, v[20:23] offset:5120
	ds_write_b128 v64, v[24:27] offset:6144
	ds_write_b128 v64, v[28:31] offset:7168
	ds_write_b128 v64, v[32:35] offset:8192
	ds_write_b128 v64, v[36:39] offset:9216
	ds_write_b128 v64, v[40:43] offset:10240
	ds_write_b128 v64, v[44:47] offset:11264
	ds_write_b128 v64, v[48:51] offset:12288
	ds_write_b128 v64, v[52:55] offset:13312
	ds_write_b128 v64, v[56:59] offset:14336
	ds_write_b128 v64, v[60:63] offset:15360
	s_waitcnt lgkmcnt(0)
	ds_read_b128 v[48:51], v65
	ds_read_b128 v[52:55], v65 offset:512
	ds_read_b128 v[56:59], v65 offset:8192
	ds_read_b128 v[60:63], v65 offset:8704
	ds_read_b128 v[32:35], v65 offset:2048
	ds_read_b128 v[36:39], v65 offset:2560
	ds_read_b128 v[40:43], v65 offset:10240
	ds_read_b128 v[44:47], v65 offset:10752
	ds_read_b128 v[16:19], v65 offset:4096
	ds_read_b128 v[20:23], v65 offset:4608
	ds_read_b128 v[24:27], v65 offset:12288
	ds_read_b128 v[28:31], v65 offset:12800
	ds_read_b128 v[0:3], v65 offset:6144
	ds_read_b128 v[4:7], v65 offset:6656
	ds_read_b128 v[8:11], v65 offset:14336
	ds_read_b128 v[12:15], v65 offset:14848
	s_waitcnt lgkmcnt(0)
	s_barrier
	s_branch .LBB0_754

.LBB0_775:
	s_ashr_i32 s6, s3, 31
	s_lshr_b32 s6, s6, 26
	s_add_i32 s6, s3, s6
	s_ashr_i32 s58, s6, 6
	s_andn2_b32 s6, s6, 63
	s_sub_i32 s6, s3, s6
	s_ashr_i32 s59, s6, 31
	s_lshr_b32 s59, s59, 29
	s_add_i32 s59, s6, s59
	s_ashr_i32 s64, s59, 3
	s_and_b32 s59, s59, -8
	s_lshl_b32 s58, s58, 3
	s_sub_i32 s6, s6, s59
	s_add_i32 s6, s6, s58
	s_lshl_b32 s67, s6, 7
	s_lshl_b32 s68, s64, 7
	s_waitcnt lgkmcnt(0)
	s_mul_i32 s38, s6, 0xb0000
	s_add_u32 s18, s14, s38
	s_addc_u32 s19, s15, 0
	s_add_u32 s18, s18, 0x879f000
	s_addc_u32 s19, s19, 0
	s_add_u32 s20, s18, 0x2c000
	s_addc_u32 s21, s19, 0
	s_add_u32 s22, s20, 0x2c000
	s_addc_u32 s23, s21, 0
	s_add_u32 s24, s22, 0x2c000
	s_addc_u32 s25, s23, 0
	s_mul_i32 s38, s64, 0xb0000
	s_add_u32 s26, s14, s38
	s_addc_u32 s27, s15, 0
	s_add_u32 s26, s26, 0x45a0000
	s_addc_u32 s27, s27, 0
	s_add_u32 s28, s26, 0x2c000
	s_addc_u32 s29, s27, 0
	s_add_u32 s30, s28, 0x2c000
	s_addc_u32 s31, s29, 0
	s_add_u32 s34, s30, 0x2c000
	s_addc_u32 s35, s31, 0
	v_and_b32_e32 v70, 15, v199
	v_bfe_u32 v71, v199, 4, 2
	v_lshrrev_b32_e32 v72, 1, v70
	v_xor_b32_e32 v71, v71, v72
	v_lshlrev_b32_e32 v71, 4, v71
	v_lshl_or_b32 v71, v70, 7, v71
	v_lshrrev_b32_e32 v72, 6, v199
	v_lshl_add_u32 v238, v72, 12, v71
	v_xor_b32_e32 v239, 64, v238
	v_add_u32_e32 v240, 0x4000, v71
	v_xor_b32_e32 v241, 64, v240
	v_readfirstlane_b32 s36, v141
	v_mov_b32_e32 v254, v64
	s_mov_b32 m0, s36
	s_nop 0
	global_load_lds_dwordx4 v254, s[18:19]
	s_add_u32 m0, m0, 0x1000
	s_nop 0
	global_load_lds_dwordx4 v254, s[20:21]
	s_add_u32 m0, m0, 0x1000
	s_nop 0
	global_load_lds_dwordx4 v254, s[22:23]
	s_add_u32 m0, m0, 0x1000
	s_nop 0
	global_load_lds_dwordx4 v254, s[24:25]
	s_add_u32 m0, m0, 0x1000
	s_nop 0
	global_load_lds_dwordx4 v254, s[26:27]
	s_add_u32 m0, m0, 0x1000
	s_nop 0
	global_load_lds_dwordx4 v254, s[28:29]
	s_add_u32 m0, m0, 0x1000
	s_nop 0
	global_load_lds_dwordx4 v254, s[30:31]
	s_add_u32 m0, m0, 0x1000
	s_nop 0
	global_load_lds_dwordx4 v254, s[34:35]
	v_add_u32_e32 v254, 0x80, v254
	s_add_u32 m0, s36, 0x8000
	s_nop 0
	global_load_lds_dwordx4 v254, s[18:19]
	s_add_u32 m0, m0, 0x1000
	s_nop 0
	global_load_lds_dwordx4 v254, s[20:21]
	s_add_u32 m0, m0, 0x1000
	s_nop 0
	global_load_lds_dwordx4 v254, s[22:23]
	s_add_u32 m0, m0, 0x1000
	s_nop 0
	global_load_lds_dwordx4 v254, s[24:25]
	s_add_u32 m0, m0, 0x1000
	s_nop 0
	global_load_lds_dwordx4 v254, s[26:27]
	s_add_u32 m0, m0, 0x1000
	s_nop 0
	global_load_lds_dwordx4 v254, s[28:29]
	s_add_u32 m0, m0, 0x1000
	s_nop 0
	global_load_lds_dwordx4 v254, s[30:31]
	s_add_u32 m0, m0, 0x1000
	s_nop 0
	global_load_lds_dwordx4 v254, s[34:35]
	v_add_u32_e32 v254, 0x80, v254
	v_mov_b32_e32 v48, 0
	v_mov_b32_e32 v49, 0
	v_mov_b32_e32 v50, 0
	v_mov_b32_e32 v51, 0
	v_mov_b32_e32 v52, 0
	v_mov_b32_e32 v53, 0
	v_mov_b32_e32 v54, 0
	v_mov_b32_e32 v55, 0
	v_mov_b32_e32 v56, 0
	v_mov_b32_e32 v57, 0
	v_mov_b32_e32 v58, 0
	v_mov_b32_e32 v59, 0
	v_mov_b32_e32 v60, 0
	v_mov_b32_e32 v61, 0
	v_mov_b32_e32 v62, 0
	v_mov_b32_e32 v63, 0
	v_mov_b32_e32 v32, 0
	v_mov_b32_e32 v33, 0
	v_mov_b32_e32 v34, 0
	v_mov_b32_e32 v35, 0
	v_mov_b32_e32 v36, 0
	v_mov_b32_e32 v37, 0
	v_mov_b32_e32 v38, 0
	v_mov_b32_e32 v39, 0
	v_mov_b32_e32 v40, 0
	v_mov_b32_e32 v41, 0
	v_mov_b32_e32 v42, 0
	v_mov_b32_e32 v43, 0
	v_mov_b32_e32 v44, 0
	v_mov_b32_e32 v45, 0
	v_mov_b32_e32 v46, 0
	v_mov_b32_e32 v47, 0
	v_mov_b32_e32 v16, 0
	v_mov_b32_e32 v17, 0
	v_mov_b32_e32 v18, 0
	v_mov_b32_e32 v19, 0
	v_mov_b32_e32 v20, 0
	v_mov_b32_e32 v21, 0
	v_mov_b32_e32 v22, 0
	v_mov_b32_e32 v23, 0
	v_mov_b32_e32 v24, 0
	v_mov_b32_e32 v25, 0
	v_mov_b32_e32 v26, 0
	v_mov_b32_e32 v27, 0
	v_mov_b32_e32 v28, 0
	v_mov_b32_e32 v29, 0
	v_mov_b32_e32 v30, 0
	v_mov_b32_e32 v31, 0
	v_mov_b32_e32 v0, 0
	v_mov_b32_e32 v1, 0
	v_mov_b32_e32 v2, 0
	v_mov_b32_e32 v3, 0
	v_mov_b32_e32 v4, 0
	v_mov_b32_e32 v5, 0
	v_mov_b32_e32 v6, 0
	v_mov_b32_e32 v7, 0
	v_mov_b32_e32 v8, 0
	v_mov_b32_e32 v9, 0
	v_mov_b32_e32 v10, 0
	v_mov_b32_e32 v11, 0
	v_mov_b32_e32 v12, 0
	v_mov_b32_e32 v13, 0
	v_mov_b32_e32 v14, 0
	v_mov_b32_e32 v15, 0
	s_mov_b32 s37, 21
.Lgk_loop_p8:
	s_waitcnt vmcnt(8)
	s_barrier
	ds_read_b128 v[70:73], v238
	ds_read_b128 v[74:77], v238 offset:2048
	ds_read_b128 v[86:89], v240
	ds_read_b128 v[90:93], v240 offset:2048
	ds_read_b128 v[94:97], v240 offset:4096
	ds_read_b128 v[98:101], v240 offset:6144
	ds_read_b128 v[102:105], v240 offset:8192
	ds_read_b128 v[106:109], v240 offset:10240
	ds_read_b128 v[110:113], v240 offset:12288
	ds_read_b128 v[202:205], v240 offset:14336
	ds_read_b128 v[78:81], v239
	ds_read_b128 v[82:85], v239 offset:2048
	ds_read_b128 v[206:209], v241
	ds_read_b128 v[210:213], v241 offset:2048
	ds_read_b128 v[214:217], v241 offset:4096
	ds_read_b128 v[218:221], v241 offset:6144
	ds_read_b128 v[222:225], v241 offset:8192
	ds_read_b128 v[226:229], v241 offset:10240
	ds_read_b128 v[230:233], v241 offset:12288
	ds_read_b128 v[234:237], v241 offset:14336
	s_waitcnt lgkmcnt(0)
	s_barrier
	s_mov_b32 m0, s36
	s_setprio 1
	v_mfma_f32_16x16x32_bf16 v[0:3], v[70:73], v[86:89], v[0:3]
	v_mfma_f32_16x16x32_bf16 v[4:7], v[70:73], v[90:93], v[4:7]
	v_mfma_f32_16x16x32_bf16 v[8:11], v[70:73], v[94:97], v[8:11]
	v_mfma_f32_16x16x32_bf16 v[12:15], v[70:73], v[98:101], v[12:15]
	global_load_lds_dwordx4 v254, s[18:19]
	s_add_u32 m0, m0, 0x1000
	v_mfma_f32_16x16x32_bf16 v[16:19], v[70:73], v[102:105], v[16:19]
	v_mfma_f32_16x16x32_bf16 v[20:23], v[70:73], v[106:109], v[20:23]
	v_mfma_f32_16x16x32_bf16 v[24:27], v[70:73], v[110:113], v[24:27]
	v_mfma_f32_16x16x32_bf16 v[28:31], v[70:73], v[202:205], v[28:31]
	global_load_lds_dwordx4 v254, s[20:21]
	s_add_u32 m0, m0, 0x1000
	v_mfma_f32_16x16x32_bf16 v[32:35], v[74:77], v[86:89], v[32:35]
	v_mfma_f32_16x16x32_bf16 v[36:39], v[74:77], v[90:93], v[36:39]
	v_mfma_f32_16x16x32_bf16 v[40:43], v[74:77], v[94:97], v[40:43]
	v_mfma_f32_16x16x32_bf16 v[44:47], v[74:77], v[98:101], v[44:47]
	global_load_lds_dwordx4 v254, s[22:23]
	s_add_u32 m0, m0, 0x1000
	v_mfma_f32_16x16x32_bf16 v[48:51], v[74:77], v[102:105], v[48:51]
	v_mfma_f32_16x16x32_bf16 v[52:55], v[74:77], v[106:109], v[52:55]
	v_mfma_f32_16x16x32_bf16 v[56:59], v[74:77], v[110:113], v[56:59]
	v_mfma_f32_16x16x32_bf16 v[60:63], v[74:77], v[202:205], v[60:63]
	global_load_lds_dwordx4 v254, s[24:25]
	s_add_u32 m0, m0, 0x1000
	v_mfma_f32_16x16x32_bf16 v[0:3], v[78:81], v[206:209], v[0:3]
	v_mfma_f32_16x16x32_bf16 v[4:7], v[78:81], v[210:213], v[4:7]
	v_mfma_f32_16x16x32_bf16 v[8:11], v[78:81], v[214:217], v[8:11]
	v_mfma_f32_16x16x32_bf16 v[12:15], v[78:81], v[218:221], v[12:15]
	global_load_lds_dwordx4 v254, s[26:27]
	s_add_u32 m0, m0, 0x1000
	v_mfma_f32_16x16x32_bf16 v[16:19], v[78:81], v[222:225], v[16:19]
	v_mfma_f32_16x16x32_bf16 v[20:23], v[78:81], v[226:229], v[20:23]
	v_mfma_f32_16x16x32_bf16 v[24:27], v[78:81], v[230:233], v[24:27]
	v_mfma_f32_16x16x32_bf16 v[28:31], v[78:81], v[234:237], v[28:31]
	global_load_lds_dwordx4 v254, s[28:29]
	s_add_u32 m0, m0, 0x1000
	v_mfma_f32_16x16x32_bf16 v[32:35], v[82:85], v[206:209], v[32:35]
	v_mfma_f32_16x16x32_bf16 v[36:39], v[82:85], v[210:213], v[36:39]
	v_mfma_f32_16x16x32_bf16 v[40:43], v[82:85], v[214:217], v[40:43]
	v_mfma_f32_16x16x32_bf16 v[44:47], v[82:85], v[218:221], v[44:47]
	global_load_lds_dwordx4 v254, s[30:31]
	s_add_u32 m0, m0, 0x1000
	v_mfma_f32_16x16x32_bf16 v[48:51], v[82:85], v[222:225], v[48:51]
	v_mfma_f32_16x16x32_bf16 v[52:55], v[82:85], v[226:229], v[52:55]
	v_mfma_f32_16x16x32_bf16 v[56:59], v[82:85], v[230:233], v[56:59]
	v_mfma_f32_16x16x32_bf16 v[60:63], v[82:85], v[234:237], v[60:63]
	global_load_lds_dwordx4 v254, s[34:35]
	s_setprio 0
	v_add_u32_e32 v254, 0x80, v254
	s_waitcnt vmcnt(8)
	s_barrier
	ds_read_b128 v[70:73], v238 offset:32768
	ds_read_b128 v[74:77], v238 offset:34816
	ds_read_b128 v[86:89], v240 offset:32768
	ds_read_b128 v[90:93], v240 offset:34816
	ds_read_b128 v[94:97], v240 offset:36864
	ds_read_b128 v[98:101], v240 offset:38912
	ds_read_b128 v[102:105], v240 offset:40960
	ds_read_b128 v[106:109], v240 offset:43008
	ds_read_b128 v[110:113], v240 offset:45056
	ds_read_b128 v[202:205], v240 offset:47104
	ds_read_b128 v[78:81], v239 offset:32768
	ds_read_b128 v[82:85], v239 offset:34816
	ds_read_b128 v[206:209], v241 offset:32768
	ds_read_b128 v[210:213], v241 offset:34816
	ds_read_b128 v[214:217], v241 offset:36864
	ds_read_b128 v[218:221], v241 offset:38912
	ds_read_b128 v[222:225], v241 offset:40960
	ds_read_b128 v[226:229], v241 offset:43008
	ds_read_b128 v[230:233], v241 offset:45056
	ds_read_b128 v[234:237], v241 offset:47104
	s_waitcnt lgkmcnt(0)
	s_barrier
	s_add_u32 m0, s36, 0x8000
	s_setprio 1
	v_mfma_f32_16x16x32_bf16 v[0:3], v[70:73], v[86:89], v[0:3]
	v_mfma_f32_16x16x32_bf16 v[4:7], v[70:73], v[90:93], v[4:7]
	v_mfma_f32_16x16x32_bf16 v[8:11], v[70:73], v[94:97], v[8:11]
	v_mfma_f32_16x16x32_bf16 v[12:15], v[70:73], v[98:101], v[12:15]
	global_load_lds_dwordx4 v254, s[18:19]
	s_add_u32 m0, m0, 0x1000
	v_mfma_f32_16x16x32_bf16 v[16:19], v[70:73], v[102:105], v[16:19]
	v_mfma_f32_16x16x32_bf16 v[20:23], v[70:73], v[106:109], v[20:23]
	v_mfma_f32_16x16x32_bf16 v[24:27], v[70:73], v[110:113], v[24:27]
	v_mfma_f32_16x16x32_bf16 v[28:31], v[70:73], v[202:205], v[28:31]
	global_load_lds_dwordx4 v254, s[20:21]
	s_add_u32 m0, m0, 0x1000
	v_mfma_f32_16x16x32_bf16 v[32:35], v[74:77], v[86:89], v[32:35]
	v_mfma_f32_16x16x32_bf16 v[36:39], v[74:77], v[90:93], v[36:39]
	v_mfma_f32_16x16x32_bf16 v[40:43], v[74:77], v[94:97], v[40:43]
	v_mfma_f32_16x16x32_bf16 v[44:47], v[74:77], v[98:101], v[44:47]
	global_load_lds_dwordx4 v254, s[22:23]
	s_add_u32 m0, m0, 0x1000
	v_mfma_f32_16x16x32_bf16 v[48:51], v[74:77], v[102:105], v[48:51]
	v_mfma_f32_16x16x32_bf16 v[52:55], v[74:77], v[106:109], v[52:55]
	v_mfma_f32_16x16x32_bf16 v[56:59], v[74:77], v[110:113], v[56:59]
	v_mfma_f32_16x16x32_bf16 v[60:63], v[74:77], v[202:205], v[60:63]
	global_load_lds_dwordx4 v254, s[24:25]
	s_add_u32 m0, m0, 0x1000
	v_mfma_f32_16x16x32_bf16 v[0:3], v[78:81], v[206:209], v[0:3]
	v_mfma_f32_16x16x32_bf16 v[4:7], v[78:81], v[210:213], v[4:7]
	v_mfma_f32_16x16x32_bf16 v[8:11], v[78:81], v[214:217], v[8:11]
	v_mfma_f32_16x16x32_bf16 v[12:15], v[78:81], v[218:221], v[12:15]
	global_load_lds_dwordx4 v254, s[26:27]
	s_add_u32 m0, m0, 0x1000
	v_mfma_f32_16x16x32_bf16 v[16:19], v[78:81], v[222:225], v[16:19]
	v_mfma_f32_16x16x32_bf16 v[20:23], v[78:81], v[226:229], v[20:23]
	v_mfma_f32_16x16x32_bf16 v[24:27], v[78:81], v[230:233], v[24:27]
	v_mfma_f32_16x16x32_bf16 v[28:31], v[78:81], v[234:237], v[28:31]
	global_load_lds_dwordx4 v254, s[28:29]
	s_add_u32 m0, m0, 0x1000
	v_mfma_f32_16x16x32_bf16 v[32:35], v[82:85], v[206:209], v[32:35]
	v_mfma_f32_16x16x32_bf16 v[36:39], v[82:85], v[210:213], v[36:39]
	v_mfma_f32_16x16x32_bf16 v[40:43], v[82:85], v[214:217], v[40:43]
	v_mfma_f32_16x16x32_bf16 v[44:47], v[82:85], v[218:221], v[44:47]
	global_load_lds_dwordx4 v254, s[30:31]
	s_add_u32 m0, m0, 0x1000
	v_mfma_f32_16x16x32_bf16 v[48:51], v[82:85], v[222:225], v[48:51]
	v_mfma_f32_16x16x32_bf16 v[52:55], v[82:85], v[226:229], v[52:55]
	v_mfma_f32_16x16x32_bf16 v[56:59], v[82:85], v[230:233], v[56:59]
	v_mfma_f32_16x16x32_bf16 v[60:63], v[82:85], v[234:237], v[60:63]
	global_load_lds_dwordx4 v254, s[34:35]
	s_setprio 0
	v_add_u32_e32 v254, 0x80, v254
	s_sub_u32 s37, s37, 1
	s_cmp_lg_u32 s37, 0
	s_cbranch_scc1 .Lgk_loop_p8
	s_waitcnt vmcnt(8)
	s_barrier
	ds_read_b128 v[70:73], v238
	ds_read_b128 v[74:77], v238 offset:2048
	ds_read_b128 v[86:89], v240
	ds_read_b128 v[90:93], v240 offset:2048
	ds_read_b128 v[94:97], v240 offset:4096
	ds_read_b128 v[98:101], v240 offset:6144
	ds_read_b128 v[102:105], v240 offset:8192
	ds_read_b128 v[106:109], v240 offset:10240
	ds_read_b128 v[110:113], v240 offset:12288
	ds_read_b128 v[202:205], v240 offset:14336
	ds_read_b128 v[78:81], v239
	ds_read_b128 v[82:85], v239 offset:2048
	ds_read_b128 v[206:209], v241
	ds_read_b128 v[210:213], v241 offset:2048
	ds_read_b128 v[214:217], v241 offset:4096
	ds_read_b128 v[218:221], v241 offset:6144
	ds_read_b128 v[222:225], v241 offset:8192
	ds_read_b128 v[226:229], v241 offset:10240
	ds_read_b128 v[230:233], v241 offset:12288
	ds_read_b128 v[234:237], v241 offset:14336
	s_waitcnt lgkmcnt(0)
	s_barrier
	s_setprio 1
	v_mfma_f32_16x16x32_bf16 v[0:3], v[70:73], v[86:89], v[0:3]
	v_mfma_f32_16x16x32_bf16 v[4:7], v[70:73], v[90:93], v[4:7]
	v_mfma_f32_16x16x32_bf16 v[8:11], v[70:73], v[94:97], v[8:11]
	v_mfma_f32_16x16x32_bf16 v[12:15], v[70:73], v[98:101], v[12:15]
	v_mfma_f32_16x16x32_bf16 v[16:19], v[70:73], v[102:105], v[16:19]
	v_mfma_f32_16x16x32_bf16 v[20:23], v[70:73], v[106:109], v[20:23]
	v_mfma_f32_16x16x32_bf16 v[24:27], v[70:73], v[110:113], v[24:27]
	v_mfma_f32_16x16x32_bf16 v[28:31], v[70:73], v[202:205], v[28:31]
	v_mfma_f32_16x16x32_bf16 v[32:35], v[74:77], v[86:89], v[32:35]
	v_mfma_f32_16x16x32_bf16 v[36:39], v[74:77], v[90:93], v[36:39]
	v_mfma_f32_16x16x32_bf16 v[40:43], v[74:77], v[94:97], v[40:43]
	v_mfma_f32_16x16x32_bf16 v[44:47], v[74:77], v[98:101], v[44:47]
	v_mfma_f32_16x16x32_bf16 v[48:51], v[74:77], v[102:105], v[48:51]
	v_mfma_f32_16x16x32_bf16 v[52:55], v[74:77], v[106:109], v[52:55]
	v_mfma_f32_16x16x32_bf16 v[56:59], v[74:77], v[110:113], v[56:59]
	v_mfma_f32_16x16x32_bf16 v[60:63], v[74:77], v[202:205], v[60:63]
	v_mfma_f32_16x16x32_bf16 v[0:3], v[78:81], v[206:209], v[0:3]
	v_mfma_f32_16x16x32_bf16 v[4:7], v[78:81], v[210:213], v[4:7]
	v_mfma_f32_16x16x32_bf16 v[8:11], v[78:81], v[214:217], v[8:11]
	v_mfma_f32_16x16x32_bf16 v[12:15], v[78:81], v[218:221], v[12:15]
	v_mfma_f32_16x16x32_bf16 v[16:19], v[78:81], v[222:225], v[16:19]
	v_mfma_f32_16x16x32_bf16 v[20:23], v[78:81], v[226:229], v[20:23]
	v_mfma_f32_16x16x32_bf16 v[24:27], v[78:81], v[230:233], v[24:27]
	v_mfma_f32_16x16x32_bf16 v[28:31], v[78:81], v[234:237], v[28:31]
	v_mfma_f32_16x16x32_bf16 v[32:35], v[82:85], v[206:209], v[32:35]
	v_mfma_f32_16x16x32_bf16 v[36:39], v[82:85], v[210:213], v[36:39]
	v_mfma_f32_16x16x32_bf16 v[40:43], v[82:85], v[214:217], v[40:43]
	v_mfma_f32_16x16x32_bf16 v[44:47], v[82:85], v[218:221], v[44:47]
	v_mfma_f32_16x16x32_bf16 v[48:51], v[82:85], v[222:225], v[48:51]
	v_mfma_f32_16x16x32_bf16 v[52:55], v[82:85], v[226:229], v[52:55]
	v_mfma_f32_16x16x32_bf16 v[56:59], v[82:85], v[230:233], v[56:59]
	v_mfma_f32_16x16x32_bf16 v[60:63], v[82:85], v[234:237], v[60:63]
	s_setprio 0
	s_waitcnt vmcnt(0)
	s_barrier
	ds_read_b128 v[70:73], v238 offset:32768
	ds_read_b128 v[74:77], v238 offset:34816
	ds_read_b128 v[86:89], v240 offset:32768
	ds_read_b128 v[90:93], v240 offset:34816
	ds_read_b128 v[94:97], v240 offset:36864
	ds_read_b128 v[98:101], v240 offset:38912
	ds_read_b128 v[102:105], v240 offset:40960
	ds_read_b128 v[106:109], v240 offset:43008
	ds_read_b128 v[110:113], v240 offset:45056
	ds_read_b128 v[202:205], v240 offset:47104
	ds_read_b128 v[78:81], v239 offset:32768
	ds_read_b128 v[82:85], v239 offset:34816
	ds_read_b128 v[206:209], v241 offset:32768
	ds_read_b128 v[210:213], v241 offset:34816
	ds_read_b128 v[214:217], v241 offset:36864
	ds_read_b128 v[218:221], v241 offset:38912
	ds_read_b128 v[222:225], v241 offset:40960
	ds_read_b128 v[226:229], v241 offset:43008
	ds_read_b128 v[230:233], v241 offset:45056
	ds_read_b128 v[234:237], v241 offset:47104
	s_waitcnt lgkmcnt(0)
	s_barrier
	s_setprio 1
	v_mfma_f32_16x16x32_bf16 v[0:3], v[70:73], v[86:89], v[0:3]
	v_mfma_f32_16x16x32_bf16 v[4:7], v[70:73], v[90:93], v[4:7]
	v_mfma_f32_16x16x32_bf16 v[8:11], v[70:73], v[94:97], v[8:11]
	v_mfma_f32_16x16x32_bf16 v[12:15], v[70:73], v[98:101], v[12:15]
	v_mfma_f32_16x16x32_bf16 v[16:19], v[70:73], v[102:105], v[16:19]
	v_mfma_f32_16x16x32_bf16 v[20:23], v[70:73], v[106:109], v[20:23]
	v_mfma_f32_16x16x32_bf16 v[24:27], v[70:73], v[110:113], v[24:27]
	v_mfma_f32_16x16x32_bf16 v[28:31], v[70:73], v[202:205], v[28:31]
	v_mfma_f32_16x16x32_bf16 v[32:35], v[74:77], v[86:89], v[32:35]
	v_mfma_f32_16x16x32_bf16 v[36:39], v[74:77], v[90:93], v[36:39]
	v_mfma_f32_16x16x32_bf16 v[40:43], v[74:77], v[94:97], v[40:43]
	v_mfma_f32_16x16x32_bf16 v[44:47], v[74:77], v[98:101], v[44:47]
	v_mfma_f32_16x16x32_bf16 v[48:51], v[74:77], v[102:105], v[48:51]
	v_mfma_f32_16x16x32_bf16 v[52:55], v[74:77], v[106:109], v[52:55]
	v_mfma_f32_16x16x32_bf16 v[56:59], v[74:77], v[110:113], v[56:59]
	v_mfma_f32_16x16x32_bf16 v[60:63], v[74:77], v[202:205], v[60:63]
	v_mfma_f32_16x16x32_bf16 v[0:3], v[78:81], v[206:209], v[0:3]
	v_mfma_f32_16x16x32_bf16 v[4:7], v[78:81], v[210:213], v[4:7]
	v_mfma_f32_16x16x32_bf16 v[8:11], v[78:81], v[214:217], v[8:11]
	v_mfma_f32_16x16x32_bf16 v[12:15], v[78:81], v[218:221], v[12:15]
	v_mfma_f32_16x16x32_bf16 v[16:19], v[78:81], v[222:225], v[16:19]
	v_mfma_f32_16x16x32_bf16 v[20:23], v[78:81], v[226:229], v[20:23]
	v_mfma_f32_16x16x32_bf16 v[24:27], v[78:81], v[230:233], v[24:27]
	v_mfma_f32_16x16x32_bf16 v[28:31], v[78:81], v[234:237], v[28:31]
	v_mfma_f32_16x16x32_bf16 v[32:35], v[82:85], v[206:209], v[32:35]
	v_mfma_f32_16x16x32_bf16 v[36:39], v[82:85], v[210:213], v[36:39]
	v_mfma_f32_16x16x32_bf16 v[40:43], v[82:85], v[214:217], v[40:43]
	v_mfma_f32_16x16x32_bf16 v[44:47], v[82:85], v[218:221], v[44:47]
	v_mfma_f32_16x16x32_bf16 v[48:51], v[82:85], v[222:225], v[48:51]
	v_mfma_f32_16x16x32_bf16 v[52:55], v[82:85], v[226:229], v[52:55]
	v_mfma_f32_16x16x32_bf16 v[56:59], v[82:85], v[230:233], v[56:59]
	v_mfma_f32_16x16x32_bf16 v[60:63], v[82:85], v[234:237], v[60:63]
	s_setprio 0
	s_nop 7
	s_nop 7
	v_and_b32_e32 v72, 63, v199
	v_lshrrev_b32_e32 v73, 6, v199
	v_lshlrev_b32_e32 v73, 14, v73
	v_lshl_add_u32 v70, v72, 4, v73
	v_and_b32_e32 v71, 15, v72
	v_lshl_add_u32 v71, v71, 4, v73
	v_bfe_u32 v73, v72, 4, 1
	v_lshl_add_u32 v71, v73, 10, v71
	v_bfe_u32 v73, v72, 5, 1
	v_lshl_add_u32 v71, v73, 8, v71
	ds_write_b128 v70, v[0:3]
	ds_write_b128 v70, v[4:7] offset:1024
	ds_write_b128 v70, v[8:11] offset:2048
	ds_write_b128 v70, v[12:15] offset:3072
	ds_write_b128 v70, v[16:19] offset:4096
	ds_write_b128 v70, v[20:23] offset:5120
	ds_write_b128 v70, v[24:27] offset:6144
	ds_write_b128 v70, v[28:31] offset:7168
	ds_write_b128 v70, v[32:35] offset:8192
	ds_write_b128 v70, v[36:39] offset:9216
	ds_write_b128 v70, v[40:43] offset:10240
	ds_write_b128 v70, v[44:47] offset:11264
	ds_write_b128 v70, v[48:51] offset:12288
	ds_write_b128 v70, v[52:55] offset:13312
	ds_write_b128 v70, v[56:59] offset:14336
	ds_write_b128 v70, v[60:63] offset:15360
	s_waitcnt lgkmcnt(0)
	ds_read_b128 v[48:51], v71
	ds_read_b128 v[52:55], v71 offset:512
	ds_read_b128 v[56:59], v71 offset:8192
	ds_read_b128 v[60:63], v71 offset:8704
	ds_read_b128 v[32:35], v71 offset:2048
	ds_read_b128 v[36:39], v71 offset:2560
	ds_read_b128 v[40:43], v71 offset:10240
	ds_read_b128 v[44:47], v71 offset:10752
	ds_read_b128 v[16:19], v71 offset:4096
	ds_read_b128 v[20:23], v71 offset:4608
	ds_read_b128 v[24:27], v71 offset:12288
	ds_read_b128 v[28:31], v71 offset:12800
	ds_read_b128 v[0:3], v71 offset:6144
	ds_read_b128 v[4:7], v71 offset:6656
	ds_read_b128 v[8:11], v71 offset:14336
	ds_read_b128 v[12:15], v71 offset:14848
	s_waitcnt lgkmcnt(0)
	s_barrier
	s_branch .LBB0_779

.LBB0_828:
	s_mul_hi_i32 s0, s3, 0x2aaaaaab
	s_lshr_b32 s1, s0, 31
	s_ashr_i32 s0, s0, 5
	s_add_i32 s0, s0, s1
	s_lshl_b32 s1, s0, 3
	s_mulk_i32 s0, 0xff40
	s_add_i32 s0, s0, s3
	s_ashr_i32 s4, s0, 31
	s_lshr_b32 s4, s4, 29
	s_add_i32 s4, s0, s4
	s_ashr_i32 s86, s4, 3
	s_and_b32 s4, s4, -8
	s_sub_i32 s8, s0, s4
	s_add_i32 s8, s8, s1
	s_lshl_b32 s68, s8, 7
	s_lshl_b32 s0, s86, 7
	s_ashr_i32 s69, s68, 31
	s_ashr_i32 s1, s0, 31
	s_lshl_b64 s[4:5], s[68:69], 11
	s_lshl_b64 s[70:71], s[0:1], 11
	s_lshl_b32 s48, s68, 11
	s_add_u32 s28, s14, s48
	s_addc_u32 s29, s15, 0
	s_add_u32 s28, s28, 0x679f000
	s_addc_u32 s29, s29, 0
	s_add_u32 s30, s28, 0x10000
	s_addc_u32 s31, s29, 0
	s_add_u32 s34, s30, 0x10000
	s_addc_u32 s35, s31, 0
	s_add_u32 s36, s34, 0x10000
	s_addc_u32 s37, s35, 0
	s_lshl_b32 s48, s0, 11
	s_add_u32 s38, s14, s48
	s_addc_u32 s39, s15, 0
	s_add_u32 s38, s38, 0x5a0000
	s_addc_u32 s39, s39, 0
	s_add_u32 s40, s38, 0x10000
	s_addc_u32 s41, s39, 0
	s_add_u32 s42, s40, 0x10000
	s_addc_u32 s43, s41, 0
	s_add_u32 s44, s42, 0x10000
	s_addc_u32 s45, s43, 0
	v_and_b32_e32 v64, 15, v199
	v_bfe_u32 v65, v199, 4, 2
	v_lshrrev_b32_e32 v66, 1, v64
	v_xor_b32_e32 v65, v65, v66
	v_lshlrev_b32_e32 v65, 4, v65
	v_lshl_or_b32 v65, v64, 7, v65
	v_lshrrev_b32_e32 v66, 6, v199
	v_lshl_add_u32 v255, v66, 12, v65
	v_xor_b32_e32 v139, 64, v255
	v_add_u32_e32 v141, 0x4000, v65
	v_xor_b32_e32 v144, 64, v141
	v_readfirstlane_b32 s46, v183
	v_mov_b32_e32 v254, v142
	s_mov_b32 m0, s46
	s_nop 0
	global_load_lds_dwordx4 v254, s[28:29]
	s_add_u32 m0, m0, 0x1000
	s_nop 0
	global_load_lds_dwordx4 v254, s[30:31]
	s_add_u32 m0, m0, 0x1000
	s_nop 0
	global_load_lds_dwordx4 v254, s[34:35]
	s_add_u32 m0, m0, 0x1000
	s_nop 0
	global_load_lds_dwordx4 v254, s[36:37]
	s_add_u32 m0, m0, 0x1000
	s_nop 0
	global_load_lds_dwordx4 v254, s[38:39]
	s_add_u32 m0, m0, 0x1000
	s_nop 0
	global_load_lds_dwordx4 v254, s[40:41]
	s_add_u32 m0, m0, 0x1000
	s_nop 0
	global_load_lds_dwordx4 v254, s[42:43]
	s_add_u32 m0, m0, 0x1000
	s_nop 0
	global_load_lds_dwordx4 v254, s[44:45]
	v_add_u32_e32 v254, 0x80, v254
	s_add_u32 m0, s46, 0x8000
	s_nop 0
	global_load_lds_dwordx4 v254, s[28:29]
	s_add_u32 m0, m0, 0x1000
	s_nop 0
	global_load_lds_dwordx4 v254, s[30:31]
	s_add_u32 m0, m0, 0x1000
	s_nop 0
	global_load_lds_dwordx4 v254, s[34:35]
	s_add_u32 m0, m0, 0x1000
	s_nop 0
	global_load_lds_dwordx4 v254, s[36:37]
	s_add_u32 m0, m0, 0x1000
	s_nop 0
	global_load_lds_dwordx4 v254, s[38:39]
	s_add_u32 m0, m0, 0x1000
	s_nop 0
	global_load_lds_dwordx4 v254, s[40:41]
	s_add_u32 m0, m0, 0x1000
	s_nop 0
	global_load_lds_dwordx4 v254, s[42:43]
	s_add_u32 m0, m0, 0x1000
	s_nop 0
	global_load_lds_dwordx4 v254, s[44:45]
	v_add_u32_e32 v254, 0x80, v254
	v_mov_b32_e32 v48, 0
	v_mov_b32_e32 v49, 0
	v_mov_b32_e32 v50, 0
	v_mov_b32_e32 v51, 0
	v_mov_b32_e32 v52, 0
	v_mov_b32_e32 v53, 0
	v_mov_b32_e32 v54, 0
	v_mov_b32_e32 v55, 0
	v_mov_b32_e32 v56, 0
	v_mov_b32_e32 v57, 0
	v_mov_b32_e32 v58, 0
	v_mov_b32_e32 v59, 0
	v_mov_b32_e32 v60, 0
	v_mov_b32_e32 v61, 0
	v_mov_b32_e32 v62, 0
	v_mov_b32_e32 v63, 0
	v_mov_b32_e32 v32, 0
	v_mov_b32_e32 v33, 0
	v_mov_b32_e32 v34, 0
	v_mov_b32_e32 v35, 0
	v_mov_b32_e32 v36, 0
	v_mov_b32_e32 v37, 0
	v_mov_b32_e32 v38, 0
	v_mov_b32_e32 v39, 0
	v_mov_b32_e32 v40, 0
	v_mov_b32_e32 v41, 0
	v_mov_b32_e32 v42, 0
	v_mov_b32_e32 v43, 0
	v_mov_b32_e32 v44, 0
	v_mov_b32_e32 v45, 0
	v_mov_b32_e32 v46, 0
	v_mov_b32_e32 v47, 0
	v_mov_b32_e32 v16, 0
	v_mov_b32_e32 v17, 0
	v_mov_b32_e32 v18, 0
	v_mov_b32_e32 v19, 0
	v_mov_b32_e32 v20, 0
	v_mov_b32_e32 v21, 0
	v_mov_b32_e32 v22, 0
	v_mov_b32_e32 v23, 0
	v_mov_b32_e32 v24, 0
	v_mov_b32_e32 v25, 0
	v_mov_b32_e32 v26, 0
	v_mov_b32_e32 v27, 0
	v_mov_b32_e32 v28, 0
	v_mov_b32_e32 v29, 0
	v_mov_b32_e32 v30, 0
	v_mov_b32_e32 v31, 0
	v_mov_b32_e32 v0, 0
	v_mov_b32_e32 v1, 0
	v_mov_b32_e32 v2, 0
	v_mov_b32_e32 v3, 0
	v_mov_b32_e32 v4, 0
	v_mov_b32_e32 v5, 0
	v_mov_b32_e32 v6, 0
	v_mov_b32_e32 v7, 0
	v_mov_b32_e32 v8, 0
	v_mov_b32_e32 v9, 0
	v_mov_b32_e32 v10, 0
	v_mov_b32_e32 v11, 0
	v_mov_b32_e32 v12, 0
	v_mov_b32_e32 v13, 0
	v_mov_b32_e32 v14, 0
	v_mov_b32_e32 v15, 0
	s_mov_b32 s47, 7
.Lgk_loop_p9:
	s_waitcnt vmcnt(8)
	s_barrier
	ds_read_b128 v[64:67], v255
	ds_read_b128 v[68:71], v255 offset:2048
	ds_read_b128 v[80:83], v141
	ds_read_b128 v[84:87], v141 offset:2048
	ds_read_b128 v[88:91], v141 offset:4096
	ds_read_b128 v[92:95], v141 offset:6144
	ds_read_b128 v[96:99], v141 offset:8192
	ds_read_b128 v[100:103], v141 offset:10240
	ds_read_b128 v[104:107], v141 offset:12288
	ds_read_b128 v[108:111], v141 offset:14336
	ds_read_b128 v[72:75], v139
	ds_read_b128 v[76:79], v139 offset:2048
	ds_read_b128 v[112:115], v144
	ds_read_b128 v[226:229], v144 offset:2048
	ds_read_b128 v[230:233], v144 offset:4096
	ds_read_b128 v[234:237], v144 offset:6144
	ds_read_b128 v[238:241], v144 offset:8192
	ds_read_b128 v[242:245], v144 offset:10240
	ds_read_b128 v[246:249], v144 offset:12288
	ds_read_b128 v[250:253], v144 offset:14336
	s_waitcnt lgkmcnt(0)
	s_barrier
	s_mov_b32 m0, s46
	s_setprio 1
	v_mfma_f32_16x16x32_bf16 v[0:3], v[64:67], v[80:83], v[0:3]
	v_mfma_f32_16x16x32_bf16 v[4:7], v[64:67], v[84:87], v[4:7]
	v_mfma_f32_16x16x32_bf16 v[8:11], v[64:67], v[88:91], v[8:11]
	v_mfma_f32_16x16x32_bf16 v[12:15], v[64:67], v[92:95], v[12:15]
	global_load_lds_dwordx4 v254, s[28:29]
	s_add_u32 m0, m0, 0x1000
	v_mfma_f32_16x16x32_bf16 v[16:19], v[64:67], v[96:99], v[16:19]
	v_mfma_f32_16x16x32_bf16 v[20:23], v[64:67], v[100:103], v[20:23]
	v_mfma_f32_16x16x32_bf16 v[24:27], v[64:67], v[104:107], v[24:27]
	v_mfma_f32_16x16x32_bf16 v[28:31], v[64:67], v[108:111], v[28:31]
	global_load_lds_dwordx4 v254, s[30:31]
	s_add_u32 m0, m0, 0x1000
	v_mfma_f32_16x16x32_bf16 v[32:35], v[68:71], v[80:83], v[32:35]
	v_mfma_f32_16x16x32_bf16 v[36:39], v[68:71], v[84:87], v[36:39]
	v_mfma_f32_16x16x32_bf16 v[40:43], v[68:71], v[88:91], v[40:43]
	v_mfma_f32_16x16x32_bf16 v[44:47], v[68:71], v[92:95], v[44:47]
	global_load_lds_dwordx4 v254, s[34:35]
	s_add_u32 m0, m0, 0x1000
	v_mfma_f32_16x16x32_bf16 v[48:51], v[68:71], v[96:99], v[48:51]
	v_mfma_f32_16x16x32_bf16 v[52:55], v[68:71], v[100:103], v[52:55]
	v_mfma_f32_16x16x32_bf16 v[56:59], v[68:71], v[104:107], v[56:59]
	v_mfma_f32_16x16x32_bf16 v[60:63], v[68:71], v[108:111], v[60:63]
	global_load_lds_dwordx4 v254, s[36:37]
	s_add_u32 m0, m0, 0x1000
	v_mfma_f32_16x16x32_bf16 v[0:3], v[72:75], v[112:115], v[0:3]
	v_mfma_f32_16x16x32_bf16 v[4:7], v[72:75], v[226:229], v[4:7]
	v_mfma_f32_16x16x32_bf16 v[8:11], v[72:75], v[230:233], v[8:11]
	v_mfma_f32_16x16x32_bf16 v[12:15], v[72:75], v[234:237], v[12:15]
	global_load_lds_dwordx4 v254, s[38:39]
	s_add_u32 m0, m0, 0x1000
	v_mfma_f32_16x16x32_bf16 v[16:19], v[72:75], v[238:241], v[16:19]
	v_mfma_f32_16x16x32_bf16 v[20:23], v[72:75], v[242:245], v[20:23]
	v_mfma_f32_16x16x32_bf16 v[24:27], v[72:75], v[246:249], v[24:27]
	v_mfma_f32_16x16x32_bf16 v[28:31], v[72:75], v[250:253], v[28:31]
	global_load_lds_dwordx4 v254, s[40:41]
	s_add_u32 m0, m0, 0x1000
	v_mfma_f32_16x16x32_bf16 v[32:35], v[76:79], v[112:115], v[32:35]
	v_mfma_f32_16x16x32_bf16 v[36:39], v[76:79], v[226:229], v[36:39]
	v_mfma_f32_16x16x32_bf16 v[40:43], v[76:79], v[230:233], v[40:43]
	v_mfma_f32_16x16x32_bf16 v[44:47], v[76:79], v[234:237], v[44:47]
	global_load_lds_dwordx4 v254, s[42:43]
	s_add_u32 m0, m0, 0x1000
	v_mfma_f32_16x16x32_bf16 v[48:51], v[76:79], v[238:241], v[48:51]
	v_mfma_f32_16x16x32_bf16 v[52:55], v[76:79], v[242:245], v[52:55]
	v_mfma_f32_16x16x32_bf16 v[56:59], v[76:79], v[246:249], v[56:59]
	v_mfma_f32_16x16x32_bf16 v[60:63], v[76:79], v[250:253], v[60:63]
	global_load_lds_dwordx4 v254, s[44:45]
	s_setprio 0
	v_add_u32_e32 v254, 0x80, v254
	s_waitcnt vmcnt(8)
	s_barrier
	ds_read_b128 v[64:67], v255 offset:32768
	ds_read_b128 v[68:71], v255 offset:34816
	ds_read_b128 v[80:83], v141 offset:32768
	ds_read_b128 v[84:87], v141 offset:34816
	ds_read_b128 v[88:91], v141 offset:36864
	ds_read_b128 v[92:95], v141 offset:38912
	ds_read_b128 v[96:99], v141 offset:40960
	ds_read_b128 v[100:103], v141 offset:43008
	ds_read_b128 v[104:107], v141 offset:45056
	ds_read_b128 v[108:111], v141 offset:47104
	ds_read_b128 v[72:75], v139 offset:32768
	ds_read_b128 v[76:79], v139 offset:34816
	ds_read_b128 v[112:115], v144 offset:32768
	ds_read_b128 v[226:229], v144 offset:34816
	ds_read_b128 v[230:233], v144 offset:36864
	ds_read_b128 v[234:237], v144 offset:38912
	ds_read_b128 v[238:241], v144 offset:40960
	ds_read_b128 v[242:245], v144 offset:43008
	ds_read_b128 v[246:249], v144 offset:45056
	ds_read_b128 v[250:253], v144 offset:47104
	s_waitcnt lgkmcnt(0)
	s_barrier
	s_add_u32 m0, s46, 0x8000
	s_setprio 1
	v_mfma_f32_16x16x32_bf16 v[0:3], v[64:67], v[80:83], v[0:3]
	v_mfma_f32_16x16x32_bf16 v[4:7], v[64:67], v[84:87], v[4:7]
	v_mfma_f32_16x16x32_bf16 v[8:11], v[64:67], v[88:91], v[8:11]
	v_mfma_f32_16x16x32_bf16 v[12:15], v[64:67], v[92:95], v[12:15]
	global_load_lds_dwordx4 v254, s[28:29]
	s_add_u32 m0, m0, 0x1000
	v_mfma_f32_16x16x32_bf16 v[16:19], v[64:67], v[96:99], v[16:19]
	v_mfma_f32_16x16x32_bf16 v[20:23], v[64:67], v[100:103], v[20:23]
	v_mfma_f32_16x16x32_bf16 v[24:27], v[64:67], v[104:107], v[24:27]
	v_mfma_f32_16x16x32_bf16 v[28:31], v[64:67], v[108:111], v[28:31]
	global_load_lds_dwordx4 v254, s[30:31]
	s_add_u32 m0, m0, 0x1000
	v_mfma_f32_16x16x32_bf16 v[32:35], v[68:71], v[80:83], v[32:35]
	v_mfma_f32_16x16x32_bf16 v[36:39], v[68:71], v[84:87], v[36:39]
	v_mfma_f32_16x16x32_bf16 v[40:43], v[68:71], v[88:91], v[40:43]
	v_mfma_f32_16x16x32_bf16 v[44:47], v[68:71], v[92:95], v[44:47]
	global_load_lds_dwordx4 v254, s[34:35]
	s_add_u32 m0, m0, 0x1000
	v_mfma_f32_16x16x32_bf16 v[48:51], v[68:71], v[96:99], v[48:51]
	v_mfma_f32_16x16x32_bf16 v[52:55], v[68:71], v[100:103], v[52:55]
	v_mfma_f32_16x16x32_bf16 v[56:59], v[68:71], v[104:107], v[56:59]
	v_mfma_f32_16x16x32_bf16 v[60:63], v[68:71], v[108:111], v[60:63]
	global_load_lds_dwordx4 v254, s[36:37]
	s_add_u32 m0, m0, 0x1000
	v_mfma_f32_16x16x32_bf16 v[0:3], v[72:75], v[112:115], v[0:3]
	v_mfma_f32_16x16x32_bf16 v[4:7], v[72:75], v[226:229], v[4:7]
	v_mfma_f32_16x16x32_bf16 v[8:11], v[72:75], v[230:233], v[8:11]
	v_mfma_f32_16x16x32_bf16 v[12:15], v[72:75], v[234:237], v[12:15]
	global_load_lds_dwordx4 v254, s[38:39]
	s_add_u32 m0, m0, 0x1000
	v_mfma_f32_16x16x32_bf16 v[16:19], v[72:75], v[238:241], v[16:19]
	v_mfma_f32_16x16x32_bf16 v[20:23], v[72:75], v[242:245], v[20:23]
	v_mfma_f32_16x16x32_bf16 v[24:27], v[72:75], v[246:249], v[24:27]
	v_mfma_f32_16x16x32_bf16 v[28:31], v[72:75], v[250:253], v[28:31]
	global_load_lds_dwordx4 v254, s[40:41]
	s_add_u32 m0, m0, 0x1000
	v_mfma_f32_16x16x32_bf16 v[32:35], v[76:79], v[112:115], v[32:35]
	v_mfma_f32_16x16x32_bf16 v[36:39], v[76:79], v[226:229], v[36:39]
	v_mfma_f32_16x16x32_bf16 v[40:43], v[76:79], v[230:233], v[40:43]
	v_mfma_f32_16x16x32_bf16 v[44:47], v[76:79], v[234:237], v[44:47]
	global_load_lds_dwordx4 v254, s[42:43]
	s_add_u32 m0, m0, 0x1000
	v_mfma_f32_16x16x32_bf16 v[48:51], v[76:79], v[238:241], v[48:51]
	v_mfma_f32_16x16x32_bf16 v[52:55], v[76:79], v[242:245], v[52:55]
	v_mfma_f32_16x16x32_bf16 v[56:59], v[76:79], v[246:249], v[56:59]
	v_mfma_f32_16x16x32_bf16 v[60:63], v[76:79], v[250:253], v[60:63]
	global_load_lds_dwordx4 v254, s[44:45]
	s_setprio 0
	v_add_u32_e32 v254, 0x80, v254
	s_sub_u32 s47, s47, 1
	s_cmp_lg_u32 s47, 0
	s_cbranch_scc1 .Lgk_loop_p9
	s_waitcnt vmcnt(8)
	s_barrier
	ds_read_b128 v[64:67], v255
	ds_read_b128 v[68:71], v255 offset:2048
	ds_read_b128 v[80:83], v141
	ds_read_b128 v[84:87], v141 offset:2048
	ds_read_b128 v[88:91], v141 offset:4096
	ds_read_b128 v[92:95], v141 offset:6144
	ds_read_b128 v[96:99], v141 offset:8192
	ds_read_b128 v[100:103], v141 offset:10240
	ds_read_b128 v[104:107], v141 offset:12288
	ds_read_b128 v[108:111], v141 offset:14336
	ds_read_b128 v[72:75], v139
	ds_read_b128 v[76:79], v139 offset:2048
	ds_read_b128 v[112:115], v144
	ds_read_b128 v[226:229], v144 offset:2048
	ds_read_b128 v[230:233], v144 offset:4096
	ds_read_b128 v[234:237], v144 offset:6144
	ds_read_b128 v[238:241], v144 offset:8192
	ds_read_b128 v[242:245], v144 offset:10240
	ds_read_b128 v[246:249], v144 offset:12288
	ds_read_b128 v[250:253], v144 offset:14336
	s_waitcnt lgkmcnt(0)
	s_barrier
	s_setprio 1
	v_mfma_f32_16x16x32_bf16 v[0:3], v[64:67], v[80:83], v[0:3]
	v_mfma_f32_16x16x32_bf16 v[4:7], v[64:67], v[84:87], v[4:7]
	v_mfma_f32_16x16x32_bf16 v[8:11], v[64:67], v[88:91], v[8:11]
	v_mfma_f32_16x16x32_bf16 v[12:15], v[64:67], v[92:95], v[12:15]
	v_mfma_f32_16x16x32_bf16 v[16:19], v[64:67], v[96:99], v[16:19]
	v_mfma_f32_16x16x32_bf16 v[20:23], v[64:67], v[100:103], v[20:23]
	v_mfma_f32_16x16x32_bf16 v[24:27], v[64:67], v[104:107], v[24:27]
	v_mfma_f32_16x16x32_bf16 v[28:31], v[64:67], v[108:111], v[28:31]
	v_mfma_f32_16x16x32_bf16 v[32:35], v[68:71], v[80:83], v[32:35]
	v_mfma_f32_16x16x32_bf16 v[36:39], v[68:71], v[84:87], v[36:39]
	v_mfma_f32_16x16x32_bf16 v[40:43], v[68:71], v[88:91], v[40:43]
	v_mfma_f32_16x16x32_bf16 v[44:47], v[68:71], v[92:95], v[44:47]
	v_mfma_f32_16x16x32_bf16 v[48:51], v[68:71], v[96:99], v[48:51]
	v_mfma_f32_16x16x32_bf16 v[52:55], v[68:71], v[100:103], v[52:55]
	v_mfma_f32_16x16x32_bf16 v[56:59], v[68:71], v[104:107], v[56:59]
	v_mfma_f32_16x16x32_bf16 v[60:63], v[68:71], v[108:111], v[60:63]
	v_mfma_f32_16x16x32_bf16 v[0:3], v[72:75], v[112:115], v[0:3]
	v_mfma_f32_16x16x32_bf16 v[4:7], v[72:75], v[226:229], v[4:7]
	v_mfma_f32_16x16x32_bf16 v[8:11], v[72:75], v[230:233], v[8:11]
	v_mfma_f32_16x16x32_bf16 v[12:15], v[72:75], v[234:237], v[12:15]
	v_mfma_f32_16x16x32_bf16 v[16:19], v[72:75], v[238:241], v[16:19]
	v_mfma_f32_16x16x32_bf16 v[20:23], v[72:75], v[242:245], v[20:23]
	v_mfma_f32_16x16x32_bf16 v[24:27], v[72:75], v[246:249], v[24:27]
	v_mfma_f32_16x16x32_bf16 v[28:31], v[72:75], v[250:253], v[28:31]
	v_mfma_f32_16x16x32_bf16 v[32:35], v[76:79], v[112:115], v[32:35]
	v_mfma_f32_16x16x32_bf16 v[36:39], v[76:79], v[226:229], v[36:39]
	v_mfma_f32_16x16x32_bf16 v[40:43], v[76:79], v[230:233], v[40:43]
	v_mfma_f32_16x16x32_bf16 v[44:47], v[76:79], v[234:237], v[44:47]
	v_mfma_f32_16x16x32_bf16 v[48:51], v[76:79], v[238:241], v[48:51]
	v_mfma_f32_16x16x32_bf16 v[52:55], v[76:79], v[242:245], v[52:55]
	v_mfma_f32_16x16x32_bf16 v[56:59], v[76:79], v[246:249], v[56:59]
	v_mfma_f32_16x16x32_bf16 v[60:63], v[76:79], v[250:253], v[60:63]
	s_setprio 0
	s_waitcnt vmcnt(0)
	s_barrier
	ds_read_b128 v[64:67], v255 offset:32768
	ds_read_b128 v[68:71], v255 offset:34816
	ds_read_b128 v[80:83], v141 offset:32768
	ds_read_b128 v[84:87], v141 offset:34816
	ds_read_b128 v[88:91], v141 offset:36864
	ds_read_b128 v[92:95], v141 offset:38912
	ds_read_b128 v[96:99], v141 offset:40960
	ds_read_b128 v[100:103], v141 offset:43008
	ds_read_b128 v[104:107], v141 offset:45056
	ds_read_b128 v[108:111], v141 offset:47104
	ds_read_b128 v[72:75], v139 offset:32768
	ds_read_b128 v[76:79], v139 offset:34816
	ds_read_b128 v[112:115], v144 offset:32768
	ds_read_b128 v[226:229], v144 offset:34816
	ds_read_b128 v[230:233], v144 offset:36864
	ds_read_b128 v[234:237], v144 offset:38912
	ds_read_b128 v[238:241], v144 offset:40960
	ds_read_b128 v[242:245], v144 offset:43008
	ds_read_b128 v[246:249], v144 offset:45056
	ds_read_b128 v[250:253], v144 offset:47104
	s_waitcnt lgkmcnt(0)
	s_barrier
	s_setprio 1
	v_mfma_f32_16x16x32_bf16 v[0:3], v[64:67], v[80:83], v[0:3]
	v_mfma_f32_16x16x32_bf16 v[4:7], v[64:67], v[84:87], v[4:7]
	v_mfma_f32_16x16x32_bf16 v[8:11], v[64:67], v[88:91], v[8:11]
	v_mfma_f32_16x16x32_bf16 v[12:15], v[64:67], v[92:95], v[12:15]
	v_mfma_f32_16x16x32_bf16 v[16:19], v[64:67], v[96:99], v[16:19]
	v_mfma_f32_16x16x32_bf16 v[20:23], v[64:67], v[100:103], v[20:23]
	v_mfma_f32_16x16x32_bf16 v[24:27], v[64:67], v[104:107], v[24:27]
	v_mfma_f32_16x16x32_bf16 v[28:31], v[64:67], v[108:111], v[28:31]
	v_mfma_f32_16x16x32_bf16 v[32:35], v[68:71], v[80:83], v[32:35]
	v_mfma_f32_16x16x32_bf16 v[36:39], v[68:71], v[84:87], v[36:39]
	v_mfma_f32_16x16x32_bf16 v[40:43], v[68:71], v[88:91], v[40:43]
	v_mfma_f32_16x16x32_bf16 v[44:47], v[68:71], v[92:95], v[44:47]
	v_mfma_f32_16x16x32_bf16 v[48:51], v[68:71], v[96:99], v[48:51]
	v_mfma_f32_16x16x32_bf16 v[52:55], v[68:71], v[100:103], v[52:55]
	v_mfma_f32_16x16x32_bf16 v[56:59], v[68:71], v[104:107], v[56:59]
	v_mfma_f32_16x16x32_bf16 v[60:63], v[68:71], v[108:111], v[60:63]
	v_mfma_f32_16x16x32_bf16 v[0:3], v[72:75], v[112:115], v[0:3]
	v_mfma_f32_16x16x32_bf16 v[4:7], v[72:75], v[226:229], v[4:7]
	v_mfma_f32_16x16x32_bf16 v[8:11], v[72:75], v[230:233], v[8:11]
	v_mfma_f32_16x16x32_bf16 v[12:15], v[72:75], v[234:237], v[12:15]
	v_mfma_f32_16x16x32_bf16 v[16:19], v[72:75], v[238:241], v[16:19]
	v_mfma_f32_16x16x32_bf16 v[20:23], v[72:75], v[242:245], v[20:23]
	v_mfma_f32_16x16x32_bf16 v[24:27], v[72:75], v[246:249], v[24:27]
	v_mfma_f32_16x16x32_bf16 v[28:31], v[72:75], v[250:253], v[28:31]
	v_mfma_f32_16x16x32_bf16 v[32:35], v[76:79], v[112:115], v[32:35]
	v_mfma_f32_16x16x32_bf16 v[36:39], v[76:79], v[226:229], v[36:39]
	v_mfma_f32_16x16x32_bf16 v[40:43], v[76:79], v[230:233], v[40:43]
	v_mfma_f32_16x16x32_bf16 v[44:47], v[76:79], v[234:237], v[44:47]
	v_mfma_f32_16x16x32_bf16 v[48:51], v[76:79], v[238:241], v[48:51]
	v_mfma_f32_16x16x32_bf16 v[52:55], v[76:79], v[242:245], v[52:55]
	v_mfma_f32_16x16x32_bf16 v[56:59], v[76:79], v[246:249], v[56:59]
	v_mfma_f32_16x16x32_bf16 v[60:63], v[76:79], v[250:253], v[60:63]
	s_setprio 0
	s_nop 7
	s_nop 7
	v_and_b32_e32 v66, 63, v199
	v_lshrrev_b32_e32 v67, 6, v199
	v_lshlrev_b32_e32 v67, 14, v67
	v_lshl_add_u32 v64, v66, 4, v67
	v_and_b32_e32 v65, 15, v66
	v_lshl_add_u32 v65, v65, 4, v67
	v_bfe_u32 v67, v66, 4, 1
	v_lshl_add_u32 v65, v67, 10, v65
	v_bfe_u32 v67, v66, 5, 1
	v_lshl_add_u32 v65, v67, 8, v65
	ds_write_b128 v64, v[0:3]
	ds_write_b128 v64, v[4:7] offset:1024
	ds_write_b128 v64, v[8:11] offset:2048
	ds_write_b128 v64, v[12:15] offset:3072
	ds_write_b128 v64, v[16:19] offset:4096
	ds_write_b128 v64, v[20:23] offset:5120
	ds_write_b128 v64, v[24:27] offset:6144
	ds_write_b128 v64, v[28:31] offset:7168
	ds_write_b128 v64, v[32:35] offset:8192
	ds_write_b128 v64, v[36:39] offset:9216
	ds_write_b128 v64, v[40:43] offset:10240
	ds_write_b128 v64, v[44:47] offset:11264
	ds_write_b128 v64, v[48:51] offset:12288
	ds_write_b128 v64, v[52:55] offset:13312
	ds_write_b128 v64, v[56:59] offset:14336
	ds_write_b128 v64, v[60:63] offset:15360
	s_waitcnt lgkmcnt(0)
	ds_read_b128 v[48:51], v65
	ds_read_b128 v[52:55], v65 offset:512
	ds_read_b128 v[56:59], v65 offset:8192
	ds_read_b128 v[60:63], v65 offset:8704
	ds_read_b128 v[32:35], v65 offset:2048
	ds_read_b128 v[36:39], v65 offset:2560
	ds_read_b128 v[40:43], v65 offset:10240
	ds_read_b128 v[44:47], v65 offset:10752
	ds_read_b128 v[16:19], v65 offset:4096
	ds_read_b128 v[20:23], v65 offset:4608
	ds_read_b128 v[24:27], v65 offset:12288
	ds_read_b128 v[28:31], v65 offset:12800
	ds_read_b128 v[0:3], v65 offset:6144
	ds_read_b128 v[4:7], v65 offset:6656
	ds_read_b128 v[8:11], v65 offset:14336
	ds_read_b128 v[12:15], v65 offset:14848
	s_waitcnt lgkmcnt(0)
	s_barrier
	s_branch .LBB0_832

.LBB0_1046:
	s_ashr_i32 s6, s3, 31
	s_lshr_b32 s6, s6, 26
	s_add_i32 s6, s3, s6
	s_ashr_i32 s58, s6, 6
	s_andn2_b32 s6, s6, 63
	s_sub_i32 s6, s3, s6
	s_ashr_i32 s59, s6, 31
	s_lshr_b32 s59, s59, 29
	s_add_i32 s59, s6, s59
	s_ashr_i32 s64, s59, 3
	s_and_b32 s59, s59, -8
	s_lshl_b32 s58, s58, 3
	s_sub_i32 s6, s6, s59
	s_add_i32 s6, s6, s58
	s_lshl_b32 s66, s6, 7
	s_ashr_i32 s67, s66, 31
	s_lshl_b32 s68, s64, 7
	s_lshl_b64 s[58:59], s[66:67], 11
	s_ashr_i32 s69, s68, 31
	s_lshl_b32 s38, s66, 11
	s_add_u32 s18, s14, s38
	s_addc_u32 s19, s15, 0
	s_add_u32 s18, s18, 0xb79f000
	s_addc_u32 s19, s19, 0
	s_add_u32 s20, s18, 0x10000
	s_addc_u32 s21, s19, 0
	s_add_u32 s22, s20, 0x10000
	s_addc_u32 s23, s21, 0
	s_add_u32 s24, s22, 0x10000
	s_addc_u32 s25, s23, 0
	s_lshl_b32 s38, s68, 11
	s_add_u32 s26, s14, s38
	s_addc_u32 s27, s15, 0
	s_add_u32 s26, s26, 0xba0000
	s_addc_u32 s27, s27, 0
	s_add_u32 s28, s26, 0x10000
	s_addc_u32 s29, s27, 0
	s_add_u32 s30, s28, 0x10000
	s_addc_u32 s31, s29, 0
	s_add_u32 s34, s30, 0x10000
	s_addc_u32 s35, s31, 0
	v_and_b32_e32 v70, 15, v199
	v_bfe_u32 v71, v199, 4, 2
	v_lshrrev_b32_e32 v72, 1, v70
	v_xor_b32_e32 v71, v71, v72
	v_lshlrev_b32_e32 v71, 4, v71
	v_lshl_or_b32 v71, v70, 7, v71
	v_lshrrev_b32_e32 v72, 6, v199
	v_lshl_add_u32 v198, v72, 12, v71
	v_xor_b32_e32 v238, 64, v198
	v_add_u32_e32 v239, 0x4000, v71
	v_xor_b32_e32 v240, 64, v239
	v_readfirstlane_b32 s36, v140
	v_mov_b32_e32 v254, v64
	s_mov_b32 m0, s36
	s_nop 0
	global_load_lds_dwordx4 v254, s[18:19]
	s_add_u32 m0, m0, 0x1000
	s_nop 0
	global_load_lds_dwordx4 v254, s[20:21]
	s_add_u32 m0, m0, 0x1000
	s_nop 0
	global_load_lds_dwordx4 v254, s[22:23]
	s_add_u32 m0, m0, 0x1000
	s_nop 0
	global_load_lds_dwordx4 v254, s[24:25]
	s_add_u32 m0, m0, 0x1000
	s_nop 0
	global_load_lds_dwordx4 v254, s[26:27]
	s_add_u32 m0, m0, 0x1000
	s_nop 0
	global_load_lds_dwordx4 v254, s[28:29]
	s_add_u32 m0, m0, 0x1000
	s_nop 0
	global_load_lds_dwordx4 v254, s[30:31]
	s_add_u32 m0, m0, 0x1000
	s_nop 0
	global_load_lds_dwordx4 v254, s[34:35]
	v_add_u32_e32 v254, 0x80, v254
	s_add_u32 m0, s36, 0x8000
	s_nop 0
	global_load_lds_dwordx4 v254, s[18:19]
	s_add_u32 m0, m0, 0x1000
	s_nop 0
	global_load_lds_dwordx4 v254, s[20:21]
	s_add_u32 m0, m0, 0x1000
	s_nop 0
	global_load_lds_dwordx4 v254, s[22:23]
	s_add_u32 m0, m0, 0x1000
	s_nop 0
	global_load_lds_dwordx4 v254, s[24:25]
	s_add_u32 m0, m0, 0x1000
	s_nop 0
	global_load_lds_dwordx4 v254, s[26:27]
	s_add_u32 m0, m0, 0x1000
	s_nop 0
	global_load_lds_dwordx4 v254, s[28:29]
	s_add_u32 m0, m0, 0x1000
	s_nop 0
	global_load_lds_dwordx4 v254, s[30:31]
	s_add_u32 m0, m0, 0x1000
	s_nop 0
	global_load_lds_dwordx4 v254, s[34:35]
	v_add_u32_e32 v254, 0x80, v254
	v_mov_b32_e32 v48, 0
	v_mov_b32_e32 v49, 0
	v_mov_b32_e32 v50, 0
	v_mov_b32_e32 v51, 0
	v_mov_b32_e32 v52, 0
	v_mov_b32_e32 v53, 0
	v_mov_b32_e32 v54, 0
	v_mov_b32_e32 v55, 0
	v_mov_b32_e32 v56, 0
	v_mov_b32_e32 v57, 0
	v_mov_b32_e32 v58, 0
	v_mov_b32_e32 v59, 0
	v_mov_b32_e32 v60, 0
	v_mov_b32_e32 v61, 0
	v_mov_b32_e32 v62, 0
	v_mov_b32_e32 v63, 0
	v_mov_b32_e32 v32, 0
	v_mov_b32_e32 v33, 0
	v_mov_b32_e32 v34, 0
	v_mov_b32_e32 v35, 0
	v_mov_b32_e32 v36, 0
	v_mov_b32_e32 v37, 0
	v_mov_b32_e32 v38, 0
	v_mov_b32_e32 v39, 0
	v_mov_b32_e32 v40, 0
	v_mov_b32_e32 v41, 0
	v_mov_b32_e32 v42, 0
	v_mov_b32_e32 v43, 0
	v_mov_b32_e32 v44, 0
	v_mov_b32_e32 v45, 0
	v_mov_b32_e32 v46, 0
	v_mov_b32_e32 v47, 0
	v_mov_b32_e32 v16, 0
	v_mov_b32_e32 v17, 0
	v_mov_b32_e32 v18, 0
	v_mov_b32_e32 v19, 0
	v_mov_b32_e32 v20, 0
	v_mov_b32_e32 v21, 0
	v_mov_b32_e32 v22, 0
	v_mov_b32_e32 v23, 0
	v_mov_b32_e32 v24, 0
	v_mov_b32_e32 v25, 0
	v_mov_b32_e32 v26, 0
	v_mov_b32_e32 v27, 0
	v_mov_b32_e32 v28, 0
	v_mov_b32_e32 v29, 0
	v_mov_b32_e32 v30, 0
	v_mov_b32_e32 v31, 0
	v_mov_b32_e32 v0, 0
	v_mov_b32_e32 v1, 0
	v_mov_b32_e32 v2, 0
	v_mov_b32_e32 v3, 0
	v_mov_b32_e32 v4, 0
	v_mov_b32_e32 v5, 0
	v_mov_b32_e32 v6, 0
	v_mov_b32_e32 v7, 0
	v_mov_b32_e32 v8, 0
	v_mov_b32_e32 v9, 0
	v_mov_b32_e32 v10, 0
	v_mov_b32_e32 v11, 0
	v_mov_b32_e32 v12, 0
	v_mov_b32_e32 v13, 0
	v_mov_b32_e32 v14, 0
	v_mov_b32_e32 v15, 0
	s_mov_b32 s37, 7
.Lgk_loop_p11:
	s_waitcnt vmcnt(8)
	s_barrier
	ds_read_b128 v[70:73], v198
	ds_read_b128 v[74:77], v198 offset:2048
	ds_read_b128 v[86:89], v239
	ds_read_b128 v[90:93], v239 offset:2048
	ds_read_b128 v[94:97], v239 offset:4096
	ds_read_b128 v[98:101], v239 offset:6144
	ds_read_b128 v[102:105], v239 offset:8192
	ds_read_b128 v[106:109], v239 offset:10240
	ds_read_b128 v[110:113], v239 offset:12288
	ds_read_b128 v[202:205], v239 offset:14336
	ds_read_b128 v[78:81], v238
	ds_read_b128 v[82:85], v238 offset:2048
	ds_read_b128 v[206:209], v240
	ds_read_b128 v[210:213], v240 offset:2048
	ds_read_b128 v[214:217], v240 offset:4096
	ds_read_b128 v[218:221], v240 offset:6144
	ds_read_b128 v[222:225], v240 offset:8192
	ds_read_b128 v[226:229], v240 offset:10240
	ds_read_b128 v[230:233], v240 offset:12288
	ds_read_b128 v[234:237], v240 offset:14336
	s_waitcnt lgkmcnt(0)
	s_barrier
	s_mov_b32 m0, s36
	s_setprio 1
	v_mfma_f32_16x16x32_bf16 v[0:3], v[70:73], v[86:89], v[0:3]
	v_mfma_f32_16x16x32_bf16 v[4:7], v[70:73], v[90:93], v[4:7]
	v_mfma_f32_16x16x32_bf16 v[8:11], v[70:73], v[94:97], v[8:11]
	v_mfma_f32_16x16x32_bf16 v[12:15], v[70:73], v[98:101], v[12:15]
	global_load_lds_dwordx4 v254, s[18:19]
	s_add_u32 m0, m0, 0x1000
	v_mfma_f32_16x16x32_bf16 v[16:19], v[70:73], v[102:105], v[16:19]
	v_mfma_f32_16x16x32_bf16 v[20:23], v[70:73], v[106:109], v[20:23]
	v_mfma_f32_16x16x32_bf16 v[24:27], v[70:73], v[110:113], v[24:27]
	v_mfma_f32_16x16x32_bf16 v[28:31], v[70:73], v[202:205], v[28:31]
	global_load_lds_dwordx4 v254, s[20:21]
	s_add_u32 m0, m0, 0x1000
	v_mfma_f32_16x16x32_bf16 v[32:35], v[74:77], v[86:89], v[32:35]
	v_mfma_f32_16x16x32_bf16 v[36:39], v[74:77], v[90:93], v[36:39]
	v_mfma_f32_16x16x32_bf16 v[40:43], v[74:77], v[94:97], v[40:43]
	v_mfma_f32_16x16x32_bf16 v[44:47], v[74:77], v[98:101], v[44:47]
	global_load_lds_dwordx4 v254, s[22:23]
	s_add_u32 m0, m0, 0x1000
	v_mfma_f32_16x16x32_bf16 v[48:51], v[74:77], v[102:105], v[48:51]
	v_mfma_f32_16x16x32_bf16 v[52:55], v[74:77], v[106:109], v[52:55]
	v_mfma_f32_16x16x32_bf16 v[56:59], v[74:77], v[110:113], v[56:59]
	v_mfma_f32_16x16x32_bf16 v[60:63], v[74:77], v[202:205], v[60:63]
	global_load_lds_dwordx4 v254, s[24:25]
	s_add_u32 m0, m0, 0x1000
	v_mfma_f32_16x16x32_bf16 v[0:3], v[78:81], v[206:209], v[0:3]
	v_mfma_f32_16x16x32_bf16 v[4:7], v[78:81], v[210:213], v[4:7]
	v_mfma_f32_16x16x32_bf16 v[8:11], v[78:81], v[214:217], v[8:11]
	v_mfma_f32_16x16x32_bf16 v[12:15], v[78:81], v[218:221], v[12:15]
	global_load_lds_dwordx4 v254, s[26:27]
	s_add_u32 m0, m0, 0x1000
	v_mfma_f32_16x16x32_bf16 v[16:19], v[78:81], v[222:225], v[16:19]
	v_mfma_f32_16x16x32_bf16 v[20:23], v[78:81], v[226:229], v[20:23]
	v_mfma_f32_16x16x32_bf16 v[24:27], v[78:81], v[230:233], v[24:27]
	v_mfma_f32_16x16x32_bf16 v[28:31], v[78:81], v[234:237], v[28:31]
	global_load_lds_dwordx4 v254, s[28:29]
	s_add_u32 m0, m0, 0x1000
	v_mfma_f32_16x16x32_bf16 v[32:35], v[82:85], v[206:209], v[32:35]
	v_mfma_f32_16x16x32_bf16 v[36:39], v[82:85], v[210:213], v[36:39]
	v_mfma_f32_16x16x32_bf16 v[40:43], v[82:85], v[214:217], v[40:43]
	v_mfma_f32_16x16x32_bf16 v[44:47], v[82:85], v[218:221], v[44:47]
	global_load_lds_dwordx4 v254, s[30:31]
	s_add_u32 m0, m0, 0x1000
	v_mfma_f32_16x16x32_bf16 v[48:51], v[82:85], v[222:225], v[48:51]
	v_mfma_f32_16x16x32_bf16 v[52:55], v[82:85], v[226:229], v[52:55]
	v_mfma_f32_16x16x32_bf16 v[56:59], v[82:85], v[230:233], v[56:59]
	v_mfma_f32_16x16x32_bf16 v[60:63], v[82:85], v[234:237], v[60:63]
	global_load_lds_dwordx4 v254, s[34:35]
	s_setprio 0
	v_add_u32_e32 v254, 0x80, v254
	s_waitcnt vmcnt(8)
	s_barrier
	ds_read_b128 v[70:73], v198 offset:32768
	ds_read_b128 v[74:77], v198 offset:34816
	ds_read_b128 v[86:89], v239 offset:32768
	ds_read_b128 v[90:93], v239 offset:34816
	ds_read_b128 v[94:97], v239 offset:36864
	ds_read_b128 v[98:101], v239 offset:38912
	ds_read_b128 v[102:105], v239 offset:40960
	ds_read_b128 v[106:109], v239 offset:43008
	ds_read_b128 v[110:113], v239 offset:45056
	ds_read_b128 v[202:205], v239 offset:47104
	ds_read_b128 v[78:81], v238 offset:32768
	ds_read_b128 v[82:85], v238 offset:34816
	ds_read_b128 v[206:209], v240 offset:32768
	ds_read_b128 v[210:213], v240 offset:34816
	ds_read_b128 v[214:217], v240 offset:36864
	ds_read_b128 v[218:221], v240 offset:38912
	ds_read_b128 v[222:225], v240 offset:40960
	ds_read_b128 v[226:229], v240 offset:43008
	ds_read_b128 v[230:233], v240 offset:45056
	ds_read_b128 v[234:237], v240 offset:47104
	s_waitcnt lgkmcnt(0)
	s_barrier
	s_add_u32 m0, s36, 0x8000
	s_setprio 1
	v_mfma_f32_16x16x32_bf16 v[0:3], v[70:73], v[86:89], v[0:3]
	v_mfma_f32_16x16x32_bf16 v[4:7], v[70:73], v[90:93], v[4:7]
	v_mfma_f32_16x16x32_bf16 v[8:11], v[70:73], v[94:97], v[8:11]
	v_mfma_f32_16x16x32_bf16 v[12:15], v[70:73], v[98:101], v[12:15]
	global_load_lds_dwordx4 v254, s[18:19]
	s_add_u32 m0, m0, 0x1000
	v_mfma_f32_16x16x32_bf16 v[16:19], v[70:73], v[102:105], v[16:19]
	v_mfma_f32_16x16x32_bf16 v[20:23], v[70:73], v[106:109], v[20:23]
	v_mfma_f32_16x16x32_bf16 v[24:27], v[70:73], v[110:113], v[24:27]
	v_mfma_f32_16x16x32_bf16 v[28:31], v[70:73], v[202:205], v[28:31]
	global_load_lds_dwordx4 v254, s[20:21]
	s_add_u32 m0, m0, 0x1000
	v_mfma_f32_16x16x32_bf16 v[32:35], v[74:77], v[86:89], v[32:35]
	v_mfma_f32_16x16x32_bf16 v[36:39], v[74:77], v[90:93], v[36:39]
	v_mfma_f32_16x16x32_bf16 v[40:43], v[74:77], v[94:97], v[40:43]
	v_mfma_f32_16x16x32_bf16 v[44:47], v[74:77], v[98:101], v[44:47]
	global_load_lds_dwordx4 v254, s[22:23]
	s_add_u32 m0, m0, 0x1000
	v_mfma_f32_16x16x32_bf16 v[48:51], v[74:77], v[102:105], v[48:51]
	v_mfma_f32_16x16x32_bf16 v[52:55], v[74:77], v[106:109], v[52:55]
	v_mfma_f32_16x16x32_bf16 v[56:59], v[74:77], v[110:113], v[56:59]
	v_mfma_f32_16x16x32_bf16 v[60:63], v[74:77], v[202:205], v[60:63]
	global_load_lds_dwordx4 v254, s[24:25]
	s_add_u32 m0, m0, 0x1000
	v_mfma_f32_16x16x32_bf16 v[0:3], v[78:81], v[206:209], v[0:3]
	v_mfma_f32_16x16x32_bf16 v[4:7], v[78:81], v[210:213], v[4:7]
	v_mfma_f32_16x16x32_bf16 v[8:11], v[78:81], v[214:217], v[8:11]
	v_mfma_f32_16x16x32_bf16 v[12:15], v[78:81], v[218:221], v[12:15]
	global_load_lds_dwordx4 v254, s[26:27]
	s_add_u32 m0, m0, 0x1000
	v_mfma_f32_16x16x32_bf16 v[16:19], v[78:81], v[222:225], v[16:19]
	v_mfma_f32_16x16x32_bf16 v[20:23], v[78:81], v[226:229], v[20:23]
	v_mfma_f32_16x16x32_bf16 v[24:27], v[78:81], v[230:233], v[24:27]
	v_mfma_f32_16x16x32_bf16 v[28:31], v[78:81], v[234:237], v[28:31]
	global_load_lds_dwordx4 v254, s[28:29]
	s_add_u32 m0, m0, 0x1000
	v_mfma_f32_16x16x32_bf16 v[32:35], v[82:85], v[206:209], v[32:35]
	v_mfma_f32_16x16x32_bf16 v[36:39], v[82:85], v[210:213], v[36:39]
	v_mfma_f32_16x16x32_bf16 v[40:43], v[82:85], v[214:217], v[40:43]
	v_mfma_f32_16x16x32_bf16 v[44:47], v[82:85], v[218:221], v[44:47]
	global_load_lds_dwordx4 v254, s[30:31]
	s_add_u32 m0, m0, 0x1000
	v_mfma_f32_16x16x32_bf16 v[48:51], v[82:85], v[222:225], v[48:51]
	v_mfma_f32_16x16x32_bf16 v[52:55], v[82:85], v[226:229], v[52:55]
	v_mfma_f32_16x16x32_bf16 v[56:59], v[82:85], v[230:233], v[56:59]
	v_mfma_f32_16x16x32_bf16 v[60:63], v[82:85], v[234:237], v[60:63]
	global_load_lds_dwordx4 v254, s[34:35]
	s_setprio 0
	v_add_u32_e32 v254, 0x80, v254
	s_sub_u32 s37, s37, 1
	s_cmp_lg_u32 s37, 0
	s_cbranch_scc1 .Lgk_loop_p11
	s_waitcnt vmcnt(8)
	s_barrier
	ds_read_b128 v[70:73], v198
	ds_read_b128 v[74:77], v198 offset:2048
	ds_read_b128 v[86:89], v239
	ds_read_b128 v[90:93], v239 offset:2048
	ds_read_b128 v[94:97], v239 offset:4096
	ds_read_b128 v[98:101], v239 offset:6144
	ds_read_b128 v[102:105], v239 offset:8192
	ds_read_b128 v[106:109], v239 offset:10240
	ds_read_b128 v[110:113], v239 offset:12288
	ds_read_b128 v[202:205], v239 offset:14336
	ds_read_b128 v[78:81], v238
	ds_read_b128 v[82:85], v238 offset:2048
	ds_read_b128 v[206:209], v240
	ds_read_b128 v[210:213], v240 offset:2048
	ds_read_b128 v[214:217], v240 offset:4096
	ds_read_b128 v[218:221], v240 offset:6144
	ds_read_b128 v[222:225], v240 offset:8192
	ds_read_b128 v[226:229], v240 offset:10240
	ds_read_b128 v[230:233], v240 offset:12288
	ds_read_b128 v[234:237], v240 offset:14336
	s_waitcnt lgkmcnt(0)
	s_barrier
	s_setprio 1
	v_mfma_f32_16x16x32_bf16 v[0:3], v[70:73], v[86:89], v[0:3]
	v_mfma_f32_16x16x32_bf16 v[4:7], v[70:73], v[90:93], v[4:7]
	v_mfma_f32_16x16x32_bf16 v[8:11], v[70:73], v[94:97], v[8:11]
	v_mfma_f32_16x16x32_bf16 v[12:15], v[70:73], v[98:101], v[12:15]
	v_mfma_f32_16x16x32_bf16 v[16:19], v[70:73], v[102:105], v[16:19]
	v_mfma_f32_16x16x32_bf16 v[20:23], v[70:73], v[106:109], v[20:23]
	v_mfma_f32_16x16x32_bf16 v[24:27], v[70:73], v[110:113], v[24:27]
	v_mfma_f32_16x16x32_bf16 v[28:31], v[70:73], v[202:205], v[28:31]
	v_mfma_f32_16x16x32_bf16 v[32:35], v[74:77], v[86:89], v[32:35]
	v_mfma_f32_16x16x32_bf16 v[36:39], v[74:77], v[90:93], v[36:39]
	v_mfma_f32_16x16x32_bf16 v[40:43], v[74:77], v[94:97], v[40:43]
	v_mfma_f32_16x16x32_bf16 v[44:47], v[74:77], v[98:101], v[44:47]
	v_mfma_f32_16x16x32_bf16 v[48:51], v[74:77], v[102:105], v[48:51]
	v_mfma_f32_16x16x32_bf16 v[52:55], v[74:77], v[106:109], v[52:55]
	v_mfma_f32_16x16x32_bf16 v[56:59], v[74:77], v[110:113], v[56:59]
	v_mfma_f32_16x16x32_bf16 v[60:63], v[74:77], v[202:205], v[60:63]
	v_mfma_f32_16x16x32_bf16 v[0:3], v[78:81], v[206:209], v[0:3]
	v_mfma_f32_16x16x32_bf16 v[4:7], v[78:81], v[210:213], v[4:7]
	v_mfma_f32_16x16x32_bf16 v[8:11], v[78:81], v[214:217], v[8:11]
	v_mfma_f32_16x16x32_bf16 v[12:15], v[78:81], v[218:221], v[12:15]
	v_mfma_f32_16x16x32_bf16 v[16:19], v[78:81], v[222:225], v[16:19]
	v_mfma_f32_16x16x32_bf16 v[20:23], v[78:81], v[226:229], v[20:23]
	v_mfma_f32_16x16x32_bf16 v[24:27], v[78:81], v[230:233], v[24:27]
	v_mfma_f32_16x16x32_bf16 v[28:31], v[78:81], v[234:237], v[28:31]
	v_mfma_f32_16x16x32_bf16 v[32:35], v[82:85], v[206:209], v[32:35]
	v_mfma_f32_16x16x32_bf16 v[36:39], v[82:85], v[210:213], v[36:39]
	v_mfma_f32_16x16x32_bf16 v[40:43], v[82:85], v[214:217], v[40:43]
	v_mfma_f32_16x16x32_bf16 v[44:47], v[82:85], v[218:221], v[44:47]
	v_mfma_f32_16x16x32_bf16 v[48:51], v[82:85], v[222:225], v[48:51]
	v_mfma_f32_16x16x32_bf16 v[52:55], v[82:85], v[226:229], v[52:55]
	v_mfma_f32_16x16x32_bf16 v[56:59], v[82:85], v[230:233], v[56:59]
	v_mfma_f32_16x16x32_bf16 v[60:63], v[82:85], v[234:237], v[60:63]
	s_setprio 0
	s_waitcnt vmcnt(0)
	s_barrier
	ds_read_b128 v[70:73], v198 offset:32768
	ds_read_b128 v[74:77], v198 offset:34816
	ds_read_b128 v[86:89], v239 offset:32768
	ds_read_b128 v[90:93], v239 offset:34816
	ds_read_b128 v[94:97], v239 offset:36864
	ds_read_b128 v[98:101], v239 offset:38912
	ds_read_b128 v[102:105], v239 offset:40960
	ds_read_b128 v[106:109], v239 offset:43008
	ds_read_b128 v[110:113], v239 offset:45056
	ds_read_b128 v[202:205], v239 offset:47104
	ds_read_b128 v[78:81], v238 offset:32768
	ds_read_b128 v[82:85], v238 offset:34816
	ds_read_b128 v[206:209], v240 offset:32768
	ds_read_b128 v[210:213], v240 offset:34816
	ds_read_b128 v[214:217], v240 offset:36864
	ds_read_b128 v[218:221], v240 offset:38912
	ds_read_b128 v[222:225], v240 offset:40960
	ds_read_b128 v[226:229], v240 offset:43008
	ds_read_b128 v[230:233], v240 offset:45056
	ds_read_b128 v[234:237], v240 offset:47104
	s_waitcnt lgkmcnt(0)
	s_barrier
	s_setprio 1
	v_mfma_f32_16x16x32_bf16 v[0:3], v[70:73], v[86:89], v[0:3]
	v_mfma_f32_16x16x32_bf16 v[4:7], v[70:73], v[90:93], v[4:7]
	v_mfma_f32_16x16x32_bf16 v[8:11], v[70:73], v[94:97], v[8:11]
	v_mfma_f32_16x16x32_bf16 v[12:15], v[70:73], v[98:101], v[12:15]
	v_mfma_f32_16x16x32_bf16 v[16:19], v[70:73], v[102:105], v[16:19]
	v_mfma_f32_16x16x32_bf16 v[20:23], v[70:73], v[106:109], v[20:23]
	v_mfma_f32_16x16x32_bf16 v[24:27], v[70:73], v[110:113], v[24:27]
	v_mfma_f32_16x16x32_bf16 v[28:31], v[70:73], v[202:205], v[28:31]
	v_mfma_f32_16x16x32_bf16 v[32:35], v[74:77], v[86:89], v[32:35]
	v_mfma_f32_16x16x32_bf16 v[36:39], v[74:77], v[90:93], v[36:39]
	v_mfma_f32_16x16x32_bf16 v[40:43], v[74:77], v[94:97], v[40:43]
	v_mfma_f32_16x16x32_bf16 v[44:47], v[74:77], v[98:101], v[44:47]
	v_mfma_f32_16x16x32_bf16 v[48:51], v[74:77], v[102:105], v[48:51]
	v_mfma_f32_16x16x32_bf16 v[52:55], v[74:77], v[106:109], v[52:55]
	v_mfma_f32_16x16x32_bf16 v[56:59], v[74:77], v[110:113], v[56:59]
	v_mfma_f32_16x16x32_bf16 v[60:63], v[74:77], v[202:205], v[60:63]
	v_mfma_f32_16x16x32_bf16 v[0:3], v[78:81], v[206:209], v[0:3]
	v_mfma_f32_16x16x32_bf16 v[4:7], v[78:81], v[210:213], v[4:7]
	v_mfma_f32_16x16x32_bf16 v[8:11], v[78:81], v[214:217], v[8:11]
	v_mfma_f32_16x16x32_bf16 v[12:15], v[78:81], v[218:221], v[12:15]
	v_mfma_f32_16x16x32_bf16 v[16:19], v[78:81], v[222:225], v[16:19]
	v_mfma_f32_16x16x32_bf16 v[20:23], v[78:81], v[226:229], v[20:23]
	v_mfma_f32_16x16x32_bf16 v[24:27], v[78:81], v[230:233], v[24:27]
	v_mfma_f32_16x16x32_bf16 v[28:31], v[78:81], v[234:237], v[28:31]
	v_mfma_f32_16x16x32_bf16 v[32:35], v[82:85], v[206:209], v[32:35]
	v_mfma_f32_16x16x32_bf16 v[36:39], v[82:85], v[210:213], v[36:39]
	v_mfma_f32_16x16x32_bf16 v[40:43], v[82:85], v[214:217], v[40:43]
	v_mfma_f32_16x16x32_bf16 v[44:47], v[82:85], v[218:221], v[44:47]
	v_mfma_f32_16x16x32_bf16 v[48:51], v[82:85], v[222:225], v[48:51]
	v_mfma_f32_16x16x32_bf16 v[52:55], v[82:85], v[226:229], v[52:55]
	v_mfma_f32_16x16x32_bf16 v[56:59], v[82:85], v[230:233], v[56:59]
	v_mfma_f32_16x16x32_bf16 v[60:63], v[82:85], v[234:237], v[60:63]
	s_setprio 0
	s_nop 7
	s_nop 7
	v_and_b32_e32 v72, 63, v199
	v_lshrrev_b32_e32 v73, 6, v199
	v_lshlrev_b32_e32 v73, 14, v73
	v_lshl_add_u32 v70, v72, 4, v73
	v_and_b32_e32 v71, 15, v72
	v_lshl_add_u32 v71, v71, 4, v73
	v_bfe_u32 v73, v72, 4, 1
	v_lshl_add_u32 v71, v73, 10, v71
	v_bfe_u32 v73, v72, 5, 1
	v_lshl_add_u32 v71, v73, 8, v71
	ds_write_b128 v70, v[0:3]
	ds_write_b128 v70, v[4:7] offset:1024
	ds_write_b128 v70, v[8:11] offset:2048
	ds_write_b128 v70, v[12:15] offset:3072
	ds_write_b128 v70, v[16:19] offset:4096
	ds_write_b128 v70, v[20:23] offset:5120
	ds_write_b128 v70, v[24:27] offset:6144
	ds_write_b128 v70, v[28:31] offset:7168
	ds_write_b128 v70, v[32:35] offset:8192
	ds_write_b128 v70, v[36:39] offset:9216
	ds_write_b128 v70, v[40:43] offset:10240
	ds_write_b128 v70, v[44:47] offset:11264
	ds_write_b128 v70, v[48:51] offset:12288
	ds_write_b128 v70, v[52:55] offset:13312
	ds_write_b128 v70, v[56:59] offset:14336
	ds_write_b128 v70, v[60:63] offset:15360
	s_waitcnt lgkmcnt(0)
	ds_read_b128 v[48:51], v71
	ds_read_b128 v[52:55], v71 offset:512
	ds_read_b128 v[56:59], v71 offset:8192
	ds_read_b128 v[60:63], v71 offset:8704
	ds_read_b128 v[32:35], v71 offset:2048
	ds_read_b128 v[36:39], v71 offset:2560
	ds_read_b128 v[40:43], v71 offset:10240
	ds_read_b128 v[44:47], v71 offset:10752
	ds_read_b128 v[16:19], v71 offset:4096
	ds_read_b128 v[20:23], v71 offset:4608
	ds_read_b128 v[24:27], v71 offset:12288
	ds_read_b128 v[28:31], v71 offset:12800
	ds_read_b128 v[0:3], v71 offset:6144
	ds_read_b128 v[4:7], v71 offset:6656
	ds_read_b128 v[8:11], v71 offset:14336
	ds_read_b128 v[12:15], v71 offset:14848
	s_waitcnt lgkmcnt(0)
	s_barrier
	s_branch .LBB0_1050

.Lmap_done_1:
	s_lshl_b32 s60, s4, 7
	s_lshl_b32 s58, s76, 7
	s_ashr_i32 s61, s60, 31
	s_ashr_i32 s59, s58, 31
	s_lshl_b64 s[62:63], s[60:61], 11
	s_lshl_b64 s[64:65], s[58:59], 11
	s_lshl_b32 s38, s60, 11
	s_add_u32 s18, s14, s38
	s_addc_u32 s19, s15, 0
	s_add_u32 s18, s18, 0x679f000
	s_addc_u32 s19, s19, 0
	s_add_u32 s20, s18, 0x10000
	s_addc_u32 s21, s19, 0
	s_add_u32 s22, s20, 0x10000
	s_addc_u32 s23, s21, 0
	s_add_u32 s24, s22, 0x10000
	s_addc_u32 s25, s23, 0
	s_lshl_b32 s38, s58, 11
	s_add_u32 s26, s14, s38
	s_addc_u32 s27, s15, 0
	s_add_u32 s26, s26, 0x24a0000
	s_addc_u32 s27, s27, 0
	s_add_u32 s28, s26, 0x10000
	s_addc_u32 s29, s27, 0
	s_add_u32 s30, s28, 0x10000
	s_addc_u32 s31, s29, 0
	s_add_u32 s34, s30, 0x10000
	s_addc_u32 s35, s31, 0
	v_and_b32_e32 v64, 15, v199
	v_bfe_u32 v65, v199, 4, 2
	v_lshrrev_b32_e32 v66, 1, v64
	v_xor_b32_e32 v65, v65, v66
	v_lshlrev_b32_e32 v65, 4, v65
	v_lshl_or_b32 v65, v64, 7, v65
	v_lshrrev_b32_e32 v66, 6, v199
	v_lshl_add_u32 v217, v66, 12, v65
	v_xor_b32_e32 v255, 64, v217
	v_add_u32_e32 v78, 0x4000, v65
	v_xor_b32_e32 v79, 64, v78
	v_readfirstlane_b32 s36, v94
	v_mov_b32_e32 v254, v76
	s_mov_b32 m0, s36
	s_nop 0
	global_load_lds_dwordx4 v254, s[18:19]
	s_add_u32 m0, m0, 0x1000
	s_nop 0
	global_load_lds_dwordx4 v254, s[20:21]
	s_add_u32 m0, m0, 0x1000
	s_nop 0
	global_load_lds_dwordx4 v254, s[22:23]
	s_add_u32 m0, m0, 0x1000
	s_nop 0
	global_load_lds_dwordx4 v254, s[24:25]
	s_add_u32 m0, m0, 0x1000
	s_nop 0
	global_load_lds_dwordx4 v254, s[26:27]
	s_add_u32 m0, m0, 0x1000
	s_nop 0
	global_load_lds_dwordx4 v254, s[28:29]
	s_add_u32 m0, m0, 0x1000
	s_nop 0
	global_load_lds_dwordx4 v254, s[30:31]
	s_add_u32 m0, m0, 0x1000
	s_nop 0
	global_load_lds_dwordx4 v254, s[34:35]
	v_add_u32_e32 v254, 0x80, v254
	s_add_u32 m0, s36, 0x8000
	s_nop 0
	global_load_lds_dwordx4 v254, s[18:19]
	s_add_u32 m0, m0, 0x1000
	s_nop 0
	global_load_lds_dwordx4 v254, s[20:21]
	s_add_u32 m0, m0, 0x1000
	s_nop 0
	global_load_lds_dwordx4 v254, s[22:23]
	s_add_u32 m0, m0, 0x1000
	s_nop 0
	global_load_lds_dwordx4 v254, s[24:25]
	s_add_u32 m0, m0, 0x1000
	s_nop 0
	global_load_lds_dwordx4 v254, s[26:27]
	s_add_u32 m0, m0, 0x1000
	s_nop 0
	global_load_lds_dwordx4 v254, s[28:29]
	s_add_u32 m0, m0, 0x1000
	s_nop 0
	global_load_lds_dwordx4 v254, s[30:31]
	s_add_u32 m0, m0, 0x1000
	s_nop 0
	global_load_lds_dwordx4 v254, s[34:35]
	v_add_u32_e32 v254, 0x80, v254
	v_mov_b32_e32 v48, 0
	v_mov_b32_e32 v49, 0
	v_mov_b32_e32 v50, 0
	v_mov_b32_e32 v51, 0
	v_mov_b32_e32 v52, 0
	v_mov_b32_e32 v53, 0
	v_mov_b32_e32 v54, 0
	v_mov_b32_e32 v55, 0
	v_mov_b32_e32 v56, 0
	v_mov_b32_e32 v57, 0
	v_mov_b32_e32 v58, 0
	v_mov_b32_e32 v59, 0
	v_mov_b32_e32 v60, 0
	v_mov_b32_e32 v61, 0
	v_mov_b32_e32 v62, 0
	v_mov_b32_e32 v63, 0
	v_mov_b32_e32 v32, 0
	v_mov_b32_e32 v33, 0
	v_mov_b32_e32 v34, 0
	v_mov_b32_e32 v35, 0
	v_mov_b32_e32 v36, 0
	v_mov_b32_e32 v37, 0
	v_mov_b32_e32 v38, 0
	v_mov_b32_e32 v39, 0
	v_mov_b32_e32 v40, 0
	v_mov_b32_e32 v41, 0
	v_mov_b32_e32 v42, 0
	v_mov_b32_e32 v43, 0
	v_mov_b32_e32 v44, 0
	v_mov_b32_e32 v45, 0
	v_mov_b32_e32 v46, 0
	v_mov_b32_e32 v47, 0
	v_mov_b32_e32 v16, 0
	v_mov_b32_e32 v17, 0
	v_mov_b32_e32 v18, 0
	v_mov_b32_e32 v19, 0
	v_mov_b32_e32 v20, 0
	v_mov_b32_e32 v21, 0
	v_mov_b32_e32 v22, 0
	v_mov_b32_e32 v23, 0
	v_mov_b32_e32 v24, 0
	v_mov_b32_e32 v25, 0
	v_mov_b32_e32 v26, 0
	v_mov_b32_e32 v27, 0
	v_mov_b32_e32 v28, 0
	v_mov_b32_e32 v29, 0
	v_mov_b32_e32 v30, 0
	v_mov_b32_e32 v31, 0
	v_mov_b32_e32 v0, 0
	v_mov_b32_e32 v1, 0
	v_mov_b32_e32 v2, 0
	v_mov_b32_e32 v3, 0
	v_mov_b32_e32 v4, 0
	v_mov_b32_e32 v5, 0
	v_mov_b32_e32 v6, 0
	v_mov_b32_e32 v7, 0
	v_mov_b32_e32 v8, 0
	v_mov_b32_e32 v9, 0
	v_mov_b32_e32 v10, 0
	v_mov_b32_e32 v11, 0
	v_mov_b32_e32 v12, 0
	v_mov_b32_e32 v13, 0
	v_mov_b32_e32 v14, 0
	v_mov_b32_e32 v15, 0
	s_mov_b32 s37, 7

.LBB0_1118:
	s_ashr_i32 s6, s3, 31
	s_lshr_b32 s6, s6, 26
	s_add_i32 s6, s3, s6
	s_ashr_i32 s58, s6, 6
	s_andn2_b32 s6, s6, 63
	s_sub_i32 s6, s3, s6
	s_ashr_i32 s59, s6, 31
	s_lshr_b32 s59, s59, 29
	s_add_i32 s59, s6, s59
	s_ashr_i32 s64, s59, 3
	s_and_b32 s59, s59, -8
	s_lshl_b32 s58, s58, 3
	s_sub_i32 s6, s6, s59
	s_add_i32 s6, s6, s58
	s_lshl_b32 s67, s6, 7
	s_lshl_b32 s68, s64, 7
	s_waitcnt lgkmcnt(0)
	s_mul_i32 s38, s6, 0xb0000
	s_add_u32 s18, s14, s38
	s_addc_u32 s19, s15, 0
	s_add_u32 s18, s18, 0x879f000
	s_addc_u32 s19, s19, 0
	s_add_u32 s20, s18, 0x2c000
	s_addc_u32 s21, s19, 0
	s_add_u32 s22, s20, 0x2c000
	s_addc_u32 s23, s21, 0
	s_add_u32 s24, s22, 0x2c000
	s_addc_u32 s25, s23, 0
	s_mul_i32 s38, s64, 0xb0000
	s_add_u32 s26, s14, s38
	s_addc_u32 s27, s15, 0
	s_add_u32 s26, s26, 0x4b20000
	s_addc_u32 s27, s27, 0
	s_add_u32 s28, s26, 0x2c000
	s_addc_u32 s29, s27, 0
	s_add_u32 s30, s28, 0x2c000
	s_addc_u32 s31, s29, 0
	s_add_u32 s34, s30, 0x2c000
	s_addc_u32 s35, s31, 0
	v_and_b32_e32 v70, 15, v199
	v_bfe_u32 v71, v199, 4, 2
	v_lshrrev_b32_e32 v72, 1, v70
	v_xor_b32_e32 v71, v71, v72
	v_lshlrev_b32_e32 v71, 4, v71
	v_lshl_or_b32 v71, v70, 7, v71
	v_lshrrev_b32_e32 v72, 6, v199
	v_lshl_add_u32 v238, v72, 12, v71
	v_xor_b32_e32 v239, 64, v238
	v_add_u32_e32 v240, 0x4000, v71
	v_xor_b32_e32 v241, 64, v240
	v_readfirstlane_b32 s36, v141
	v_mov_b32_e32 v254, v64
	s_mov_b32 m0, s36
	s_nop 0
	global_load_lds_dwordx4 v254, s[18:19]
	s_add_u32 m0, m0, 0x1000
	s_nop 0
	global_load_lds_dwordx4 v254, s[20:21]
	s_add_u32 m0, m0, 0x1000
	s_nop 0
	global_load_lds_dwordx4 v254, s[22:23]
	s_add_u32 m0, m0, 0x1000
	s_nop 0
	global_load_lds_dwordx4 v254, s[24:25]
	s_add_u32 m0, m0, 0x1000
	s_nop 0
	global_load_lds_dwordx4 v254, s[26:27]
	s_add_u32 m0, m0, 0x1000
	s_nop 0
	global_load_lds_dwordx4 v254, s[28:29]
	s_add_u32 m0, m0, 0x1000
	s_nop 0
	global_load_lds_dwordx4 v254, s[30:31]
	s_add_u32 m0, m0, 0x1000
	s_nop 0
	global_load_lds_dwordx4 v254, s[34:35]
	v_add_u32_e32 v254, 0x80, v254
	s_add_u32 m0, s36, 0x8000
	s_nop 0
	global_load_lds_dwordx4 v254, s[18:19]
	s_add_u32 m0, m0, 0x1000
	s_nop 0
	global_load_lds_dwordx4 v254, s[20:21]
	s_add_u32 m0, m0, 0x1000
	s_nop 0
	global_load_lds_dwordx4 v254, s[22:23]
	s_add_u32 m0, m0, 0x1000
	s_nop 0
	global_load_lds_dwordx4 v254, s[24:25]
	s_add_u32 m0, m0, 0x1000
	s_nop 0
	global_load_lds_dwordx4 v254, s[26:27]
	s_add_u32 m0, m0, 0x1000
	s_nop 0
	global_load_lds_dwordx4 v254, s[28:29]
	s_add_u32 m0, m0, 0x1000
	s_nop 0
	global_load_lds_dwordx4 v254, s[30:31]
	s_add_u32 m0, m0, 0x1000
	s_nop 0
	global_load_lds_dwordx4 v254, s[34:35]
	v_add_u32_e32 v254, 0x80, v254
	v_mov_b32_e32 v48, 0
	v_mov_b32_e32 v49, 0
	v_mov_b32_e32 v50, 0
	v_mov_b32_e32 v51, 0
	v_mov_b32_e32 v52, 0
	v_mov_b32_e32 v53, 0
	v_mov_b32_e32 v54, 0
	v_mov_b32_e32 v55, 0
	v_mov_b32_e32 v56, 0
	v_mov_b32_e32 v57, 0
	v_mov_b32_e32 v58, 0
	v_mov_b32_e32 v59, 0
	v_mov_b32_e32 v60, 0
	v_mov_b32_e32 v61, 0
	v_mov_b32_e32 v62, 0
	v_mov_b32_e32 v63, 0
	v_mov_b32_e32 v32, 0
	v_mov_b32_e32 v33, 0
	v_mov_b32_e32 v34, 0
	v_mov_b32_e32 v35, 0
	v_mov_b32_e32 v36, 0
	v_mov_b32_e32 v37, 0
	v_mov_b32_e32 v38, 0
	v_mov_b32_e32 v39, 0
	v_mov_b32_e32 v40, 0
	v_mov_b32_e32 v41, 0
	v_mov_b32_e32 v42, 0
	v_mov_b32_e32 v43, 0
	v_mov_b32_e32 v44, 0
	v_mov_b32_e32 v45, 0
	v_mov_b32_e32 v46, 0
	v_mov_b32_e32 v47, 0
	v_mov_b32_e32 v16, 0
	v_mov_b32_e32 v17, 0
	v_mov_b32_e32 v18, 0
	v_mov_b32_e32 v19, 0
	v_mov_b32_e32 v20, 0
	v_mov_b32_e32 v21, 0
	v_mov_b32_e32 v22, 0
	v_mov_b32_e32 v23, 0
	v_mov_b32_e32 v24, 0
	v_mov_b32_e32 v25, 0
	v_mov_b32_e32 v26, 0
	v_mov_b32_e32 v27, 0
	v_mov_b32_e32 v28, 0
	v_mov_b32_e32 v29, 0
	v_mov_b32_e32 v30, 0
	v_mov_b32_e32 v31, 0
	v_mov_b32_e32 v0, 0
	v_mov_b32_e32 v1, 0
	v_mov_b32_e32 v2, 0
	v_mov_b32_e32 v3, 0
	v_mov_b32_e32 v4, 0
	v_mov_b32_e32 v5, 0
	v_mov_b32_e32 v6, 0
	v_mov_b32_e32 v7, 0
	v_mov_b32_e32 v8, 0
	v_mov_b32_e32 v9, 0
	v_mov_b32_e32 v10, 0
	v_mov_b32_e32 v11, 0
	v_mov_b32_e32 v12, 0
	v_mov_b32_e32 v13, 0
	v_mov_b32_e32 v14, 0
	v_mov_b32_e32 v15, 0
	s_mov_b32 s37, 21

.LBB0_1171:
	s_mul_hi_i32 s0, s3, 0x2aaaaaab
	s_lshr_b32 s1, s0, 31
	s_ashr_i32 s0, s0, 4
	s_add_i32 s0, s0, s1
	s_mul_i32 s85, s0, 0xffffffa0
	s_add_i32 s85, s85, s3
	s_lshl_b32 s1, s0, 3
	s_ashr_i32 s0, s85, 31
	s_lshr_b32 s0, s0, 29
	s_add_i32 s0, s85, s0
	s_ashr_i32 s84, s0, 3
	s_and_b32 s0, s0, -8
	s_sub_i32 s8, s85, s0
	s_add_i32 s8, s8, s1
	s_lshl_b32 s66, s8, 7
	s_lshl_b32 s4, s84, 7
	s_ashr_i32 s67, s66, 31
	s_ashr_i32 s5, s4, 31
	s_lshl_b64 s[0:1], s[66:67], 11
	s_lshl_b64 s[68:69], s[4:5], 11
	s_lshl_b32 s48, s66, 11
	s_add_u32 s28, s14, s48
	s_addc_u32 s29, s15, 0
	s_add_u32 s28, s28, 0x679f000
	s_addc_u32 s29, s29, 0
	s_add_u32 s30, s28, 0x10000
	s_addc_u32 s31, s29, 0
	s_add_u32 s34, s30, 0x10000
	s_addc_u32 s35, s31, 0
	s_add_u32 s36, s34, 0x10000
	s_addc_u32 s37, s35, 0
	s_lshl_b32 s48, s4, 11
	s_add_u32 s38, s14, s48
	s_addc_u32 s39, s15, 0
	s_add_u32 s38, s38, 0xda0000
	s_addc_u32 s39, s39, 0
	s_add_u32 s40, s38, 0x10000
	s_addc_u32 s41, s39, 0
	s_add_u32 s42, s40, 0x10000
	s_addc_u32 s43, s41, 0
	s_add_u32 s44, s42, 0x10000
	s_addc_u32 s45, s43, 0
	v_and_b32_e32 v64, 15, v199
	v_bfe_u32 v65, v199, 4, 2
	v_lshrrev_b32_e32 v66, 1, v64
	v_xor_b32_e32 v65, v65, v66
	v_lshlrev_b32_e32 v65, 4, v65
	v_lshl_or_b32 v65, v64, 7, v65
	v_lshrrev_b32_e32 v66, 6, v199
	v_lshl_add_u32 v255, v66, 12, v65
	v_xor_b32_e32 v109, 64, v255
	v_add_u32_e32 v112, 0x4000, v65
	v_xor_b32_e32 v113, 64, v112
	v_readfirstlane_b32 s46, v156
	v_mov_b32_e32 v254, v110
	s_mov_b32 m0, s46
	s_nop 0
	global_load_lds_dwordx4 v254, s[28:29]
	s_add_u32 m0, m0, 0x1000
	s_nop 0
	global_load_lds_dwordx4 v254, s[30:31]
	s_add_u32 m0, m0, 0x1000
	s_nop 0
	global_load_lds_dwordx4 v254, s[34:35]
	s_add_u32 m0, m0, 0x1000
	s_nop 0
	global_load_lds_dwordx4 v254, s[36:37]
	s_add_u32 m0, m0, 0x1000
	s_nop 0
	global_load_lds_dwordx4 v254, s[38:39]
	s_add_u32 m0, m0, 0x1000
	s_nop 0
	global_load_lds_dwordx4 v254, s[40:41]
	s_add_u32 m0, m0, 0x1000
	s_nop 0
	global_load_lds_dwordx4 v254, s[42:43]
	s_add_u32 m0, m0, 0x1000
	s_nop 0
	global_load_lds_dwordx4 v254, s[44:45]
	v_add_u32_e32 v254, 0x80, v254
	s_add_u32 m0, s46, 0x8000
	s_nop 0
	global_load_lds_dwordx4 v254, s[28:29]
	s_add_u32 m0, m0, 0x1000
	s_nop 0
	global_load_lds_dwordx4 v254, s[30:31]
	s_add_u32 m0, m0, 0x1000
	s_nop 0
	global_load_lds_dwordx4 v254, s[34:35]
	s_add_u32 m0, m0, 0x1000
	s_nop 0
	global_load_lds_dwordx4 v254, s[36:37]
	s_add_u32 m0, m0, 0x1000
	s_nop 0
	global_load_lds_dwordx4 v254, s[38:39]
	s_add_u32 m0, m0, 0x1000
	s_nop 0
	global_load_lds_dwordx4 v254, s[40:41]
	s_add_u32 m0, m0, 0x1000
	s_nop 0
	global_load_lds_dwordx4 v254, s[42:43]
	s_add_u32 m0, m0, 0x1000
	s_nop 0
	global_load_lds_dwordx4 v254, s[44:45]
	v_add_u32_e32 v254, 0x80, v254
	v_mov_b32_e32 v48, 0
	v_mov_b32_e32 v49, 0
	v_mov_b32_e32 v50, 0
	v_mov_b32_e32 v51, 0
	v_mov_b32_e32 v52, 0
	v_mov_b32_e32 v53, 0
	v_mov_b32_e32 v54, 0
	v_mov_b32_e32 v55, 0
	v_mov_b32_e32 v56, 0
	v_mov_b32_e32 v57, 0
	v_mov_b32_e32 v58, 0
	v_mov_b32_e32 v59, 0
	v_mov_b32_e32 v60, 0
	v_mov_b32_e32 v61, 0
	v_mov_b32_e32 v62, 0
	v_mov_b32_e32 v63, 0
	v_mov_b32_e32 v32, 0
	v_mov_b32_e32 v33, 0
	v_mov_b32_e32 v34, 0
	v_mov_b32_e32 v35, 0
	v_mov_b32_e32 v36, 0
	v_mov_b32_e32 v37, 0
	v_mov_b32_e32 v38, 0
	v_mov_b32_e32 v39, 0
	v_mov_b32_e32 v40, 0
	v_mov_b32_e32 v41, 0
	v_mov_b32_e32 v42, 0
	v_mov_b32_e32 v43, 0
	v_mov_b32_e32 v44, 0
	v_mov_b32_e32 v45, 0
	v_mov_b32_e32 v46, 0
	v_mov_b32_e32 v47, 0
	v_mov_b32_e32 v16, 0
	v_mov_b32_e32 v17, 0
	v_mov_b32_e32 v18, 0
	v_mov_b32_e32 v19, 0
	v_mov_b32_e32 v20, 0
	v_mov_b32_e32 v21, 0
	v_mov_b32_e32 v22, 0
	v_mov_b32_e32 v23, 0
	v_mov_b32_e32 v24, 0
	v_mov_b32_e32 v25, 0
	v_mov_b32_e32 v26, 0
	v_mov_b32_e32 v27, 0
	v_mov_b32_e32 v28, 0
	v_mov_b32_e32 v29, 0
	v_mov_b32_e32 v30, 0
	v_mov_b32_e32 v31, 0
	v_mov_b32_e32 v0, 0
	v_mov_b32_e32 v1, 0
	v_mov_b32_e32 v2, 0
	v_mov_b32_e32 v3, 0
	v_mov_b32_e32 v4, 0
	v_mov_b32_e32 v5, 0
	v_mov_b32_e32 v6, 0
	v_mov_b32_e32 v7, 0
	v_mov_b32_e32 v8, 0
	v_mov_b32_e32 v9, 0
	v_mov_b32_e32 v10, 0
	v_mov_b32_e32 v11, 0
	v_mov_b32_e32 v12, 0
	v_mov_b32_e32 v13, 0
	v_mov_b32_e32 v14, 0
	v_mov_b32_e32 v15, 0
	s_mov_b32 s47, 7
.Lgk_loop_p14:
	s_waitcnt vmcnt(8)
	s_barrier
	ds_read_b128 v[64:67], v255
	ds_read_b128 v[68:71], v255 offset:2048
	ds_read_b128 v[80:83], v112
	ds_read_b128 v[84:87], v112 offset:2048
	ds_read_b128 v[88:91], v112 offset:4096
	ds_read_b128 v[92:95], v112 offset:6144
	ds_read_b128 v[96:99], v112 offset:8192
	ds_read_b128 v[100:103], v112 offset:10240
	ds_read_b128 v[118:121], v112 offset:12288
	ds_read_b128 v[122:125], v112 offset:14336
	ds_read_b128 v[72:75], v109
	ds_read_b128 v[76:79], v109 offset:2048
	ds_read_b128 v[172:175], v113
	ds_read_b128 v[226:229], v113 offset:2048
	ds_read_b128 v[230:233], v113 offset:4096
	ds_read_b128 v[234:237], v113 offset:6144
	ds_read_b128 v[238:241], v113 offset:8192
	ds_read_b128 v[242:245], v113 offset:10240
	ds_read_b128 v[246:249], v113 offset:12288
	ds_read_b128 v[250:253], v113 offset:14336
	s_waitcnt lgkmcnt(0)
	s_barrier
	s_mov_b32 m0, s46
	s_setprio 1
	v_mfma_f32_16x16x32_bf16 v[0:3], v[64:67], v[80:83], v[0:3]
	v_mfma_f32_16x16x32_bf16 v[4:7], v[64:67], v[84:87], v[4:7]
	v_mfma_f32_16x16x32_bf16 v[8:11], v[64:67], v[88:91], v[8:11]
	v_mfma_f32_16x16x32_bf16 v[12:15], v[64:67], v[92:95], v[12:15]
	global_load_lds_dwordx4 v254, s[28:29]
	s_add_u32 m0, m0, 0x1000
	v_mfma_f32_16x16x32_bf16 v[16:19], v[64:67], v[96:99], v[16:19]
	v_mfma_f32_16x16x32_bf16 v[20:23], v[64:67], v[100:103], v[20:23]
	v_mfma_f32_16x16x32_bf16 v[24:27], v[64:67], v[118:121], v[24:27]
	v_mfma_f32_16x16x32_bf16 v[28:31], v[64:67], v[122:125], v[28:31]
	global_load_lds_dwordx4 v254, s[30:31]
	s_add_u32 m0, m0, 0x1000
	v_mfma_f32_16x16x32_bf16 v[32:35], v[68:71], v[80:83], v[32:35]
	v_mfma_f32_16x16x32_bf16 v[36:39], v[68:71], v[84:87], v[36:39]
	v_mfma_f32_16x16x32_bf16 v[40:43], v[68:71], v[88:91], v[40:43]
	v_mfma_f32_16x16x32_bf16 v[44:47], v[68:71], v[92:95], v[44:47]
	global_load_lds_dwordx4 v254, s[34:35]
	s_add_u32 m0, m0, 0x1000
	v_mfma_f32_16x16x32_bf16 v[48:51], v[68:71], v[96:99], v[48:51]
	v_mfma_f32_16x16x32_bf16 v[52:55], v[68:71], v[100:103], v[52:55]
	v_mfma_f32_16x16x32_bf16 v[56:59], v[68:71], v[118:121], v[56:59]
	v_mfma_f32_16x16x32_bf16 v[60:63], v[68:71], v[122:125], v[60:63]
	global_load_lds_dwordx4 v254, s[36:37]
	s_add_u32 m0, m0, 0x1000
	v_mfma_f32_16x16x32_bf16 v[0:3], v[72:75], v[172:175], v[0:3]
	v_mfma_f32_16x16x32_bf16 v[4:7], v[72:75], v[226:229], v[4:7]
	v_mfma_f32_16x16x32_bf16 v[8:11], v[72:75], v[230:233], v[8:11]
	v_mfma_f32_16x16x32_bf16 v[12:15], v[72:75], v[234:237], v[12:15]
	global_load_lds_dwordx4 v254, s[38:39]
	s_add_u32 m0, m0, 0x1000
	v_mfma_f32_16x16x32_bf16 v[16:19], v[72:75], v[238:241], v[16:19]
	v_mfma_f32_16x16x32_bf16 v[20:23], v[72:75], v[242:245], v[20:23]
	v_mfma_f32_16x16x32_bf16 v[24:27], v[72:75], v[246:249], v[24:27]
	v_mfma_f32_16x16x32_bf16 v[28:31], v[72:75], v[250:253], v[28:31]
	global_load_lds_dwordx4 v254, s[40:41]
	s_add_u32 m0, m0, 0x1000
	v_mfma_f32_16x16x32_bf16 v[32:35], v[76:79], v[172:175], v[32:35]
	v_mfma_f32_16x16x32_bf16 v[36:39], v[76:79], v[226:229], v[36:39]
	v_mfma_f32_16x16x32_bf16 v[40:43], v[76:79], v[230:233], v[40:43]
	v_mfma_f32_16x16x32_bf16 v[44:47], v[76:79], v[234:237], v[44:47]
	global_load_lds_dwordx4 v254, s[42:43]
	s_add_u32 m0, m0, 0x1000
	v_mfma_f32_16x16x32_bf16 v[48:51], v[76:79], v[238:241], v[48:51]
	v_mfma_f32_16x16x32_bf16 v[52:55], v[76:79], v[242:245], v[52:55]
	v_mfma_f32_16x16x32_bf16 v[56:59], v[76:79], v[246:249], v[56:59]
	v_mfma_f32_16x16x32_bf16 v[60:63], v[76:79], v[250:253], v[60:63]
	global_load_lds_dwordx4 v254, s[44:45]
	s_setprio 0
	v_add_u32_e32 v254, 0x80, v254
	s_waitcnt vmcnt(8)
	s_barrier
	ds_read_b128 v[64:67], v255 offset:32768
	ds_read_b128 v[68:71], v255 offset:34816
	ds_read_b128 v[80:83], v112 offset:32768
	ds_read_b128 v[84:87], v112 offset:34816
	ds_read_b128 v[88:91], v112 offset:36864
	ds_read_b128 v[92:95], v112 offset:38912
	ds_read_b128 v[96:99], v112 offset:40960
	ds_read_b128 v[100:103], v112 offset:43008
	ds_read_b128 v[118:121], v112 offset:45056
	ds_read_b128 v[122:125], v112 offset:47104
	ds_read_b128 v[72:75], v109 offset:32768
	ds_read_b128 v[76:79], v109 offset:34816
	ds_read_b128 v[172:175], v113 offset:32768
	ds_read_b128 v[226:229], v113 offset:34816
	ds_read_b128 v[230:233], v113 offset:36864
	ds_read_b128 v[234:237], v113 offset:38912
	ds_read_b128 v[238:241], v113 offset:40960
	ds_read_b128 v[242:245], v113 offset:43008
	ds_read_b128 v[246:249], v113 offset:45056
	ds_read_b128 v[250:253], v113 offset:47104
	s_waitcnt lgkmcnt(0)
	s_barrier
	s_add_u32 m0, s46, 0x8000
	s_setprio 1
	v_mfma_f32_16x16x32_bf16 v[0:3], v[64:67], v[80:83], v[0:3]
	v_mfma_f32_16x16x32_bf16 v[4:7], v[64:67], v[84:87], v[4:7]
	v_mfma_f32_16x16x32_bf16 v[8:11], v[64:67], v[88:91], v[8:11]
	v_mfma_f32_16x16x32_bf16 v[12:15], v[64:67], v[92:95], v[12:15]
	global_load_lds_dwordx4 v254, s[28:29]
	s_add_u32 m0, m0, 0x1000
	v_mfma_f32_16x16x32_bf16 v[16:19], v[64:67], v[96:99], v[16:19]
	v_mfma_f32_16x16x32_bf16 v[20:23], v[64:67], v[100:103], v[20:23]
	v_mfma_f32_16x16x32_bf16 v[24:27], v[64:67], v[118:121], v[24:27]
	v_mfma_f32_16x16x32_bf16 v[28:31], v[64:67], v[122:125], v[28:31]
	global_load_lds_dwordx4 v254, s[30:31]
	s_add_u32 m0, m0, 0x1000
	v_mfma_f32_16x16x32_bf16 v[32:35], v[68:71], v[80:83], v[32:35]
	v_mfma_f32_16x16x32_bf16 v[36:39], v[68:71], v[84:87], v[36:39]
	v_mfma_f32_16x16x32_bf16 v[40:43], v[68:71], v[88:91], v[40:43]
	v_mfma_f32_16x16x32_bf16 v[44:47], v[68:71], v[92:95], v[44:47]
	global_load_lds_dwordx4 v254, s[34:35]
	s_add_u32 m0, m0, 0x1000
	v_mfma_f32_16x16x32_bf16 v[48:51], v[68:71], v[96:99], v[48:51]
	v_mfma_f32_16x16x32_bf16 v[52:55], v[68:71], v[100:103], v[52:55]
	v_mfma_f32_16x16x32_bf16 v[56:59], v[68:71], v[118:121], v[56:59]
	v_mfma_f32_16x16x32_bf16 v[60:63], v[68:71], v[122:125], v[60:63]
	global_load_lds_dwordx4 v254, s[36:37]
	s_add_u32 m0, m0, 0x1000
	v_mfma_f32_16x16x32_bf16 v[0:3], v[72:75], v[172:175], v[0:3]
	v_mfma_f32_16x16x32_bf16 v[4:7], v[72:75], v[226:229], v[4:7]
	v_mfma_f32_16x16x32_bf16 v[8:11], v[72:75], v[230:233], v[8:11]
	v_mfma_f32_16x16x32_bf16 v[12:15], v[72:75], v[234:237], v[12:15]
	global_load_lds_dwordx4 v254, s[38:39]
	s_add_u32 m0, m0, 0x1000
	v_mfma_f32_16x16x32_bf16 v[16:19], v[72:75], v[238:241], v[16:19]
	v_mfma_f32_16x16x32_bf16 v[20:23], v[72:75], v[242:245], v[20:23]
	v_mfma_f32_16x16x32_bf16 v[24:27], v[72:75], v[246:249], v[24:27]
	v_mfma_f32_16x16x32_bf16 v[28:31], v[72:75], v[250:253], v[28:31]
	global_load_lds_dwordx4 v254, s[40:41]
	s_add_u32 m0, m0, 0x1000
	v_mfma_f32_16x16x32_bf16 v[32:35], v[76:79], v[172:175], v[32:35]
	v_mfma_f32_16x16x32_bf16 v[36:39], v[76:79], v[226:229], v[36:39]
	v_mfma_f32_16x16x32_bf16 v[40:43], v[76:79], v[230:233], v[40:43]
	v_mfma_f32_16x16x32_bf16 v[44:47], v[76:79], v[234:237], v[44:47]
	global_load_lds_dwordx4 v254, s[42:43]
	s_add_u32 m0, m0, 0x1000
	v_mfma_f32_16x16x32_bf16 v[48:51], v[76:79], v[238:241], v[48:51]
	v_mfma_f32_16x16x32_bf16 v[52:55], v[76:79], v[242:245], v[52:55]
	v_mfma_f32_16x16x32_bf16 v[56:59], v[76:79], v[246:249], v[56:59]
	v_mfma_f32_16x16x32_bf16 v[60:63], v[76:79], v[250:253], v[60:63]
	global_load_lds_dwordx4 v254, s[44:45]
	s_setprio 0
	v_add_u32_e32 v254, 0x80, v254
	s_sub_u32 s47, s47, 1
	s_cmp_lg_u32 s47, 0
	s_cbranch_scc1 .Lgk_loop_p14
	s_waitcnt vmcnt(8)
	s_barrier
	ds_read_b128 v[64:67], v255
	ds_read_b128 v[68:71], v255 offset:2048
	ds_read_b128 v[80:83], v112
	ds_read_b128 v[84:87], v112 offset:2048
	ds_read_b128 v[88:91], v112 offset:4096
	ds_read_b128 v[92:95], v112 offset:6144
	ds_read_b128 v[96:99], v112 offset:8192
	ds_read_b128 v[100:103], v112 offset:10240
	ds_read_b128 v[118:121], v112 offset:12288
	ds_read_b128 v[122:125], v112 offset:14336
	ds_read_b128 v[72:75], v109
	ds_read_b128 v[76:79], v109 offset:2048
	ds_read_b128 v[172:175], v113
	ds_read_b128 v[226:229], v113 offset:2048
	ds_read_b128 v[230:233], v113 offset:4096
	ds_read_b128 v[234:237], v113 offset:6144
	ds_read_b128 v[238:241], v113 offset:8192
	ds_read_b128 v[242:245], v113 offset:10240
	ds_read_b128 v[246:249], v113 offset:12288
	ds_read_b128 v[250:253], v113 offset:14336
	s_waitcnt lgkmcnt(0)
	s_barrier
	s_setprio 1
	v_mfma_f32_16x16x32_bf16 v[0:3], v[64:67], v[80:83], v[0:3]
	v_mfma_f32_16x16x32_bf16 v[4:7], v[64:67], v[84:87], v[4:7]
	v_mfma_f32_16x16x32_bf16 v[8:11], v[64:67], v[88:91], v[8:11]
	v_mfma_f32_16x16x32_bf16 v[12:15], v[64:67], v[92:95], v[12:15]
	v_mfma_f32_16x16x32_bf16 v[16:19], v[64:67], v[96:99], v[16:19]
	v_mfma_f32_16x16x32_bf16 v[20:23], v[64:67], v[100:103], v[20:23]
	v_mfma_f32_16x16x32_bf16 v[24:27], v[64:67], v[118:121], v[24:27]
	v_mfma_f32_16x16x32_bf16 v[28:31], v[64:67], v[122:125], v[28:31]
	v_mfma_f32_16x16x32_bf16 v[32:35], v[68:71], v[80:83], v[32:35]
	v_mfma_f32_16x16x32_bf16 v[36:39], v[68:71], v[84:87], v[36:39]
	v_mfma_f32_16x16x32_bf16 v[40:43], v[68:71], v[88:91], v[40:43]
	v_mfma_f32_16x16x32_bf16 v[44:47], v[68:71], v[92:95], v[44:47]
	v_mfma_f32_16x16x32_bf16 v[48:51], v[68:71], v[96:99], v[48:51]
	v_mfma_f32_16x16x32_bf16 v[52:55], v[68:71], v[100:103], v[52:55]
	v_mfma_f32_16x16x32_bf16 v[56:59], v[68:71], v[118:121], v[56:59]
	v_mfma_f32_16x16x32_bf16 v[60:63], v[68:71], v[122:125], v[60:63]
	v_mfma_f32_16x16x32_bf16 v[0:3], v[72:75], v[172:175], v[0:3]
	v_mfma_f32_16x16x32_bf16 v[4:7], v[72:75], v[226:229], v[4:7]
	v_mfma_f32_16x16x32_bf16 v[8:11], v[72:75], v[230:233], v[8:11]
	v_mfma_f32_16x16x32_bf16 v[12:15], v[72:75], v[234:237], v[12:15]
	v_mfma_f32_16x16x32_bf16 v[16:19], v[72:75], v[238:241], v[16:19]
	v_mfma_f32_16x16x32_bf16 v[20:23], v[72:75], v[242:245], v[20:23]
	v_mfma_f32_16x16x32_bf16 v[24:27], v[72:75], v[246:249], v[24:27]
	v_mfma_f32_16x16x32_bf16 v[28:31], v[72:75], v[250:253], v[28:31]
	v_mfma_f32_16x16x32_bf16 v[32:35], v[76:79], v[172:175], v[32:35]
	v_mfma_f32_16x16x32_bf16 v[36:39], v[76:79], v[226:229], v[36:39]
	v_mfma_f32_16x16x32_bf16 v[40:43], v[76:79], v[230:233], v[40:43]
	v_mfma_f32_16x16x32_bf16 v[44:47], v[76:79], v[234:237], v[44:47]
	v_mfma_f32_16x16x32_bf16 v[48:51], v[76:79], v[238:241], v[48:51]
	v_mfma_f32_16x16x32_bf16 v[52:55], v[76:79], v[242:245], v[52:55]
	v_mfma_f32_16x16x32_bf16 v[56:59], v[76:79], v[246:249], v[56:59]
	v_mfma_f32_16x16x32_bf16 v[60:63], v[76:79], v[250:253], v[60:63]
	s_setprio 0
	s_waitcnt vmcnt(0)
	s_barrier
	ds_read_b128 v[64:67], v255 offset:32768
	ds_read_b128 v[68:71], v255 offset:34816
	ds_read_b128 v[80:83], v112 offset:32768
	ds_read_b128 v[84:87], v112 offset:34816
	ds_read_b128 v[88:91], v112 offset:36864
	ds_read_b128 v[92:95], v112 offset:38912
	ds_read_b128 v[96:99], v112 offset:40960
	ds_read_b128 v[100:103], v112 offset:43008
	ds_read_b128 v[118:121], v112 offset:45056
	ds_read_b128 v[122:125], v112 offset:47104
	ds_read_b128 v[72:75], v109 offset:32768
	ds_read_b128 v[76:79], v109 offset:34816
	ds_read_b128 v[172:175], v113 offset:32768
	ds_read_b128 v[226:229], v113 offset:34816
	ds_read_b128 v[230:233], v113 offset:36864
	ds_read_b128 v[234:237], v113 offset:38912
	ds_read_b128 v[238:241], v113 offset:40960
	ds_read_b128 v[242:245], v113 offset:43008
	ds_read_b128 v[246:249], v113 offset:45056
	ds_read_b128 v[250:253], v113 offset:47104
	s_waitcnt lgkmcnt(0)
	s_barrier
	s_setprio 1
	v_mfma_f32_16x16x32_bf16 v[0:3], v[64:67], v[80:83], v[0:3]
	v_mfma_f32_16x16x32_bf16 v[4:7], v[64:67], v[84:87], v[4:7]
	v_mfma_f32_16x16x32_bf16 v[8:11], v[64:67], v[88:91], v[8:11]
	v_mfma_f32_16x16x32_bf16 v[12:15], v[64:67], v[92:95], v[12:15]
	v_mfma_f32_16x16x32_bf16 v[16:19], v[64:67], v[96:99], v[16:19]
	v_mfma_f32_16x16x32_bf16 v[20:23], v[64:67], v[100:103], v[20:23]
	v_mfma_f32_16x16x32_bf16 v[24:27], v[64:67], v[118:121], v[24:27]
	v_mfma_f32_16x16x32_bf16 v[28:31], v[64:67], v[122:125], v[28:31]
	v_mfma_f32_16x16x32_bf16 v[32:35], v[68:71], v[80:83], v[32:35]
	v_mfma_f32_16x16x32_bf16 v[36:39], v[68:71], v[84:87], v[36:39]
	v_mfma_f32_16x16x32_bf16 v[40:43], v[68:71], v[88:91], v[40:43]
	v_mfma_f32_16x16x32_bf16 v[44:47], v[68:71], v[92:95], v[44:47]
	v_mfma_f32_16x16x32_bf16 v[48:51], v[68:71], v[96:99], v[48:51]
	v_mfma_f32_16x16x32_bf16 v[52:55], v[68:71], v[100:103], v[52:55]
	v_mfma_f32_16x16x32_bf16 v[56:59], v[68:71], v[118:121], v[56:59]
	v_mfma_f32_16x16x32_bf16 v[60:63], v[68:71], v[122:125], v[60:63]
	v_mfma_f32_16x16x32_bf16 v[0:3], v[72:75], v[172:175], v[0:3]
	v_mfma_f32_16x16x32_bf16 v[4:7], v[72:75], v[226:229], v[4:7]
	v_mfma_f32_16x16x32_bf16 v[8:11], v[72:75], v[230:233], v[8:11]
	v_mfma_f32_16x16x32_bf16 v[12:15], v[72:75], v[234:237], v[12:15]
	v_mfma_f32_16x16x32_bf16 v[16:19], v[72:75], v[238:241], v[16:19]
	v_mfma_f32_16x16x32_bf16 v[20:23], v[72:75], v[242:245], v[20:23]
	v_mfma_f32_16x16x32_bf16 v[24:27], v[72:75], v[246:249], v[24:27]
	v_mfma_f32_16x16x32_bf16 v[28:31], v[72:75], v[250:253], v[28:31]
	v_mfma_f32_16x16x32_bf16 v[32:35], v[76:79], v[172:175], v[32:35]
	v_mfma_f32_16x16x32_bf16 v[36:39], v[76:79], v[226:229], v[36:39]
	v_mfma_f32_16x16x32_bf16 v[40:43], v[76:79], v[230:233], v[40:43]
	v_mfma_f32_16x16x32_bf16 v[44:47], v[76:79], v[234:237], v[44:47]
	v_mfma_f32_16x16x32_bf16 v[48:51], v[76:79], v[238:241], v[48:51]
	v_mfma_f32_16x16x32_bf16 v[52:55], v[76:79], v[242:245], v[52:55]
	v_mfma_f32_16x16x32_bf16 v[56:59], v[76:79], v[246:249], v[56:59]
	v_mfma_f32_16x16x32_bf16 v[60:63], v[76:79], v[250:253], v[60:63]
	s_setprio 0
	s_nop 7
	s_nop 7
	v_and_b32_e32 v66, 63, v199
	v_lshrrev_b32_e32 v67, 6, v199
	v_lshlrev_b32_e32 v67, 14, v67
	v_lshl_add_u32 v64, v66, 4, v67
	v_and_b32_e32 v65, 15, v66
	v_lshl_add_u32 v65, v65, 4, v67
	v_bfe_u32 v67, v66, 4, 1
	v_lshl_add_u32 v65, v67, 10, v65
	v_bfe_u32 v67, v66, 5, 1
	v_lshl_add_u32 v65, v67, 8, v65
	ds_write_b128 v64, v[0:3]
	ds_write_b128 v64, v[4:7] offset:1024
	ds_write_b128 v64, v[8:11] offset:2048
	ds_write_b128 v64, v[12:15] offset:3072
	ds_write_b128 v64, v[16:19] offset:4096
	ds_write_b128 v64, v[20:23] offset:5120
	ds_write_b128 v64, v[24:27] offset:6144
	ds_write_b128 v64, v[28:31] offset:7168
	ds_write_b128 v64, v[32:35] offset:8192
	ds_write_b128 v64, v[36:39] offset:9216
	ds_write_b128 v64, v[40:43] offset:10240
	ds_write_b128 v64, v[44:47] offset:11264
	ds_write_b128 v64, v[48:51] offset:12288
	ds_write_b128 v64, v[52:55] offset:13312
	ds_write_b128 v64, v[56:59] offset:14336
	ds_write_b128 v64, v[60:63] offset:15360
	s_waitcnt lgkmcnt(0)
	ds_read_b128 v[48:51], v65
	ds_read_b128 v[52:55], v65 offset:512
	ds_read_b128 v[56:59], v65 offset:8192
	ds_read_b128 v[60:63], v65 offset:8704
	ds_read_b128 v[32:35], v65 offset:2048
	ds_read_b128 v[36:39], v65 offset:2560
	ds_read_b128 v[40:43], v65 offset:10240
	ds_read_b128 v[44:47], v65 offset:10752
	ds_read_b128 v[16:19], v65 offset:4096
	ds_read_b128 v[20:23], v65 offset:4608
	ds_read_b128 v[24:27], v65 offset:12288
	ds_read_b128 v[28:31], v65 offset:12800
	ds_read_b128 v[0:3], v65 offset:6144
	ds_read_b128 v[4:7], v65 offset:6656
	ds_read_b128 v[8:11], v65 offset:14336
	ds_read_b128 v[12:15], v65 offset:14848
	s_waitcnt lgkmcnt(0)
	s_barrier
	s_branch .LBB0_1175

.LBB0_1322:
	s_ashr_i32 s6, s3, 31
	s_lshr_b32 s6, s6, 26
	s_add_i32 s6, s3, s6
	s_ashr_i32 s58, s6, 6
	s_andn2_b32 s6, s6, 63
	s_sub_i32 s6, s3, s6
	s_ashr_i32 s59, s6, 31
	s_lshr_b32 s59, s59, 29
	s_add_i32 s59, s6, s59
	s_ashr_i32 s64, s59, 3
	s_and_b32 s59, s59, -8
	s_lshl_b32 s58, s58, 3
	s_sub_i32 s6, s6, s59
	s_add_i32 s6, s6, s58
	s_lshl_b32 s66, s6, 7
	s_ashr_i32 s67, s66, 31
	s_lshl_b32 s68, s64, 7
	s_lshl_b64 s[58:59], s[66:67], 11
	s_ashr_i32 s69, s68, 31
	s_lshl_b32 s38, s66, 11
	s_add_u32 s18, s14, s38
	s_addc_u32 s19, s15, 0
	s_add_u32 s18, s18, 0xb79f000
	s_addc_u32 s19, s19, 0
	s_add_u32 s20, s18, 0x10000
	s_addc_u32 s21, s19, 0
	s_add_u32 s22, s20, 0x10000
	s_addc_u32 s23, s21, 0
	s_add_u32 s24, s22, 0x10000
	s_addc_u32 s25, s23, 0
	s_lshl_b32 s38, s68, 11
	s_add_u32 s26, s14, s38
	s_addc_u32 s27, s15, 0
	s_add_u32 s26, s26, 0x10a0000
	s_addc_u32 s27, s27, 0
	s_add_u32 s28, s26, 0x10000
	s_addc_u32 s29, s27, 0
	s_add_u32 s30, s28, 0x10000
	s_addc_u32 s31, s29, 0
	s_add_u32 s34, s30, 0x10000
	s_addc_u32 s35, s31, 0
	v_and_b32_e32 v70, 15, v199
	v_bfe_u32 v71, v199, 4, 2
	v_lshrrev_b32_e32 v72, 1, v70
	v_xor_b32_e32 v71, v71, v72
	v_lshlrev_b32_e32 v71, 4, v71
	v_lshl_or_b32 v71, v70, 7, v71
	v_lshrrev_b32_e32 v72, 6, v199
	v_lshl_add_u32 v198, v72, 12, v71
	v_xor_b32_e32 v238, 64, v198
	v_add_u32_e32 v239, 0x4000, v71
	v_xor_b32_e32 v240, 64, v239
	v_readfirstlane_b32 s36, v140
	v_mov_b32_e32 v254, v64
	s_mov_b32 m0, s36
	s_nop 0
	global_load_lds_dwordx4 v254, s[18:19]
	s_add_u32 m0, m0, 0x1000
	s_nop 0
	global_load_lds_dwordx4 v254, s[20:21]
	s_add_u32 m0, m0, 0x1000
	s_nop 0
	global_load_lds_dwordx4 v254, s[22:23]
	s_add_u32 m0, m0, 0x1000
	s_nop 0
	global_load_lds_dwordx4 v254, s[24:25]
	s_add_u32 m0, m0, 0x1000
	s_nop 0
	global_load_lds_dwordx4 v254, s[26:27]
	s_add_u32 m0, m0, 0x1000
	s_nop 0
	global_load_lds_dwordx4 v254, s[28:29]
	s_add_u32 m0, m0, 0x1000
	s_nop 0
	global_load_lds_dwordx4 v254, s[30:31]
	s_add_u32 m0, m0, 0x1000
	s_nop 0
	global_load_lds_dwordx4 v254, s[34:35]
	v_add_u32_e32 v254, 0x80, v254
	s_add_u32 m0, s36, 0x8000
	s_nop 0
	global_load_lds_dwordx4 v254, s[18:19]
	s_add_u32 m0, m0, 0x1000
	s_nop 0
	global_load_lds_dwordx4 v254, s[20:21]
	s_add_u32 m0, m0, 0x1000
	s_nop 0
	global_load_lds_dwordx4 v254, s[22:23]
	s_add_u32 m0, m0, 0x1000
	s_nop 0
	global_load_lds_dwordx4 v254, s[24:25]
	s_add_u32 m0, m0, 0x1000
	s_nop 0
	global_load_lds_dwordx4 v254, s[26:27]
	s_add_u32 m0, m0, 0x1000
	s_nop 0
	global_load_lds_dwordx4 v254, s[28:29]
	s_add_u32 m0, m0, 0x1000
	s_nop 0
	global_load_lds_dwordx4 v254, s[30:31]
	s_add_u32 m0, m0, 0x1000
	s_nop 0
	global_load_lds_dwordx4 v254, s[34:35]
	v_add_u32_e32 v254, 0x80, v254
	v_mov_b32_e32 v48, 0
	v_mov_b32_e32 v49, 0
	v_mov_b32_e32 v50, 0
	v_mov_b32_e32 v51, 0
	v_mov_b32_e32 v52, 0
	v_mov_b32_e32 v53, 0
	v_mov_b32_e32 v54, 0
	v_mov_b32_e32 v55, 0
	v_mov_b32_e32 v56, 0
	v_mov_b32_e32 v57, 0
	v_mov_b32_e32 v58, 0
	v_mov_b32_e32 v59, 0
	v_mov_b32_e32 v60, 0
	v_mov_b32_e32 v61, 0
	v_mov_b32_e32 v62, 0
	v_mov_b32_e32 v63, 0
	v_mov_b32_e32 v32, 0
	v_mov_b32_e32 v33, 0
	v_mov_b32_e32 v34, 0
	v_mov_b32_e32 v35, 0
	v_mov_b32_e32 v36, 0
	v_mov_b32_e32 v37, 0
	v_mov_b32_e32 v38, 0
	v_mov_b32_e32 v39, 0
	v_mov_b32_e32 v40, 0
	v_mov_b32_e32 v41, 0
	v_mov_b32_e32 v42, 0
	v_mov_b32_e32 v43, 0
	v_mov_b32_e32 v44, 0
	v_mov_b32_e32 v45, 0
	v_mov_b32_e32 v46, 0
	v_mov_b32_e32 v47, 0
	v_mov_b32_e32 v16, 0
	v_mov_b32_e32 v17, 0
	v_mov_b32_e32 v18, 0
	v_mov_b32_e32 v19, 0
	v_mov_b32_e32 v20, 0
	v_mov_b32_e32 v21, 0
	v_mov_b32_e32 v22, 0
	v_mov_b32_e32 v23, 0
	v_mov_b32_e32 v24, 0
	v_mov_b32_e32 v25, 0
	v_mov_b32_e32 v26, 0
	v_mov_b32_e32 v27, 0
	v_mov_b32_e32 v28, 0
	v_mov_b32_e32 v29, 0
	v_mov_b32_e32 v30, 0
	v_mov_b32_e32 v31, 0
	v_mov_b32_e32 v0, 0
	v_mov_b32_e32 v1, 0
	v_mov_b32_e32 v2, 0
	v_mov_b32_e32 v3, 0
	v_mov_b32_e32 v4, 0
	v_mov_b32_e32 v5, 0
	v_mov_b32_e32 v6, 0
	v_mov_b32_e32 v7, 0
	v_mov_b32_e32 v8, 0
	v_mov_b32_e32 v9, 0
	v_mov_b32_e32 v10, 0
	v_mov_b32_e32 v11, 0
	v_mov_b32_e32 v12, 0
	v_mov_b32_e32 v13, 0
	v_mov_b32_e32 v14, 0
	v_mov_b32_e32 v15, 0
	s_mov_b32 s37, 7

.Lmap_done_2:
	s_lshl_b32 s60, s4, 7
	s_lshl_b32 s58, s76, 7
	s_ashr_i32 s61, s60, 31
	s_ashr_i32 s59, s58, 31
	s_lshl_b64 s[62:63], s[60:61], 11
	s_lshl_b64 s[64:65], s[58:59], 11
	s_lshl_b32 s38, s60, 11
	s_add_u32 s18, s14, s38
	s_addc_u32 s19, s15, 0
	s_add_u32 s18, s18, 0x679f000
	s_addc_u32 s19, s19, 0
	s_add_u32 s20, s18, 0x10000
	s_addc_u32 s21, s19, 0
	s_add_u32 s22, s20, 0x10000
	s_addc_u32 s23, s21, 0
	s_add_u32 s24, s22, 0x10000
	s_addc_u32 s25, s23, 0
	s_lshl_b32 s38, s58, 11
	s_add_u32 s26, s14, s38
	s_addc_u32 s27, s15, 0
	s_add_u32 s26, s26, 0x2fa0000
	s_addc_u32 s27, s27, 0
	s_add_u32 s28, s26, 0x10000
	s_addc_u32 s29, s27, 0
	s_add_u32 s30, s28, 0x10000
	s_addc_u32 s31, s29, 0
	s_add_u32 s34, s30, 0x10000
	s_addc_u32 s35, s31, 0
	v_and_b32_e32 v64, 15, v199
	v_bfe_u32 v65, v199, 4, 2
	v_lshrrev_b32_e32 v66, 1, v64
	v_xor_b32_e32 v65, v65, v66
	v_lshlrev_b32_e32 v65, 4, v65
	v_lshl_or_b32 v65, v64, 7, v65
	v_lshrrev_b32_e32 v66, 6, v199
	v_lshl_add_u32 v217, v66, 12, v65
	v_xor_b32_e32 v255, 64, v217
	v_add_u32_e32 v78, 0x4000, v65
	v_xor_b32_e32 v79, 64, v78
	v_readfirstlane_b32 s36, v94
	v_mov_b32_e32 v254, v76
	s_mov_b32 m0, s36
	s_nop 0
	global_load_lds_dwordx4 v254, s[18:19]
	s_add_u32 m0, m0, 0x1000
	s_nop 0
	global_load_lds_dwordx4 v254, s[20:21]
	s_add_u32 m0, m0, 0x1000
	s_nop 0
	global_load_lds_dwordx4 v254, s[22:23]
	s_add_u32 m0, m0, 0x1000
	s_nop 0
	global_load_lds_dwordx4 v254, s[24:25]
	s_add_u32 m0, m0, 0x1000
	s_nop 0
	global_load_lds_dwordx4 v254, s[26:27]
	s_add_u32 m0, m0, 0x1000
	s_nop 0
	global_load_lds_dwordx4 v254, s[28:29]
	s_add_u32 m0, m0, 0x1000
	s_nop 0
	global_load_lds_dwordx4 v254, s[30:31]
	s_add_u32 m0, m0, 0x1000
	s_nop 0
	global_load_lds_dwordx4 v254, s[34:35]
	v_add_u32_e32 v254, 0x80, v254
	s_add_u32 m0, s36, 0x8000
	s_nop 0
	global_load_lds_dwordx4 v254, s[18:19]
	s_add_u32 m0, m0, 0x1000
	s_nop 0
	global_load_lds_dwordx4 v254, s[20:21]
	s_add_u32 m0, m0, 0x1000
	s_nop 0
	global_load_lds_dwordx4 v254, s[22:23]
	s_add_u32 m0, m0, 0x1000
	s_nop 0
	global_load_lds_dwordx4 v254, s[24:25]
	s_add_u32 m0, m0, 0x1000
	s_nop 0
	global_load_lds_dwordx4 v254, s[26:27]
	s_add_u32 m0, m0, 0x1000
	s_nop 0
	global_load_lds_dwordx4 v254, s[28:29]
	s_add_u32 m0, m0, 0x1000
	s_nop 0
	global_load_lds_dwordx4 v254, s[30:31]
	s_add_u32 m0, m0, 0x1000
	s_nop 0
	global_load_lds_dwordx4 v254, s[34:35]
	v_add_u32_e32 v254, 0x80, v254
	v_mov_b32_e32 v48, 0
	v_mov_b32_e32 v49, 0
	v_mov_b32_e32 v50, 0
	v_mov_b32_e32 v51, 0
	v_mov_b32_e32 v52, 0
	v_mov_b32_e32 v53, 0
	v_mov_b32_e32 v54, 0
	v_mov_b32_e32 v55, 0
	v_mov_b32_e32 v56, 0
	v_mov_b32_e32 v57, 0
	v_mov_b32_e32 v58, 0
	v_mov_b32_e32 v59, 0
	v_mov_b32_e32 v60, 0
	v_mov_b32_e32 v61, 0
	v_mov_b32_e32 v62, 0
	v_mov_b32_e32 v63, 0
	v_mov_b32_e32 v32, 0
	v_mov_b32_e32 v33, 0
	v_mov_b32_e32 v34, 0
	v_mov_b32_e32 v35, 0
	v_mov_b32_e32 v36, 0
	v_mov_b32_e32 v37, 0
	v_mov_b32_e32 v38, 0
	v_mov_b32_e32 v39, 0
	v_mov_b32_e32 v40, 0
	v_mov_b32_e32 v41, 0
	v_mov_b32_e32 v42, 0
	v_mov_b32_e32 v43, 0
	v_mov_b32_e32 v44, 0
	v_mov_b32_e32 v45, 0
	v_mov_b32_e32 v46, 0
	v_mov_b32_e32 v47, 0
	v_mov_b32_e32 v16, 0
	v_mov_b32_e32 v17, 0
	v_mov_b32_e32 v18, 0
	v_mov_b32_e32 v19, 0
	v_mov_b32_e32 v20, 0
	v_mov_b32_e32 v21, 0
	v_mov_b32_e32 v22, 0
	v_mov_b32_e32 v23, 0
	v_mov_b32_e32 v24, 0
	v_mov_b32_e32 v25, 0
	v_mov_b32_e32 v26, 0
	v_mov_b32_e32 v27, 0
	v_mov_b32_e32 v28, 0
	v_mov_b32_e32 v29, 0
	v_mov_b32_e32 v30, 0
	v_mov_b32_e32 v31, 0
	v_mov_b32_e32 v0, 0
	v_mov_b32_e32 v1, 0
	v_mov_b32_e32 v2, 0
	v_mov_b32_e32 v3, 0
	v_mov_b32_e32 v4, 0
	v_mov_b32_e32 v5, 0
	v_mov_b32_e32 v6, 0
	v_mov_b32_e32 v7, 0
	v_mov_b32_e32 v8, 0
	v_mov_b32_e32 v9, 0
	v_mov_b32_e32 v10, 0
	v_mov_b32_e32 v11, 0
	v_mov_b32_e32 v12, 0
	v_mov_b32_e32 v13, 0
	v_mov_b32_e32 v14, 0
	v_mov_b32_e32 v15, 0
	s_mov_b32 s37, 7

.LBB0_1394:
	s_ashr_i32 s6, s3, 31
	s_lshr_b32 s6, s6, 26
	s_add_i32 s6, s3, s6
	s_ashr_i32 s58, s6, 6
	s_andn2_b32 s6, s6, 63
	s_sub_i32 s6, s3, s6
	s_ashr_i32 s59, s6, 31
	s_lshr_b32 s59, s59, 29
	s_add_i32 s59, s6, s59
	s_ashr_i32 s64, s59, 3
	s_and_b32 s59, s59, -8
	s_lshl_b32 s58, s58, 3
	s_sub_i32 s6, s6, s59
	s_add_i32 s6, s6, s58
	s_lshl_b32 s67, s6, 7
	s_lshl_b32 s68, s64, 7
	s_waitcnt lgkmcnt(0)
	s_mul_i32 s38, s6, 0xb0000
	s_add_u32 s18, s14, s38
	s_addc_u32 s19, s15, 0
	s_add_u32 s18, s18, 0x879f000
	s_addc_u32 s19, s19, 0
	s_add_u32 s20, s18, 0x2c000
	s_addc_u32 s21, s19, 0
	s_add_u32 s22, s20, 0x2c000
	s_addc_u32 s23, s21, 0
	s_add_u32 s24, s22, 0x2c000
	s_addc_u32 s25, s23, 0
	s_mul_i32 s38, s64, 0xb0000
	s_add_u32 s26, s14, s38
	s_addc_u32 s27, s15, 0
	s_add_u32 s26, s26, 0x50a0000
	s_addc_u32 s27, s27, 0
	s_add_u32 s28, s26, 0x2c000
	s_addc_u32 s29, s27, 0
	s_add_u32 s30, s28, 0x2c000
	s_addc_u32 s31, s29, 0
	s_add_u32 s34, s30, 0x2c000
	s_addc_u32 s35, s31, 0
	v_and_b32_e32 v70, 15, v199
	v_bfe_u32 v71, v199, 4, 2
	v_lshrrev_b32_e32 v72, 1, v70
	v_xor_b32_e32 v71, v71, v72
	v_lshlrev_b32_e32 v71, 4, v71
	v_lshl_or_b32 v71, v70, 7, v71
	v_lshrrev_b32_e32 v72, 6, v199
	v_lshl_add_u32 v238, v72, 12, v71
	v_xor_b32_e32 v239, 64, v238
	v_add_u32_e32 v240, 0x4000, v71
	v_xor_b32_e32 v241, 64, v240
	v_readfirstlane_b32 s36, v141
	v_mov_b32_e32 v254, v64
	s_mov_b32 m0, s36
	s_nop 0
	global_load_lds_dwordx4 v254, s[18:19]
	s_add_u32 m0, m0, 0x1000
	s_nop 0
	global_load_lds_dwordx4 v254, s[20:21]
	s_add_u32 m0, m0, 0x1000
	s_nop 0
	global_load_lds_dwordx4 v254, s[22:23]
	s_add_u32 m0, m0, 0x1000
	s_nop 0
	global_load_lds_dwordx4 v254, s[24:25]
	s_add_u32 m0, m0, 0x1000
	s_nop 0
	global_load_lds_dwordx4 v254, s[26:27]
	s_add_u32 m0, m0, 0x1000
	s_nop 0
	global_load_lds_dwordx4 v254, s[28:29]
	s_add_u32 m0, m0, 0x1000
	s_nop 0
	global_load_lds_dwordx4 v254, s[30:31]
	s_add_u32 m0, m0, 0x1000
	s_nop 0
	global_load_lds_dwordx4 v254, s[34:35]
	v_add_u32_e32 v254, 0x80, v254
	s_add_u32 m0, s36, 0x8000
	s_nop 0
	global_load_lds_dwordx4 v254, s[18:19]
	s_add_u32 m0, m0, 0x1000
	s_nop 0
	global_load_lds_dwordx4 v254, s[20:21]
	s_add_u32 m0, m0, 0x1000
	s_nop 0
	global_load_lds_dwordx4 v254, s[22:23]
	s_add_u32 m0, m0, 0x1000
	s_nop 0
	global_load_lds_dwordx4 v254, s[24:25]
	s_add_u32 m0, m0, 0x1000
	s_nop 0
	global_load_lds_dwordx4 v254, s[26:27]
	s_add_u32 m0, m0, 0x1000
	s_nop 0
	global_load_lds_dwordx4 v254, s[28:29]
	s_add_u32 m0, m0, 0x1000
	s_nop 0
	global_load_lds_dwordx4 v254, s[30:31]
	s_add_u32 m0, m0, 0x1000
	s_nop 0
	global_load_lds_dwordx4 v254, s[34:35]
	v_add_u32_e32 v254, 0x80, v254
	v_mov_b32_e32 v48, 0
	v_mov_b32_e32 v49, 0
	v_mov_b32_e32 v50, 0
	v_mov_b32_e32 v51, 0
	v_mov_b32_e32 v52, 0
	v_mov_b32_e32 v53, 0
	v_mov_b32_e32 v54, 0
	v_mov_b32_e32 v55, 0
	v_mov_b32_e32 v56, 0
	v_mov_b32_e32 v57, 0
	v_mov_b32_e32 v58, 0
	v_mov_b32_e32 v59, 0
	v_mov_b32_e32 v60, 0
	v_mov_b32_e32 v61, 0
	v_mov_b32_e32 v62, 0
	v_mov_b32_e32 v63, 0
	v_mov_b32_e32 v32, 0
	v_mov_b32_e32 v33, 0
	v_mov_b32_e32 v34, 0
	v_mov_b32_e32 v35, 0
	v_mov_b32_e32 v36, 0
	v_mov_b32_e32 v37, 0
	v_mov_b32_e32 v38, 0
	v_mov_b32_e32 v39, 0
	v_mov_b32_e32 v40, 0
	v_mov_b32_e32 v41, 0
	v_mov_b32_e32 v42, 0
	v_mov_b32_e32 v43, 0
	v_mov_b32_e32 v44, 0
	v_mov_b32_e32 v45, 0
	v_mov_b32_e32 v46, 0
	v_mov_b32_e32 v47, 0
	v_mov_b32_e32 v16, 0
	v_mov_b32_e32 v17, 0
	v_mov_b32_e32 v18, 0
	v_mov_b32_e32 v19, 0
	v_mov_b32_e32 v20, 0
	v_mov_b32_e32 v21, 0
	v_mov_b32_e32 v22, 0
	v_mov_b32_e32 v23, 0
	v_mov_b32_e32 v24, 0
	v_mov_b32_e32 v25, 0
	v_mov_b32_e32 v26, 0
	v_mov_b32_e32 v27, 0
	v_mov_b32_e32 v28, 0
	v_mov_b32_e32 v29, 0
	v_mov_b32_e32 v30, 0
	v_mov_b32_e32 v31, 0
	v_mov_b32_e32 v0, 0
	v_mov_b32_e32 v1, 0
	v_mov_b32_e32 v2, 0
	v_mov_b32_e32 v3, 0
	v_mov_b32_e32 v4, 0
	v_mov_b32_e32 v5, 0
	v_mov_b32_e32 v6, 0
	v_mov_b32_e32 v7, 0
	v_mov_b32_e32 v8, 0
	v_mov_b32_e32 v9, 0
	v_mov_b32_e32 v10, 0
	v_mov_b32_e32 v11, 0
	v_mov_b32_e32 v12, 0
	v_mov_b32_e32 v13, 0
	v_mov_b32_e32 v14, 0
	v_mov_b32_e32 v15, 0
	s_mov_b32 s37, 21

.LBB0_1446:
	s_ashr_i32 s4, s3, 31
	s_lshr_b32 s4, s4, 25
	s_add_i32 s4, s3, s4
	s_ashr_i32 s60, s4, 7
	s_and_b32 s4, s4, 0xffffff80
	s_sub_i32 s77, s3, s4
	s_ashr_i32 s4, s77, 31
	s_lshr_b32 s4, s4, 29
	s_add_i32 s61, s77, s4
	s_and_b32 s4, s61, -8
	s_lshl_b32 s60, s60, 3
	s_sub_i32 s4, s77, s4
	s_add_i32 s4, s4, s60
	s_lshl_b32 s60, s61, 4
	s_lshl_b32 s62, s4, 7
	s_and_b32 s60, s60, 0xffffff80
	s_ashr_i32 s63, s62, 31
	s_ashr_i32 s61, s60, 31
	s_lshl_b64 s[64:65], s[62:63], 11
	s_lshl_b64 s[66:67], s[60:61], 11
	s_lshl_b32 s40, s62, 11
	s_add_u32 s20, s14, s40
	s_addc_u32 s21, s15, 0
	s_add_u32 s20, s20, 0x679f000
	s_addc_u32 s21, s21, 0
	s_add_u32 s22, s20, 0x10000
	s_addc_u32 s23, s21, 0
	s_add_u32 s24, s22, 0x10000
	s_addc_u32 s25, s23, 0
	s_add_u32 s26, s24, 0x10000
	s_addc_u32 s27, s25, 0
	s_lshl_b32 s40, s60, 11
	s_add_u32 s28, s14, s40
	s_addc_u32 s29, s15, 0
	s_add_u32 s28, s28, 0x12a0000
	s_addc_u32 s29, s29, 0
	s_add_u32 s30, s28, 0x10000
	s_addc_u32 s31, s29, 0
	s_add_u32 s34, s30, 0x10000
	s_addc_u32 s35, s31, 0
	s_add_u32 s36, s34, 0x10000
	s_addc_u32 s37, s35, 0
	v_and_b32_e32 v64, 15, v199
	v_bfe_u32 v65, v199, 4, 2
	v_lshrrev_b32_e32 v66, 1, v64
	v_xor_b32_e32 v65, v65, v66
	v_lshlrev_b32_e32 v65, 4, v65
	v_lshl_or_b32 v65, v64, 7, v65
	v_lshrrev_b32_e32 v66, 6, v199
	v_lshl_add_u32 v255, v66, 12, v65
	v_xor_b32_e32 v78, 64, v255
	v_add_u32_e32 v79, 0x4000, v65
	v_xor_b32_e32 v80, 64, v79
	v_readfirstlane_b32 s38, v97
	v_mov_b32_e32 v254, v76
	s_mov_b32 m0, s38
	s_nop 0
	global_load_lds_dwordx4 v254, s[20:21]
	s_add_u32 m0, m0, 0x1000
	s_nop 0
	global_load_lds_dwordx4 v254, s[22:23]
	s_add_u32 m0, m0, 0x1000
	s_nop 0
	global_load_lds_dwordx4 v254, s[24:25]
	s_add_u32 m0, m0, 0x1000
	s_nop 0
	global_load_lds_dwordx4 v254, s[26:27]
	s_add_u32 m0, m0, 0x1000
	s_nop 0
	global_load_lds_dwordx4 v254, s[28:29]
	s_add_u32 m0, m0, 0x1000
	s_nop 0
	global_load_lds_dwordx4 v254, s[30:31]
	s_add_u32 m0, m0, 0x1000
	s_nop 0
	global_load_lds_dwordx4 v254, s[34:35]
	s_add_u32 m0, m0, 0x1000
	s_nop 0
	global_load_lds_dwordx4 v254, s[36:37]
	v_add_u32_e32 v254, 0x80, v254
	s_add_u32 m0, s38, 0x8000
	s_nop 0
	global_load_lds_dwordx4 v254, s[20:21]
	s_add_u32 m0, m0, 0x1000
	s_nop 0
	global_load_lds_dwordx4 v254, s[22:23]
	s_add_u32 m0, m0, 0x1000
	s_nop 0
	global_load_lds_dwordx4 v254, s[24:25]
	s_add_u32 m0, m0, 0x1000
	s_nop 0
	global_load_lds_dwordx4 v254, s[26:27]
	s_add_u32 m0, m0, 0x1000
	s_nop 0
	global_load_lds_dwordx4 v254, s[28:29]
	s_add_u32 m0, m0, 0x1000
	s_nop 0
	global_load_lds_dwordx4 v254, s[30:31]
	s_add_u32 m0, m0, 0x1000
	s_nop 0
	global_load_lds_dwordx4 v254, s[34:35]
	s_add_u32 m0, m0, 0x1000
	s_nop 0
	global_load_lds_dwordx4 v254, s[36:37]
	v_add_u32_e32 v254, 0x80, v254
	v_mov_b32_e32 v48, 0
	v_mov_b32_e32 v49, 0
	v_mov_b32_e32 v50, 0
	v_mov_b32_e32 v51, 0
	v_mov_b32_e32 v52, 0
	v_mov_b32_e32 v53, 0
	v_mov_b32_e32 v54, 0
	v_mov_b32_e32 v55, 0
	v_mov_b32_e32 v56, 0
	v_mov_b32_e32 v57, 0
	v_mov_b32_e32 v58, 0
	v_mov_b32_e32 v59, 0
	v_mov_b32_e32 v60, 0
	v_mov_b32_e32 v61, 0
	v_mov_b32_e32 v62, 0
	v_mov_b32_e32 v63, 0
	v_mov_b32_e32 v32, 0
	v_mov_b32_e32 v33, 0
	v_mov_b32_e32 v34, 0
	v_mov_b32_e32 v35, 0
	v_mov_b32_e32 v36, 0
	v_mov_b32_e32 v37, 0
	v_mov_b32_e32 v38, 0
	v_mov_b32_e32 v39, 0
	v_mov_b32_e32 v40, 0
	v_mov_b32_e32 v41, 0
	v_mov_b32_e32 v42, 0
	v_mov_b32_e32 v43, 0
	v_mov_b32_e32 v44, 0
	v_mov_b32_e32 v45, 0
	v_mov_b32_e32 v46, 0
	v_mov_b32_e32 v47, 0
	v_mov_b32_e32 v16, 0
	v_mov_b32_e32 v17, 0
	v_mov_b32_e32 v18, 0
	v_mov_b32_e32 v19, 0
	v_mov_b32_e32 v20, 0
	v_mov_b32_e32 v21, 0
	v_mov_b32_e32 v22, 0
	v_mov_b32_e32 v23, 0
	v_mov_b32_e32 v24, 0
	v_mov_b32_e32 v25, 0
	v_mov_b32_e32 v26, 0
	v_mov_b32_e32 v27, 0
	v_mov_b32_e32 v28, 0
	v_mov_b32_e32 v29, 0
	v_mov_b32_e32 v30, 0
	v_mov_b32_e32 v31, 0
	v_mov_b32_e32 v0, 0
	v_mov_b32_e32 v1, 0
	v_mov_b32_e32 v2, 0
	v_mov_b32_e32 v3, 0
	v_mov_b32_e32 v4, 0
	v_mov_b32_e32 v5, 0
	v_mov_b32_e32 v6, 0
	v_mov_b32_e32 v7, 0
	v_mov_b32_e32 v8, 0
	v_mov_b32_e32 v9, 0
	v_mov_b32_e32 v10, 0
	v_mov_b32_e32 v11, 0
	v_mov_b32_e32 v12, 0
	v_mov_b32_e32 v13, 0
	v_mov_b32_e32 v14, 0
	v_mov_b32_e32 v15, 0
	s_mov_b32 s39, 7
.Lgk_loop_p19:
	s_waitcnt vmcnt(8)
	s_barrier
	ds_read_b128 v[64:67], v255
	ds_read_b128 v[68:71], v255 offset:2048
	ds_read_b128 v[86:89], v79
	ds_read_b128 v[90:93], v79 offset:2048
	ds_read_b128 v[122:125], v79 offset:4096
	ds_read_b128 v[126:129], v79 offset:6144
	ds_read_b128 v[130:133], v79 offset:8192
	ds_read_b128 v[134:137], v79 offset:10240
	ds_read_b128 v[138:141], v79 offset:12288
	ds_read_b128 v[218:221], v79 offset:14336
	ds_read_b128 v[72:75], v78
	ds_read_b128 v[82:85], v78 offset:2048
	ds_read_b128 v[222:225], v80
	ds_read_b128 v[226:229], v80 offset:2048
	ds_read_b128 v[230:233], v80 offset:4096
	ds_read_b128 v[234:237], v80 offset:6144
	ds_read_b128 v[238:241], v80 offset:8192
	ds_read_b128 v[242:245], v80 offset:10240
	ds_read_b128 v[246:249], v80 offset:12288
	ds_read_b128 v[250:253], v80 offset:14336
	s_waitcnt lgkmcnt(0)
	s_barrier
	s_mov_b32 m0, s38
	s_setprio 1
	v_mfma_f32_16x16x32_bf16 v[0:3], v[64:67], v[86:89], v[0:3]
	v_mfma_f32_16x16x32_bf16 v[4:7], v[64:67], v[90:93], v[4:7]
	v_mfma_f32_16x16x32_bf16 v[8:11], v[64:67], v[122:125], v[8:11]
	v_mfma_f32_16x16x32_bf16 v[12:15], v[64:67], v[126:129], v[12:15]
	global_load_lds_dwordx4 v254, s[20:21]
	s_add_u32 m0, m0, 0x1000
	v_mfma_f32_16x16x32_bf16 v[16:19], v[64:67], v[130:133], v[16:19]
	v_mfma_f32_16x16x32_bf16 v[20:23], v[64:67], v[134:137], v[20:23]
	v_mfma_f32_16x16x32_bf16 v[24:27], v[64:67], v[138:141], v[24:27]
	v_mfma_f32_16x16x32_bf16 v[28:31], v[64:67], v[218:221], v[28:31]
	global_load_lds_dwordx4 v254, s[22:23]
	s_add_u32 m0, m0, 0x1000
	v_mfma_f32_16x16x32_bf16 v[32:35], v[68:71], v[86:89], v[32:35]
	v_mfma_f32_16x16x32_bf16 v[36:39], v[68:71], v[90:93], v[36:39]
	v_mfma_f32_16x16x32_bf16 v[40:43], v[68:71], v[122:125], v[40:43]
	v_mfma_f32_16x16x32_bf16 v[44:47], v[68:71], v[126:129], v[44:47]
	global_load_lds_dwordx4 v254, s[24:25]
	s_add_u32 m0, m0, 0x1000
	v_mfma_f32_16x16x32_bf16 v[48:51], v[68:71], v[130:133], v[48:51]
	v_mfma_f32_16x16x32_bf16 v[52:55], v[68:71], v[134:137], v[52:55]
	v_mfma_f32_16x16x32_bf16 v[56:59], v[68:71], v[138:141], v[56:59]
	v_mfma_f32_16x16x32_bf16 v[60:63], v[68:71], v[218:221], v[60:63]
	global_load_lds_dwordx4 v254, s[26:27]
	s_add_u32 m0, m0, 0x1000
	v_mfma_f32_16x16x32_bf16 v[0:3], v[72:75], v[222:225], v[0:3]
	v_mfma_f32_16x16x32_bf16 v[4:7], v[72:75], v[226:229], v[4:7]
	v_mfma_f32_16x16x32_bf16 v[8:11], v[72:75], v[230:233], v[8:11]
	v_mfma_f32_16x16x32_bf16 v[12:15], v[72:75], v[234:237], v[12:15]
	global_load_lds_dwordx4 v254, s[28:29]
	s_add_u32 m0, m0, 0x1000
	v_mfma_f32_16x16x32_bf16 v[16:19], v[72:75], v[238:241], v[16:19]
	v_mfma_f32_16x16x32_bf16 v[20:23], v[72:75], v[242:245], v[20:23]
	v_mfma_f32_16x16x32_bf16 v[24:27], v[72:75], v[246:249], v[24:27]
	v_mfma_f32_16x16x32_bf16 v[28:31], v[72:75], v[250:253], v[28:31]
	global_load_lds_dwordx4 v254, s[30:31]
	s_add_u32 m0, m0, 0x1000
	v_mfma_f32_16x16x32_bf16 v[32:35], v[82:85], v[222:225], v[32:35]
	v_mfma_f32_16x16x32_bf16 v[36:39], v[82:85], v[226:229], v[36:39]
	v_mfma_f32_16x16x32_bf16 v[40:43], v[82:85], v[230:233], v[40:43]
	v_mfma_f32_16x16x32_bf16 v[44:47], v[82:85], v[234:237], v[44:47]
	global_load_lds_dwordx4 v254, s[34:35]
	s_add_u32 m0, m0, 0x1000
	v_mfma_f32_16x16x32_bf16 v[48:51], v[82:85], v[238:241], v[48:51]
	v_mfma_f32_16x16x32_bf16 v[52:55], v[82:85], v[242:245], v[52:55]
	v_mfma_f32_16x16x32_bf16 v[56:59], v[82:85], v[246:249], v[56:59]
	v_mfma_f32_16x16x32_bf16 v[60:63], v[82:85], v[250:253], v[60:63]
	global_load_lds_dwordx4 v254, s[36:37]
	s_setprio 0
	v_add_u32_e32 v254, 0x80, v254
	s_waitcnt vmcnt(8)
	s_barrier
	ds_read_b128 v[64:67], v255 offset:32768
	ds_read_b128 v[68:71], v255 offset:34816
	ds_read_b128 v[86:89], v79 offset:32768
	ds_read_b128 v[90:93], v79 offset:34816
	ds_read_b128 v[122:125], v79 offset:36864
	ds_read_b128 v[126:129], v79 offset:38912
	ds_read_b128 v[130:133], v79 offset:40960
	ds_read_b128 v[134:137], v79 offset:43008
	ds_read_b128 v[138:141], v79 offset:45056
	ds_read_b128 v[218:221], v79 offset:47104
	ds_read_b128 v[72:75], v78 offset:32768
	ds_read_b128 v[82:85], v78 offset:34816
	ds_read_b128 v[222:225], v80 offset:32768
	ds_read_b128 v[226:229], v80 offset:34816
	ds_read_b128 v[230:233], v80 offset:36864
	ds_read_b128 v[234:237], v80 offset:38912
	ds_read_b128 v[238:241], v80 offset:40960
	ds_read_b128 v[242:245], v80 offset:43008
	ds_read_b128 v[246:249], v80 offset:45056
	ds_read_b128 v[250:253], v80 offset:47104
	s_waitcnt lgkmcnt(0)
	s_barrier
	s_add_u32 m0, s38, 0x8000
	s_setprio 1
	v_mfma_f32_16x16x32_bf16 v[0:3], v[64:67], v[86:89], v[0:3]
	v_mfma_f32_16x16x32_bf16 v[4:7], v[64:67], v[90:93], v[4:7]
	v_mfma_f32_16x16x32_bf16 v[8:11], v[64:67], v[122:125], v[8:11]
	v_mfma_f32_16x16x32_bf16 v[12:15], v[64:67], v[126:129], v[12:15]
	global_load_lds_dwordx4 v254, s[20:21]
	s_add_u32 m0, m0, 0x1000
	v_mfma_f32_16x16x32_bf16 v[16:19], v[64:67], v[130:133], v[16:19]
	v_mfma_f32_16x16x32_bf16 v[20:23], v[64:67], v[134:137], v[20:23]
	v_mfma_f32_16x16x32_bf16 v[24:27], v[64:67], v[138:141], v[24:27]
	v_mfma_f32_16x16x32_bf16 v[28:31], v[64:67], v[218:221], v[28:31]
	global_load_lds_dwordx4 v254, s[22:23]
	s_add_u32 m0, m0, 0x1000
	v_mfma_f32_16x16x32_bf16 v[32:35], v[68:71], v[86:89], v[32:35]
	v_mfma_f32_16x16x32_bf16 v[36:39], v[68:71], v[90:93], v[36:39]
	v_mfma_f32_16x16x32_bf16 v[40:43], v[68:71], v[122:125], v[40:43]
	v_mfma_f32_16x16x32_bf16 v[44:47], v[68:71], v[126:129], v[44:47]
	global_load_lds_dwordx4 v254, s[24:25]
	s_add_u32 m0, m0, 0x1000
	v_mfma_f32_16x16x32_bf16 v[48:51], v[68:71], v[130:133], v[48:51]
	v_mfma_f32_16x16x32_bf16 v[52:55], v[68:71], v[134:137], v[52:55]
	v_mfma_f32_16x16x32_bf16 v[56:59], v[68:71], v[138:141], v[56:59]
	v_mfma_f32_16x16x32_bf16 v[60:63], v[68:71], v[218:221], v[60:63]
	global_load_lds_dwordx4 v254, s[26:27]
	s_add_u32 m0, m0, 0x1000
	v_mfma_f32_16x16x32_bf16 v[0:3], v[72:75], v[222:225], v[0:3]
	v_mfma_f32_16x16x32_bf16 v[4:7], v[72:75], v[226:229], v[4:7]
	v_mfma_f32_16x16x32_bf16 v[8:11], v[72:75], v[230:233], v[8:11]
	v_mfma_f32_16x16x32_bf16 v[12:15], v[72:75], v[234:237], v[12:15]
	global_load_lds_dwordx4 v254, s[28:29]
	s_add_u32 m0, m0, 0x1000
	v_mfma_f32_16x16x32_bf16 v[16:19], v[72:75], v[238:241], v[16:19]
	v_mfma_f32_16x16x32_bf16 v[20:23], v[72:75], v[242:245], v[20:23]
	v_mfma_f32_16x16x32_bf16 v[24:27], v[72:75], v[246:249], v[24:27]
	v_mfma_f32_16x16x32_bf16 v[28:31], v[72:75], v[250:253], v[28:31]
	global_load_lds_dwordx4 v254, s[30:31]
	s_add_u32 m0, m0, 0x1000
	v_mfma_f32_16x16x32_bf16 v[32:35], v[82:85], v[222:225], v[32:35]
	v_mfma_f32_16x16x32_bf16 v[36:39], v[82:85], v[226:229], v[36:39]
	v_mfma_f32_16x16x32_bf16 v[40:43], v[82:85], v[230:233], v[40:43]
	v_mfma_f32_16x16x32_bf16 v[44:47], v[82:85], v[234:237], v[44:47]
	global_load_lds_dwordx4 v254, s[34:35]
	s_add_u32 m0, m0, 0x1000
	v_mfma_f32_16x16x32_bf16 v[48:51], v[82:85], v[238:241], v[48:51]
	v_mfma_f32_16x16x32_bf16 v[52:55], v[82:85], v[242:245], v[52:55]
	v_mfma_f32_16x16x32_bf16 v[56:59], v[82:85], v[246:249], v[56:59]
	v_mfma_f32_16x16x32_bf16 v[60:63], v[82:85], v[250:253], v[60:63]
	global_load_lds_dwordx4 v254, s[36:37]
	s_setprio 0
	v_add_u32_e32 v254, 0x80, v254
	s_sub_u32 s39, s39, 1
	s_cmp_lg_u32 s39, 0
	s_cbranch_scc1 .Lgk_loop_p19
	s_waitcnt vmcnt(8)
	s_barrier
	ds_read_b128 v[64:67], v255
	ds_read_b128 v[68:71], v255 offset:2048
	ds_read_b128 v[86:89], v79
	ds_read_b128 v[90:93], v79 offset:2048
	ds_read_b128 v[122:125], v79 offset:4096
	ds_read_b128 v[126:129], v79 offset:6144
	ds_read_b128 v[130:133], v79 offset:8192
	ds_read_b128 v[134:137], v79 offset:10240
	ds_read_b128 v[138:141], v79 offset:12288
	ds_read_b128 v[218:221], v79 offset:14336
	ds_read_b128 v[72:75], v78
	ds_read_b128 v[82:85], v78 offset:2048
	ds_read_b128 v[222:225], v80
	ds_read_b128 v[226:229], v80 offset:2048
	ds_read_b128 v[230:233], v80 offset:4096
	ds_read_b128 v[234:237], v80 offset:6144
	ds_read_b128 v[238:241], v80 offset:8192
	ds_read_b128 v[242:245], v80 offset:10240
	ds_read_b128 v[246:249], v80 offset:12288
	ds_read_b128 v[250:253], v80 offset:14336
	s_waitcnt lgkmcnt(0)
	s_barrier
	s_setprio 1
	v_mfma_f32_16x16x32_bf16 v[0:3], v[64:67], v[86:89], v[0:3]
	v_mfma_f32_16x16x32_bf16 v[4:7], v[64:67], v[90:93], v[4:7]
	v_mfma_f32_16x16x32_bf16 v[8:11], v[64:67], v[122:125], v[8:11]
	v_mfma_f32_16x16x32_bf16 v[12:15], v[64:67], v[126:129], v[12:15]
	v_mfma_f32_16x16x32_bf16 v[16:19], v[64:67], v[130:133], v[16:19]
	v_mfma_f32_16x16x32_bf16 v[20:23], v[64:67], v[134:137], v[20:23]
	v_mfma_f32_16x16x32_bf16 v[24:27], v[64:67], v[138:141], v[24:27]
	v_mfma_f32_16x16x32_bf16 v[28:31], v[64:67], v[218:221], v[28:31]
	v_mfma_f32_16x16x32_bf16 v[32:35], v[68:71], v[86:89], v[32:35]
	v_mfma_f32_16x16x32_bf16 v[36:39], v[68:71], v[90:93], v[36:39]
	v_mfma_f32_16x16x32_bf16 v[40:43], v[68:71], v[122:125], v[40:43]
	v_mfma_f32_16x16x32_bf16 v[44:47], v[68:71], v[126:129], v[44:47]
	v_mfma_f32_16x16x32_bf16 v[48:51], v[68:71], v[130:133], v[48:51]
	v_mfma_f32_16x16x32_bf16 v[52:55], v[68:71], v[134:137], v[52:55]
	v_mfma_f32_16x16x32_bf16 v[56:59], v[68:71], v[138:141], v[56:59]
	v_mfma_f32_16x16x32_bf16 v[60:63], v[68:71], v[218:221], v[60:63]
	v_mfma_f32_16x16x32_bf16 v[0:3], v[72:75], v[222:225], v[0:3]
	v_mfma_f32_16x16x32_bf16 v[4:7], v[72:75], v[226:229], v[4:7]
	v_mfma_f32_16x16x32_bf16 v[8:11], v[72:75], v[230:233], v[8:11]
	v_mfma_f32_16x16x32_bf16 v[12:15], v[72:75], v[234:237], v[12:15]
	v_mfma_f32_16x16x32_bf16 v[16:19], v[72:75], v[238:241], v[16:19]
	v_mfma_f32_16x16x32_bf16 v[20:23], v[72:75], v[242:245], v[20:23]
	v_mfma_f32_16x16x32_bf16 v[24:27], v[72:75], v[246:249], v[24:27]
	v_mfma_f32_16x16x32_bf16 v[28:31], v[72:75], v[250:253], v[28:31]
	v_mfma_f32_16x16x32_bf16 v[32:35], v[82:85], v[222:225], v[32:35]
	v_mfma_f32_16x16x32_bf16 v[36:39], v[82:85], v[226:229], v[36:39]
	v_mfma_f32_16x16x32_bf16 v[40:43], v[82:85], v[230:233], v[40:43]
	v_mfma_f32_16x16x32_bf16 v[44:47], v[82:85], v[234:237], v[44:47]
	v_mfma_f32_16x16x32_bf16 v[48:51], v[82:85], v[238:241], v[48:51]
	v_mfma_f32_16x16x32_bf16 v[52:55], v[82:85], v[242:245], v[52:55]
	v_mfma_f32_16x16x32_bf16 v[56:59], v[82:85], v[246:249], v[56:59]
	v_mfma_f32_16x16x32_bf16 v[60:63], v[82:85], v[250:253], v[60:63]
	s_setprio 0
	s_waitcnt vmcnt(0)
	s_barrier
	ds_read_b128 v[64:67], v255 offset:32768
	ds_read_b128 v[68:71], v255 offset:34816
	ds_read_b128 v[86:89], v79 offset:32768
	ds_read_b128 v[90:93], v79 offset:34816
	ds_read_b128 v[122:125], v79 offset:36864
	ds_read_b128 v[126:129], v79 offset:38912
	ds_read_b128 v[130:133], v79 offset:40960
	ds_read_b128 v[134:137], v79 offset:43008
	ds_read_b128 v[138:141], v79 offset:45056
	ds_read_b128 v[218:221], v79 offset:47104
	ds_read_b128 v[72:75], v78 offset:32768
	ds_read_b128 v[82:85], v78 offset:34816
	ds_read_b128 v[222:225], v80 offset:32768
	ds_read_b128 v[226:229], v80 offset:34816
	ds_read_b128 v[230:233], v80 offset:36864
	ds_read_b128 v[234:237], v80 offset:38912
	ds_read_b128 v[238:241], v80 offset:40960
	ds_read_b128 v[242:245], v80 offset:43008
	ds_read_b128 v[246:249], v80 offset:45056
	ds_read_b128 v[250:253], v80 offset:47104
	s_waitcnt lgkmcnt(0)
	s_barrier
	s_setprio 1
	v_mfma_f32_16x16x32_bf16 v[0:3], v[64:67], v[86:89], v[0:3]
	v_mfma_f32_16x16x32_bf16 v[4:7], v[64:67], v[90:93], v[4:7]
	v_mfma_f32_16x16x32_bf16 v[8:11], v[64:67], v[122:125], v[8:11]
	v_mfma_f32_16x16x32_bf16 v[12:15], v[64:67], v[126:129], v[12:15]
	v_mfma_f32_16x16x32_bf16 v[16:19], v[64:67], v[130:133], v[16:19]
	v_mfma_f32_16x16x32_bf16 v[20:23], v[64:67], v[134:137], v[20:23]
	v_mfma_f32_16x16x32_bf16 v[24:27], v[64:67], v[138:141], v[24:27]
	v_mfma_f32_16x16x32_bf16 v[28:31], v[64:67], v[218:221], v[28:31]
	v_mfma_f32_16x16x32_bf16 v[32:35], v[68:71], v[86:89], v[32:35]
	v_mfma_f32_16x16x32_bf16 v[36:39], v[68:71], v[90:93], v[36:39]
	v_mfma_f32_16x16x32_bf16 v[40:43], v[68:71], v[122:125], v[40:43]
	v_mfma_f32_16x16x32_bf16 v[44:47], v[68:71], v[126:129], v[44:47]
	v_mfma_f32_16x16x32_bf16 v[48:51], v[68:71], v[130:133], v[48:51]
	v_mfma_f32_16x16x32_bf16 v[52:55], v[68:71], v[134:137], v[52:55]
	v_mfma_f32_16x16x32_bf16 v[56:59], v[68:71], v[138:141], v[56:59]
	v_mfma_f32_16x16x32_bf16 v[60:63], v[68:71], v[218:221], v[60:63]
	v_mfma_f32_16x16x32_bf16 v[0:3], v[72:75], v[222:225], v[0:3]
	v_mfma_f32_16x16x32_bf16 v[4:7], v[72:75], v[226:229], v[4:7]
	v_mfma_f32_16x16x32_bf16 v[8:11], v[72:75], v[230:233], v[8:11]
	v_mfma_f32_16x16x32_bf16 v[12:15], v[72:75], v[234:237], v[12:15]
	v_mfma_f32_16x16x32_bf16 v[16:19], v[72:75], v[238:241], v[16:19]
	v_mfma_f32_16x16x32_bf16 v[20:23], v[72:75], v[242:245], v[20:23]
	v_mfma_f32_16x16x32_bf16 v[24:27], v[72:75], v[246:249], v[24:27]
	v_mfma_f32_16x16x32_bf16 v[28:31], v[72:75], v[250:253], v[28:31]
	v_mfma_f32_16x16x32_bf16 v[32:35], v[82:85], v[222:225], v[32:35]
	v_mfma_f32_16x16x32_bf16 v[36:39], v[82:85], v[226:229], v[36:39]
	v_mfma_f32_16x16x32_bf16 v[40:43], v[82:85], v[230:233], v[40:43]
	v_mfma_f32_16x16x32_bf16 v[44:47], v[82:85], v[234:237], v[44:47]
	v_mfma_f32_16x16x32_bf16 v[48:51], v[82:85], v[238:241], v[48:51]
	v_mfma_f32_16x16x32_bf16 v[52:55], v[82:85], v[242:245], v[52:55]
	v_mfma_f32_16x16x32_bf16 v[56:59], v[82:85], v[246:249], v[56:59]
	v_mfma_f32_16x16x32_bf16 v[60:63], v[82:85], v[250:253], v[60:63]
	s_setprio 0
	s_nop 7
	s_nop 7
	v_and_b32_e32 v66, 63, v199
	v_lshrrev_b32_e32 v67, 6, v199
	v_lshlrev_b32_e32 v67, 14, v67
	v_lshl_add_u32 v64, v66, 4, v67
	v_and_b32_e32 v65, 15, v66
	v_lshl_add_u32 v65, v65, 4, v67
	v_bfe_u32 v67, v66, 4, 1
	v_lshl_add_u32 v65, v67, 10, v65
	v_bfe_u32 v67, v66, 5, 1
	v_lshl_add_u32 v65, v67, 8, v65
	ds_write_b128 v64, v[0:3]
	ds_write_b128 v64, v[4:7] offset:1024
	ds_write_b128 v64, v[8:11] offset:2048
	ds_write_b128 v64, v[12:15] offset:3072
	ds_write_b128 v64, v[16:19] offset:4096
	ds_write_b128 v64, v[20:23] offset:5120
	ds_write_b128 v64, v[24:27] offset:6144
	ds_write_b128 v64, v[28:31] offset:7168
	ds_write_b128 v64, v[32:35] offset:8192
	ds_write_b128 v64, v[36:39] offset:9216
	ds_write_b128 v64, v[40:43] offset:10240
	ds_write_b128 v64, v[44:47] offset:11264
	ds_write_b128 v64, v[48:51] offset:12288
	ds_write_b128 v64, v[52:55] offset:13312
	ds_write_b128 v64, v[56:59] offset:14336
	ds_write_b128 v64, v[60:63] offset:15360
	s_waitcnt lgkmcnt(0)
	ds_read_b128 v[48:51], v65
	ds_read_b128 v[52:55], v65 offset:512
	ds_read_b128 v[56:59], v65 offset:8192
	ds_read_b128 v[60:63], v65 offset:8704
	ds_read_b128 v[32:35], v65 offset:2048
	ds_read_b128 v[36:39], v65 offset:2560
	ds_read_b128 v[40:43], v65 offset:10240
	ds_read_b128 v[44:47], v65 offset:10752
	ds_read_b128 v[16:19], v65 offset:4096
	ds_read_b128 v[20:23], v65 offset:4608
	ds_read_b128 v[24:27], v65 offset:12288
	ds_read_b128 v[28:31], v65 offset:12800
	ds_read_b128 v[0:3], v65 offset:6144
	ds_read_b128 v[4:7], v65 offset:6656
	ds_read_b128 v[8:11], v65 offset:14336
	ds_read_b128 v[12:15], v65 offset:14848
	s_waitcnt lgkmcnt(0)
	s_barrier
	s_branch .LBB0_1450

.LBB0_1565:
	s_ashr_i32 s6, s3, 31
	s_lshr_b32 s6, s6, 26
	s_add_i32 s6, s3, s6
	s_ashr_i32 s58, s6, 6
	s_andn2_b32 s6, s6, 63
	s_sub_i32 s6, s3, s6
	s_ashr_i32 s59, s6, 31
	s_lshr_b32 s59, s59, 29
	s_add_i32 s59, s6, s59
	s_ashr_i32 s64, s59, 3
	s_and_b32 s59, s59, -8
	s_lshl_b32 s58, s58, 3
	s_sub_i32 s6, s6, s59
	s_add_i32 s6, s6, s58
	s_lshl_b32 s66, s6, 7
	s_ashr_i32 s67, s66, 31
	s_lshl_b32 s68, s64, 7
	s_lshl_b64 s[58:59], s[66:67], 11
	s_ashr_i32 s69, s68, 31
	s_lshl_b32 s38, s66, 11
	s_add_u32 s18, s14, s38
	s_addc_u32 s19, s15, 0
	s_add_u32 s18, s18, 0xdf9f000
	s_addc_u32 s19, s19, 0
	s_add_u32 s20, s18, 0x10000
	s_addc_u32 s21, s19, 0
	s_add_u32 s22, s20, 0x10000
	s_addc_u32 s23, s21, 0
	s_add_u32 s24, s22, 0x10000
	s_addc_u32 s25, s23, 0
	s_lshl_b32 s38, s68, 11
	s_add_u32 s26, s14, s38
	s_addc_u32 s27, s15, 0
	s_add_u32 s26, s26, 0x17a0000
	s_addc_u32 s27, s27, 0
	s_add_u32 s28, s26, 0x10000
	s_addc_u32 s29, s27, 0
	s_add_u32 s30, s28, 0x10000
	s_addc_u32 s31, s29, 0
	s_add_u32 s34, s30, 0x10000
	s_addc_u32 s35, s31, 0
	v_and_b32_e32 v70, 15, v199
	v_bfe_u32 v71, v199, 4, 2
	v_lshrrev_b32_e32 v72, 1, v70
	v_xor_b32_e32 v71, v71, v72
	v_lshlrev_b32_e32 v71, 4, v71
	v_lshl_or_b32 v71, v70, 7, v71
	v_lshrrev_b32_e32 v72, 6, v199
	v_lshl_add_u32 v198, v72, 12, v71
	v_xor_b32_e32 v238, 64, v198
	v_add_u32_e32 v239, 0x4000, v71
	v_xor_b32_e32 v240, 64, v239
	v_readfirstlane_b32 s36, v140
	v_mov_b32_e32 v254, v64
	s_mov_b32 m0, s36
	s_nop 0
	global_load_lds_dwordx4 v254, s[18:19]
	s_add_u32 m0, m0, 0x1000
	s_nop 0
	global_load_lds_dwordx4 v254, s[20:21]
	s_add_u32 m0, m0, 0x1000
	s_nop 0
	global_load_lds_dwordx4 v254, s[22:23]
	s_add_u32 m0, m0, 0x1000
	s_nop 0
	global_load_lds_dwordx4 v254, s[24:25]
	s_add_u32 m0, m0, 0x1000
	s_nop 0
	global_load_lds_dwordx4 v254, s[26:27]
	s_add_u32 m0, m0, 0x1000
	s_nop 0
	global_load_lds_dwordx4 v254, s[28:29]
	s_add_u32 m0, m0, 0x1000
	s_nop 0
	global_load_lds_dwordx4 v254, s[30:31]
	s_add_u32 m0, m0, 0x1000
	s_nop 0
	global_load_lds_dwordx4 v254, s[34:35]
	v_add_u32_e32 v254, 0x80, v254
	s_add_u32 m0, s36, 0x8000
	s_nop 0
	global_load_lds_dwordx4 v254, s[18:19]
	s_add_u32 m0, m0, 0x1000
	s_nop 0
	global_load_lds_dwordx4 v254, s[20:21]
	s_add_u32 m0, m0, 0x1000
	s_nop 0
	global_load_lds_dwordx4 v254, s[22:23]
	s_add_u32 m0, m0, 0x1000
	s_nop 0
	global_load_lds_dwordx4 v254, s[24:25]
	s_add_u32 m0, m0, 0x1000
	s_nop 0
	global_load_lds_dwordx4 v254, s[26:27]
	s_add_u32 m0, m0, 0x1000
	s_nop 0
	global_load_lds_dwordx4 v254, s[28:29]
	s_add_u32 m0, m0, 0x1000
	s_nop 0
	global_load_lds_dwordx4 v254, s[30:31]
	s_add_u32 m0, m0, 0x1000
	s_nop 0
	global_load_lds_dwordx4 v254, s[34:35]
	v_add_u32_e32 v254, 0x80, v254
	v_mov_b32_e32 v48, 0
	v_mov_b32_e32 v49, 0
	v_mov_b32_e32 v50, 0
	v_mov_b32_e32 v51, 0
	v_mov_b32_e32 v52, 0
	v_mov_b32_e32 v53, 0
	v_mov_b32_e32 v54, 0
	v_mov_b32_e32 v55, 0
	v_mov_b32_e32 v56, 0
	v_mov_b32_e32 v57, 0
	v_mov_b32_e32 v58, 0
	v_mov_b32_e32 v59, 0
	v_mov_b32_e32 v60, 0
	v_mov_b32_e32 v61, 0
	v_mov_b32_e32 v62, 0
	v_mov_b32_e32 v63, 0
	v_mov_b32_e32 v32, 0
	v_mov_b32_e32 v33, 0
	v_mov_b32_e32 v34, 0
	v_mov_b32_e32 v35, 0
	v_mov_b32_e32 v36, 0
	v_mov_b32_e32 v37, 0
	v_mov_b32_e32 v38, 0
	v_mov_b32_e32 v39, 0
	v_mov_b32_e32 v40, 0
	v_mov_b32_e32 v41, 0
	v_mov_b32_e32 v42, 0
	v_mov_b32_e32 v43, 0
	v_mov_b32_e32 v44, 0
	v_mov_b32_e32 v45, 0
	v_mov_b32_e32 v46, 0
	v_mov_b32_e32 v47, 0
	v_mov_b32_e32 v16, 0
	v_mov_b32_e32 v17, 0
	v_mov_b32_e32 v18, 0
	v_mov_b32_e32 v19, 0
	v_mov_b32_e32 v20, 0
	v_mov_b32_e32 v21, 0
	v_mov_b32_e32 v22, 0
	v_mov_b32_e32 v23, 0
	v_mov_b32_e32 v24, 0
	v_mov_b32_e32 v25, 0
	v_mov_b32_e32 v26, 0
	v_mov_b32_e32 v27, 0
	v_mov_b32_e32 v28, 0
	v_mov_b32_e32 v29, 0
	v_mov_b32_e32 v30, 0
	v_mov_b32_e32 v31, 0
	v_mov_b32_e32 v0, 0
	v_mov_b32_e32 v1, 0
	v_mov_b32_e32 v2, 0
	v_mov_b32_e32 v3, 0
	v_mov_b32_e32 v4, 0
	v_mov_b32_e32 v5, 0
	v_mov_b32_e32 v6, 0
	v_mov_b32_e32 v7, 0
	v_mov_b32_e32 v8, 0
	v_mov_b32_e32 v9, 0
	v_mov_b32_e32 v10, 0
	v_mov_b32_e32 v11, 0
	v_mov_b32_e32 v12, 0
	v_mov_b32_e32 v13, 0
	v_mov_b32_e32 v14, 0
	v_mov_b32_e32 v15, 0
	s_mov_b32 s37, 7

.Lmap_done_3:
	s_lshl_b32 s60, s4, 7
	s_lshl_b32 s58, s76, 7
	s_ashr_i32 s61, s60, 31
	s_ashr_i32 s59, s58, 31
	s_lshl_b64 s[62:63], s[60:61], 11
	s_lshl_b64 s[64:65], s[58:59], 11
	s_lshl_b32 s38, s60, 11
	s_add_u32 s18, s14, s38
	s_addc_u32 s19, s15, 0
	s_add_u32 s18, s18, 0x679f000
	s_addc_u32 s19, s19, 0
	s_add_u32 s20, s18, 0x10000
	s_addc_u32 s21, s19, 0
	s_add_u32 s22, s20, 0x10000
	s_addc_u32 s23, s21, 0
	s_add_u32 s24, s22, 0x10000
	s_addc_u32 s25, s23, 0
	s_lshl_b32 s38, s58, 11
	s_add_u32 s26, s14, s38
	s_addc_u32 s27, s15, 0
	s_add_u32 s26, s26, 0x3aa0000
	s_addc_u32 s27, s27, 0
	s_add_u32 s28, s26, 0x10000
	s_addc_u32 s29, s27, 0
	s_add_u32 s30, s28, 0x10000
	s_addc_u32 s31, s29, 0
	s_add_u32 s34, s30, 0x10000
	s_addc_u32 s35, s31, 0
	v_and_b32_e32 v64, 15, v199
	v_bfe_u32 v65, v199, 4, 2
	v_lshrrev_b32_e32 v66, 1, v64
	v_xor_b32_e32 v65, v65, v66
	v_lshlrev_b32_e32 v65, 4, v65
	v_lshl_or_b32 v65, v64, 7, v65
	v_lshrrev_b32_e32 v66, 6, v199
	v_lshl_add_u32 v217, v66, 12, v65
	v_xor_b32_e32 v255, 64, v217
	v_add_u32_e32 v78, 0x4000, v65
	v_xor_b32_e32 v79, 64, v78
	v_readfirstlane_b32 s36, v94
	v_mov_b32_e32 v254, v76
	s_mov_b32 m0, s36
	s_nop 0
	global_load_lds_dwordx4 v254, s[18:19]
	s_add_u32 m0, m0, 0x1000
	s_nop 0
	global_load_lds_dwordx4 v254, s[20:21]
	s_add_u32 m0, m0, 0x1000
	s_nop 0
	global_load_lds_dwordx4 v254, s[22:23]
	s_add_u32 m0, m0, 0x1000
	s_nop 0
	global_load_lds_dwordx4 v254, s[24:25]
	s_add_u32 m0, m0, 0x1000
	s_nop 0
	global_load_lds_dwordx4 v254, s[26:27]
	s_add_u32 m0, m0, 0x1000
	s_nop 0
	global_load_lds_dwordx4 v254, s[28:29]
	s_add_u32 m0, m0, 0x1000
	s_nop 0
	global_load_lds_dwordx4 v254, s[30:31]
	s_add_u32 m0, m0, 0x1000
	s_nop 0
	global_load_lds_dwordx4 v254, s[34:35]
	v_add_u32_e32 v254, 0x80, v254
	s_add_u32 m0, s36, 0x8000
	s_nop 0
	global_load_lds_dwordx4 v254, s[18:19]
	s_add_u32 m0, m0, 0x1000
	s_nop 0
	global_load_lds_dwordx4 v254, s[20:21]
	s_add_u32 m0, m0, 0x1000
	s_nop 0
	global_load_lds_dwordx4 v254, s[22:23]
	s_add_u32 m0, m0, 0x1000
	s_nop 0
	global_load_lds_dwordx4 v254, s[24:25]
	s_add_u32 m0, m0, 0x1000
	s_nop 0
	global_load_lds_dwordx4 v254, s[26:27]
	s_add_u32 m0, m0, 0x1000
	s_nop 0
	global_load_lds_dwordx4 v254, s[28:29]
	s_add_u32 m0, m0, 0x1000
	s_nop 0
	global_load_lds_dwordx4 v254, s[30:31]
	s_add_u32 m0, m0, 0x1000
	s_nop 0
	global_load_lds_dwordx4 v254, s[34:35]
	v_add_u32_e32 v254, 0x80, v254
	v_mov_b32_e32 v48, 0
	v_mov_b32_e32 v49, 0
	v_mov_b32_e32 v50, 0
	v_mov_b32_e32 v51, 0
	v_mov_b32_e32 v52, 0
	v_mov_b32_e32 v53, 0
	v_mov_b32_e32 v54, 0
	v_mov_b32_e32 v55, 0
	v_mov_b32_e32 v56, 0
	v_mov_b32_e32 v57, 0
	v_mov_b32_e32 v58, 0
	v_mov_b32_e32 v59, 0
	v_mov_b32_e32 v60, 0
	v_mov_b32_e32 v61, 0
	v_mov_b32_e32 v62, 0
	v_mov_b32_e32 v63, 0
	v_mov_b32_e32 v32, 0
	v_mov_b32_e32 v33, 0
	v_mov_b32_e32 v34, 0
	v_mov_b32_e32 v35, 0
	v_mov_b32_e32 v36, 0
	v_mov_b32_e32 v37, 0
	v_mov_b32_e32 v38, 0
	v_mov_b32_e32 v39, 0
	v_mov_b32_e32 v40, 0
	v_mov_b32_e32 v41, 0
	v_mov_b32_e32 v42, 0
	v_mov_b32_e32 v43, 0
	v_mov_b32_e32 v44, 0
	v_mov_b32_e32 v45, 0
	v_mov_b32_e32 v46, 0
	v_mov_b32_e32 v47, 0
	v_mov_b32_e32 v16, 0
	v_mov_b32_e32 v17, 0
	v_mov_b32_e32 v18, 0
	v_mov_b32_e32 v19, 0
	v_mov_b32_e32 v20, 0
	v_mov_b32_e32 v21, 0
	v_mov_b32_e32 v22, 0
	v_mov_b32_e32 v23, 0
	v_mov_b32_e32 v24, 0
	v_mov_b32_e32 v25, 0
	v_mov_b32_e32 v26, 0
	v_mov_b32_e32 v27, 0
	v_mov_b32_e32 v28, 0
	v_mov_b32_e32 v29, 0
	v_mov_b32_e32 v30, 0
	v_mov_b32_e32 v31, 0
	v_mov_b32_e32 v0, 0
	v_mov_b32_e32 v1, 0
	v_mov_b32_e32 v2, 0
	v_mov_b32_e32 v3, 0
	v_mov_b32_e32 v4, 0
	v_mov_b32_e32 v5, 0
	v_mov_b32_e32 v6, 0
	v_mov_b32_e32 v7, 0
	v_mov_b32_e32 v8, 0
	v_mov_b32_e32 v9, 0
	v_mov_b32_e32 v10, 0
	v_mov_b32_e32 v11, 0
	v_mov_b32_e32 v12, 0
	v_mov_b32_e32 v13, 0
	v_mov_b32_e32 v14, 0
	v_mov_b32_e32 v15, 0
	s_mov_b32 s37, 7

.LBB0_1637:
	s_ashr_i32 s2, s10, 31
	s_lshr_b32 s2, s2, 26
	s_add_i32 s2, s10, s2
	s_ashr_i32 s11, s2, 6
	s_andn2_b32 s2, s2, 63
	s_sub_i32 s2, s10, s2
	s_ashr_i32 s16, s2, 31
	s_lshr_b32 s16, s16, 29
	s_add_i32 s16, s2, s16
	s_and_b32 s52, s16, -8
	s_lshl_b32 s11, s11, 3
	s_sub_i32 s2, s2, s52
	s_add_i32 s2, s2, s11
	s_lshl_b32 s16, s16, 4
	s_lshl_b32 s11, s2, 7
	s_and_b32 s16, s16, 0xffffff80
	s_mul_i32 s38, s2, 0xb0000
	s_add_u32 s18, s14, s38
	s_addc_u32 s19, s15, 0
	s_add_u32 s18, s18, 0x879f000
	s_addc_u32 s19, s19, 0
	s_add_u32 s20, s18, 0x2c000
	s_addc_u32 s21, s19, 0
	s_add_u32 s22, s20, 0x2c000
	s_addc_u32 s23, s21, 0
	s_add_u32 s24, s22, 0x2c000
	s_addc_u32 s25, s23, 0
	s_mul_i32 s38, s16, 0x1600
	s_add_u32 s26, s14, s38
	s_addc_u32 s27, s15, 0
	s_add_u32 s26, s26, 0x5620000
	s_addc_u32 s27, s27, 0
	s_add_u32 s28, s26, 0x2c000
	s_addc_u32 s29, s27, 0
	s_add_u32 s30, s28, 0x2c000
	s_addc_u32 s31, s29, 0
	s_add_u32 s34, s30, 0x2c000
	s_addc_u32 s35, s31, 0
	v_and_b32_e32 v70, 15, v199
	v_bfe_u32 v71, v199, 4, 2
	v_lshrrev_b32_e32 v72, 1, v70
	v_xor_b32_e32 v71, v71, v72
	v_lshlrev_b32_e32 v71, 4, v71
	v_lshl_or_b32 v71, v70, 7, v71
	v_lshrrev_b32_e32 v72, 6, v199
	v_lshl_add_u32 v198, v72, 12, v71
	v_xor_b32_e32 v202, 64, v198
	v_add_u32_e32 v203, 0x4000, v71
	v_xor_b32_e32 v204, 64, v203
	v_readfirstlane_b32 s36, v77
	v_mov_b32_e32 v254, v64
	s_mov_b32 m0, s36
	s_nop 0
	global_load_lds_dwordx4 v254, s[18:19]
	s_add_u32 m0, m0, 0x1000
	s_nop 0
	global_load_lds_dwordx4 v254, s[20:21]
	s_add_u32 m0, m0, 0x1000
	s_nop 0
	global_load_lds_dwordx4 v254, s[22:23]
	s_add_u32 m0, m0, 0x1000
	s_nop 0
	global_load_lds_dwordx4 v254, s[24:25]
	s_add_u32 m0, m0, 0x1000
	s_nop 0
	global_load_lds_dwordx4 v254, s[26:27]
	s_add_u32 m0, m0, 0x1000
	s_nop 0
	global_load_lds_dwordx4 v254, s[28:29]
	s_add_u32 m0, m0, 0x1000
	s_nop 0
	global_load_lds_dwordx4 v254, s[30:31]
	s_add_u32 m0, m0, 0x1000
	s_nop 0
	global_load_lds_dwordx4 v254, s[34:35]
	v_add_u32_e32 v254, 0x80, v254
	s_add_u32 m0, s36, 0x8000
	s_nop 0
	global_load_lds_dwordx4 v254, s[18:19]
	s_add_u32 m0, m0, 0x1000
	s_nop 0
	global_load_lds_dwordx4 v254, s[20:21]
	s_add_u32 m0, m0, 0x1000
	s_nop 0
	global_load_lds_dwordx4 v254, s[22:23]
	s_add_u32 m0, m0, 0x1000
	s_nop 0
	global_load_lds_dwordx4 v254, s[24:25]
	s_add_u32 m0, m0, 0x1000
	s_nop 0
	global_load_lds_dwordx4 v254, s[26:27]
	s_add_u32 m0, m0, 0x1000
	s_nop 0
	global_load_lds_dwordx4 v254, s[28:29]
	s_add_u32 m0, m0, 0x1000
	s_nop 0
	global_load_lds_dwordx4 v254, s[30:31]
	s_add_u32 m0, m0, 0x1000
	s_nop 0
	global_load_lds_dwordx4 v254, s[34:35]
	v_add_u32_e32 v254, 0x80, v254
	v_mov_b32_e32 v48, 0
	v_mov_b32_e32 v49, 0
	v_mov_b32_e32 v50, 0
	v_mov_b32_e32 v51, 0
	v_mov_b32_e32 v52, 0
	v_mov_b32_e32 v53, 0
	v_mov_b32_e32 v54, 0
	v_mov_b32_e32 v55, 0
	v_mov_b32_e32 v56, 0
	v_mov_b32_e32 v57, 0
	v_mov_b32_e32 v58, 0
	v_mov_b32_e32 v59, 0
	v_mov_b32_e32 v60, 0
	v_mov_b32_e32 v61, 0
	v_mov_b32_e32 v62, 0
	v_mov_b32_e32 v63, 0
	v_mov_b32_e32 v32, 0
	v_mov_b32_e32 v33, 0
	v_mov_b32_e32 v34, 0
	v_mov_b32_e32 v35, 0
	v_mov_b32_e32 v36, 0
	v_mov_b32_e32 v37, 0
	v_mov_b32_e32 v38, 0
	v_mov_b32_e32 v39, 0
	v_mov_b32_e32 v40, 0
	v_mov_b32_e32 v41, 0
	v_mov_b32_e32 v42, 0
	v_mov_b32_e32 v43, 0
	v_mov_b32_e32 v44, 0
	v_mov_b32_e32 v45, 0
	v_mov_b32_e32 v46, 0
	v_mov_b32_e32 v47, 0
	v_mov_b32_e32 v16, 0
	v_mov_b32_e32 v17, 0
	v_mov_b32_e32 v18, 0
	v_mov_b32_e32 v19, 0
	v_mov_b32_e32 v20, 0
	v_mov_b32_e32 v21, 0
	v_mov_b32_e32 v22, 0
	v_mov_b32_e32 v23, 0
	v_mov_b32_e32 v24, 0
	v_mov_b32_e32 v25, 0
	v_mov_b32_e32 v26, 0
	v_mov_b32_e32 v27, 0
	v_mov_b32_e32 v28, 0
	v_mov_b32_e32 v29, 0
	v_mov_b32_e32 v30, 0
	v_mov_b32_e32 v31, 0
	v_mov_b32_e32 v0, 0
	v_mov_b32_e32 v1, 0
	v_mov_b32_e32 v2, 0
	v_mov_b32_e32 v3, 0
	v_mov_b32_e32 v4, 0
	v_mov_b32_e32 v5, 0
	v_mov_b32_e32 v6, 0
	v_mov_b32_e32 v7, 0
	v_mov_b32_e32 v8, 0
	v_mov_b32_e32 v9, 0
	v_mov_b32_e32 v10, 0
	v_mov_b32_e32 v11, 0
	v_mov_b32_e32 v12, 0
	v_mov_b32_e32 v13, 0
	v_mov_b32_e32 v14, 0
	v_mov_b32_e32 v15, 0
	s_mov_b32 s37, 21
.Lgk_loop_p26:
	s_waitcnt vmcnt(8)
	s_barrier
	ds_read_b128 v[70:73], v198
	ds_read_b128 v[102:105], v198 offset:2048
	ds_read_b128 v[114:117], v203
	ds_read_b128 v[118:121], v203 offset:2048
	ds_read_b128 v[122:125], v203 offset:4096
	ds_read_b128 v[126:129], v203 offset:6144
	ds_read_b128 v[130:133], v203 offset:8192
	ds_read_b128 v[134:137], v203 offset:10240
	ds_read_b128 v[138:141], v203 offset:12288
	ds_read_b128 v[162:165], v203 offset:14336
	ds_read_b128 v[106:109], v202
	ds_read_b128 v[110:113], v202 offset:2048
	ds_read_b128 v[166:169], v204
	ds_read_b128 v[170:173], v204 offset:2048
	ds_read_b128 v[174:177], v204 offset:4096
	ds_read_b128 v[178:181], v204 offset:6144
	ds_read_b128 v[182:185], v204 offset:8192
	ds_read_b128 v[186:189], v204 offset:10240
	ds_read_b128 v[190:193], v204 offset:12288
	ds_read_b128 v[194:197], v204 offset:14336
	s_waitcnt lgkmcnt(0)
	s_barrier
	s_mov_b32 m0, s36
	s_setprio 1
	v_mfma_f32_16x16x32_bf16 v[0:3], v[70:73], v[114:117], v[0:3]
	v_mfma_f32_16x16x32_bf16 v[4:7], v[70:73], v[118:121], v[4:7]
	v_mfma_f32_16x16x32_bf16 v[8:11], v[70:73], v[122:125], v[8:11]
	v_mfma_f32_16x16x32_bf16 v[12:15], v[70:73], v[126:129], v[12:15]
	global_load_lds_dwordx4 v254, s[18:19]
	s_add_u32 m0, m0, 0x1000
	v_mfma_f32_16x16x32_bf16 v[16:19], v[70:73], v[130:133], v[16:19]
	v_mfma_f32_16x16x32_bf16 v[20:23], v[70:73], v[134:137], v[20:23]
	v_mfma_f32_16x16x32_bf16 v[24:27], v[70:73], v[138:141], v[24:27]
	v_mfma_f32_16x16x32_bf16 v[28:31], v[70:73], v[162:165], v[28:31]
	global_load_lds_dwordx4 v254, s[20:21]
	s_add_u32 m0, m0, 0x1000
	v_mfma_f32_16x16x32_bf16 v[32:35], v[102:105], v[114:117], v[32:35]
	v_mfma_f32_16x16x32_bf16 v[36:39], v[102:105], v[118:121], v[36:39]
	v_mfma_f32_16x16x32_bf16 v[40:43], v[102:105], v[122:125], v[40:43]
	v_mfma_f32_16x16x32_bf16 v[44:47], v[102:105], v[126:129], v[44:47]
	global_load_lds_dwordx4 v254, s[22:23]
	s_add_u32 m0, m0, 0x1000
	v_mfma_f32_16x16x32_bf16 v[48:51], v[102:105], v[130:133], v[48:51]
	v_mfma_f32_16x16x32_bf16 v[52:55], v[102:105], v[134:137], v[52:55]
	v_mfma_f32_16x16x32_bf16 v[56:59], v[102:105], v[138:141], v[56:59]
	v_mfma_f32_16x16x32_bf16 v[60:63], v[102:105], v[162:165], v[60:63]
	global_load_lds_dwordx4 v254, s[24:25]
	s_add_u32 m0, m0, 0x1000
	v_mfma_f32_16x16x32_bf16 v[0:3], v[106:109], v[166:169], v[0:3]
	v_mfma_f32_16x16x32_bf16 v[4:7], v[106:109], v[170:173], v[4:7]
	v_mfma_f32_16x16x32_bf16 v[8:11], v[106:109], v[174:177], v[8:11]
	v_mfma_f32_16x16x32_bf16 v[12:15], v[106:109], v[178:181], v[12:15]
	global_load_lds_dwordx4 v254, s[26:27]
	s_add_u32 m0, m0, 0x1000
	v_mfma_f32_16x16x32_bf16 v[16:19], v[106:109], v[182:185], v[16:19]
	v_mfma_f32_16x16x32_bf16 v[20:23], v[106:109], v[186:189], v[20:23]
	v_mfma_f32_16x16x32_bf16 v[24:27], v[106:109], v[190:193], v[24:27]
	v_mfma_f32_16x16x32_bf16 v[28:31], v[106:109], v[194:197], v[28:31]
	global_load_lds_dwordx4 v254, s[28:29]
	s_add_u32 m0, m0, 0x1000
	v_mfma_f32_16x16x32_bf16 v[32:35], v[110:113], v[166:169], v[32:35]
	v_mfma_f32_16x16x32_bf16 v[36:39], v[110:113], v[170:173], v[36:39]
	v_mfma_f32_16x16x32_bf16 v[40:43], v[110:113], v[174:177], v[40:43]
	v_mfma_f32_16x16x32_bf16 v[44:47], v[110:113], v[178:181], v[44:47]
	global_load_lds_dwordx4 v254, s[30:31]
	s_add_u32 m0, m0, 0x1000
	v_mfma_f32_16x16x32_bf16 v[48:51], v[110:113], v[182:185], v[48:51]
	v_mfma_f32_16x16x32_bf16 v[52:55], v[110:113], v[186:189], v[52:55]
	v_mfma_f32_16x16x32_bf16 v[56:59], v[110:113], v[190:193], v[56:59]
	v_mfma_f32_16x16x32_bf16 v[60:63], v[110:113], v[194:197], v[60:63]
	global_load_lds_dwordx4 v254, s[34:35]
	s_setprio 0
	v_add_u32_e32 v254, 0x80, v254
	s_waitcnt vmcnt(8)
	s_barrier
	ds_read_b128 v[70:73], v198 offset:32768
	ds_read_b128 v[102:105], v198 offset:34816
	ds_read_b128 v[114:117], v203 offset:32768
	ds_read_b128 v[118:121], v203 offset:34816
	ds_read_b128 v[122:125], v203 offset:36864
	ds_read_b128 v[126:129], v203 offset:38912
	ds_read_b128 v[130:133], v203 offset:40960
	ds_read_b128 v[134:137], v203 offset:43008
	ds_read_b128 v[138:141], v203 offset:45056
	ds_read_b128 v[162:165], v203 offset:47104
	ds_read_b128 v[106:109], v202 offset:32768
	ds_read_b128 v[110:113], v202 offset:34816
	ds_read_b128 v[166:169], v204 offset:32768
	ds_read_b128 v[170:173], v204 offset:34816
	ds_read_b128 v[174:177], v204 offset:36864
	ds_read_b128 v[178:181], v204 offset:38912
	ds_read_b128 v[182:185], v204 offset:40960
	ds_read_b128 v[186:189], v204 offset:43008
	ds_read_b128 v[190:193], v204 offset:45056
	ds_read_b128 v[194:197], v204 offset:47104
	s_waitcnt lgkmcnt(0)
	s_barrier
	s_add_u32 m0, s36, 0x8000
	s_setprio 1
	v_mfma_f32_16x16x32_bf16 v[0:3], v[70:73], v[114:117], v[0:3]
	v_mfma_f32_16x16x32_bf16 v[4:7], v[70:73], v[118:121], v[4:7]
	v_mfma_f32_16x16x32_bf16 v[8:11], v[70:73], v[122:125], v[8:11]
	v_mfma_f32_16x16x32_bf16 v[12:15], v[70:73], v[126:129], v[12:15]
	global_load_lds_dwordx4 v254, s[18:19]
	s_add_u32 m0, m0, 0x1000
	v_mfma_f32_16x16x32_bf16 v[16:19], v[70:73], v[130:133], v[16:19]
	v_mfma_f32_16x16x32_bf16 v[20:23], v[70:73], v[134:137], v[20:23]
	v_mfma_f32_16x16x32_bf16 v[24:27], v[70:73], v[138:141], v[24:27]
	v_mfma_f32_16x16x32_bf16 v[28:31], v[70:73], v[162:165], v[28:31]
	global_load_lds_dwordx4 v254, s[20:21]
	s_add_u32 m0, m0, 0x1000
	v_mfma_f32_16x16x32_bf16 v[32:35], v[102:105], v[114:117], v[32:35]
	v_mfma_f32_16x16x32_bf16 v[36:39], v[102:105], v[118:121], v[36:39]
	v_mfma_f32_16x16x32_bf16 v[40:43], v[102:105], v[122:125], v[40:43]
	v_mfma_f32_16x16x32_bf16 v[44:47], v[102:105], v[126:129], v[44:47]
	global_load_lds_dwordx4 v254, s[22:23]
	s_add_u32 m0, m0, 0x1000
	v_mfma_f32_16x16x32_bf16 v[48:51], v[102:105], v[130:133], v[48:51]
	v_mfma_f32_16x16x32_bf16 v[52:55], v[102:105], v[134:137], v[52:55]
	v_mfma_f32_16x16x32_bf16 v[56:59], v[102:105], v[138:141], v[56:59]
	v_mfma_f32_16x16x32_bf16 v[60:63], v[102:105], v[162:165], v[60:63]
	global_load_lds_dwordx4 v254, s[24:25]
	s_add_u32 m0, m0, 0x1000
	v_mfma_f32_16x16x32_bf16 v[0:3], v[106:109], v[166:169], v[0:3]
	v_mfma_f32_16x16x32_bf16 v[4:7], v[106:109], v[170:173], v[4:7]
	v_mfma_f32_16x16x32_bf16 v[8:11], v[106:109], v[174:177], v[8:11]
	v_mfma_f32_16x16x32_bf16 v[12:15], v[106:109], v[178:181], v[12:15]
	global_load_lds_dwordx4 v254, s[26:27]
	s_add_u32 m0, m0, 0x1000
	v_mfma_f32_16x16x32_bf16 v[16:19], v[106:109], v[182:185], v[16:19]
	v_mfma_f32_16x16x32_bf16 v[20:23], v[106:109], v[186:189], v[20:23]
	v_mfma_f32_16x16x32_bf16 v[24:27], v[106:109], v[190:193], v[24:27]
	v_mfma_f32_16x16x32_bf16 v[28:31], v[106:109], v[194:197], v[28:31]
	global_load_lds_dwordx4 v254, s[28:29]
	s_add_u32 m0, m0, 0x1000
	v_mfma_f32_16x16x32_bf16 v[32:35], v[110:113], v[166:169], v[32:35]
	v_mfma_f32_16x16x32_bf16 v[36:39], v[110:113], v[170:173], v[36:39]
	v_mfma_f32_16x16x32_bf16 v[40:43], v[110:113], v[174:177], v[40:43]
	v_mfma_f32_16x16x32_bf16 v[44:47], v[110:113], v[178:181], v[44:47]
	global_load_lds_dwordx4 v254, s[30:31]
	s_add_u32 m0, m0, 0x1000
	v_mfma_f32_16x16x32_bf16 v[48:51], v[110:113], v[182:185], v[48:51]
	v_mfma_f32_16x16x32_bf16 v[52:55], v[110:113], v[186:189], v[52:55]
	v_mfma_f32_16x16x32_bf16 v[56:59], v[110:113], v[190:193], v[56:59]
	v_mfma_f32_16x16x32_bf16 v[60:63], v[110:113], v[194:197], v[60:63]
	global_load_lds_dwordx4 v254, s[34:35]
	s_setprio 0
	v_add_u32_e32 v254, 0x80, v254
	s_sub_u32 s37, s37, 1
	s_cmp_lg_u32 s37, 0
	s_cbranch_scc1 .Lgk_loop_p26
	s_waitcnt vmcnt(8)
	s_barrier
	ds_read_b128 v[70:73], v198
	ds_read_b128 v[102:105], v198 offset:2048
	ds_read_b128 v[114:117], v203
	ds_read_b128 v[118:121], v203 offset:2048
	ds_read_b128 v[122:125], v203 offset:4096
	ds_read_b128 v[126:129], v203 offset:6144
	ds_read_b128 v[130:133], v203 offset:8192
	ds_read_b128 v[134:137], v203 offset:10240
	ds_read_b128 v[138:141], v203 offset:12288
	ds_read_b128 v[162:165], v203 offset:14336
	ds_read_b128 v[106:109], v202
	ds_read_b128 v[110:113], v202 offset:2048
	ds_read_b128 v[166:169], v204
	ds_read_b128 v[170:173], v204 offset:2048
	ds_read_b128 v[174:177], v204 offset:4096
	ds_read_b128 v[178:181], v204 offset:6144
	ds_read_b128 v[182:185], v204 offset:8192
	ds_read_b128 v[186:189], v204 offset:10240
	ds_read_b128 v[190:193], v204 offset:12288
	ds_read_b128 v[194:197], v204 offset:14336
	s_waitcnt lgkmcnt(0)
	s_barrier
	s_setprio 1
	v_mfma_f32_16x16x32_bf16 v[0:3], v[70:73], v[114:117], v[0:3]
	v_mfma_f32_16x16x32_bf16 v[4:7], v[70:73], v[118:121], v[4:7]
	v_mfma_f32_16x16x32_bf16 v[8:11], v[70:73], v[122:125], v[8:11]
	v_mfma_f32_16x16x32_bf16 v[12:15], v[70:73], v[126:129], v[12:15]
	v_mfma_f32_16x16x32_bf16 v[16:19], v[70:73], v[130:133], v[16:19]
	v_mfma_f32_16x16x32_bf16 v[20:23], v[70:73], v[134:137], v[20:23]
	v_mfma_f32_16x16x32_bf16 v[24:27], v[70:73], v[138:141], v[24:27]
	v_mfma_f32_16x16x32_bf16 v[28:31], v[70:73], v[162:165], v[28:31]
	v_mfma_f32_16x16x32_bf16 v[32:35], v[102:105], v[114:117], v[32:35]
	v_mfma_f32_16x16x32_bf16 v[36:39], v[102:105], v[118:121], v[36:39]
	v_mfma_f32_16x16x32_bf16 v[40:43], v[102:105], v[122:125], v[40:43]
	v_mfma_f32_16x16x32_bf16 v[44:47], v[102:105], v[126:129], v[44:47]
	v_mfma_f32_16x16x32_bf16 v[48:51], v[102:105], v[130:133], v[48:51]
	v_mfma_f32_16x16x32_bf16 v[52:55], v[102:105], v[134:137], v[52:55]
	v_mfma_f32_16x16x32_bf16 v[56:59], v[102:105], v[138:141], v[56:59]
	v_mfma_f32_16x16x32_bf16 v[60:63], v[102:105], v[162:165], v[60:63]
	v_mfma_f32_16x16x32_bf16 v[0:3], v[106:109], v[166:169], v[0:3]
	v_mfma_f32_16x16x32_bf16 v[4:7], v[106:109], v[170:173], v[4:7]
	v_mfma_f32_16x16x32_bf16 v[8:11], v[106:109], v[174:177], v[8:11]
	v_mfma_f32_16x16x32_bf16 v[12:15], v[106:109], v[178:181], v[12:15]
	v_mfma_f32_16x16x32_bf16 v[16:19], v[106:109], v[182:185], v[16:19]
	v_mfma_f32_16x16x32_bf16 v[20:23], v[106:109], v[186:189], v[20:23]
	v_mfma_f32_16x16x32_bf16 v[24:27], v[106:109], v[190:193], v[24:27]
	v_mfma_f32_16x16x32_bf16 v[28:31], v[106:109], v[194:197], v[28:31]
	v_mfma_f32_16x16x32_bf16 v[32:35], v[110:113], v[166:169], v[32:35]
	v_mfma_f32_16x16x32_bf16 v[36:39], v[110:113], v[170:173], v[36:39]
	v_mfma_f32_16x16x32_bf16 v[40:43], v[110:113], v[174:177], v[40:43]
	v_mfma_f32_16x16x32_bf16 v[44:47], v[110:113], v[178:181], v[44:47]
	v_mfma_f32_16x16x32_bf16 v[48:51], v[110:113], v[182:185], v[48:51]
	v_mfma_f32_16x16x32_bf16 v[52:55], v[110:113], v[186:189], v[52:55]
	v_mfma_f32_16x16x32_bf16 v[56:59], v[110:113], v[190:193], v[56:59]
	v_mfma_f32_16x16x32_bf16 v[60:63], v[110:113], v[194:197], v[60:63]
	s_setprio 0
	s_waitcnt vmcnt(0)
	s_barrier
	ds_read_b128 v[70:73], v198 offset:32768
	ds_read_b128 v[102:105], v198 offset:34816
	ds_read_b128 v[114:117], v203 offset:32768
	ds_read_b128 v[118:121], v203 offset:34816
	ds_read_b128 v[122:125], v203 offset:36864
	ds_read_b128 v[126:129], v203 offset:38912
	ds_read_b128 v[130:133], v203 offset:40960
	ds_read_b128 v[134:137], v203 offset:43008
	ds_read_b128 v[138:141], v203 offset:45056
	ds_read_b128 v[162:165], v203 offset:47104
	ds_read_b128 v[106:109], v202 offset:32768
	ds_read_b128 v[110:113], v202 offset:34816
	ds_read_b128 v[166:169], v204 offset:32768
	ds_read_b128 v[170:173], v204 offset:34816
	ds_read_b128 v[174:177], v204 offset:36864
	ds_read_b128 v[178:181], v204 offset:38912
	ds_read_b128 v[182:185], v204 offset:40960
	ds_read_b128 v[186:189], v204 offset:43008
	ds_read_b128 v[190:193], v204 offset:45056
	ds_read_b128 v[194:197], v204 offset:47104
	s_waitcnt lgkmcnt(0)
	s_barrier
	s_setprio 1
	v_mfma_f32_16x16x32_bf16 v[0:3], v[70:73], v[114:117], v[0:3]
	v_mfma_f32_16x16x32_bf16 v[4:7], v[70:73], v[118:121], v[4:7]
	v_mfma_f32_16x16x32_bf16 v[8:11], v[70:73], v[122:125], v[8:11]
	v_mfma_f32_16x16x32_bf16 v[12:15], v[70:73], v[126:129], v[12:15]
	v_mfma_f32_16x16x32_bf16 v[16:19], v[70:73], v[130:133], v[16:19]
	v_mfma_f32_16x16x32_bf16 v[20:23], v[70:73], v[134:137], v[20:23]
	v_mfma_f32_16x16x32_bf16 v[24:27], v[70:73], v[138:141], v[24:27]
	v_mfma_f32_16x16x32_bf16 v[28:31], v[70:73], v[162:165], v[28:31]
	v_mfma_f32_16x16x32_bf16 v[32:35], v[102:105], v[114:117], v[32:35]
	v_mfma_f32_16x16x32_bf16 v[36:39], v[102:105], v[118:121], v[36:39]
	v_mfma_f32_16x16x32_bf16 v[40:43], v[102:105], v[122:125], v[40:43]
	v_mfma_f32_16x16x32_bf16 v[44:47], v[102:105], v[126:129], v[44:47]
	v_mfma_f32_16x16x32_bf16 v[48:51], v[102:105], v[130:133], v[48:51]
	v_mfma_f32_16x16x32_bf16 v[52:55], v[102:105], v[134:137], v[52:55]
	v_mfma_f32_16x16x32_bf16 v[56:59], v[102:105], v[138:141], v[56:59]
	v_mfma_f32_16x16x32_bf16 v[60:63], v[102:105], v[162:165], v[60:63]
	v_mfma_f32_16x16x32_bf16 v[0:3], v[106:109], v[166:169], v[0:3]
	v_mfma_f32_16x16x32_bf16 v[4:7], v[106:109], v[170:173], v[4:7]
	v_mfma_f32_16x16x32_bf16 v[8:11], v[106:109], v[174:177], v[8:11]
	v_mfma_f32_16x16x32_bf16 v[12:15], v[106:109], v[178:181], v[12:15]
	v_mfma_f32_16x16x32_bf16 v[16:19], v[106:109], v[182:185], v[16:19]
	v_mfma_f32_16x16x32_bf16 v[20:23], v[106:109], v[186:189], v[20:23]
	v_mfma_f32_16x16x32_bf16 v[24:27], v[106:109], v[190:193], v[24:27]
	v_mfma_f32_16x16x32_bf16 v[28:31], v[106:109], v[194:197], v[28:31]
	v_mfma_f32_16x16x32_bf16 v[32:35], v[110:113], v[166:169], v[32:35]
	v_mfma_f32_16x16x32_bf16 v[36:39], v[110:113], v[170:173], v[36:39]
	v_mfma_f32_16x16x32_bf16 v[40:43], v[110:113], v[174:177], v[40:43]
	v_mfma_f32_16x16x32_bf16 v[44:47], v[110:113], v[178:181], v[44:47]
	v_mfma_f32_16x16x32_bf16 v[48:51], v[110:113], v[182:185], v[48:51]
	v_mfma_f32_16x16x32_bf16 v[52:55], v[110:113], v[186:189], v[52:55]
	v_mfma_f32_16x16x32_bf16 v[56:59], v[110:113], v[190:193], v[56:59]
	v_mfma_f32_16x16x32_bf16 v[60:63], v[110:113], v[194:197], v[60:63]
	s_setprio 0
	s_nop 7
	s_nop 7
	v_and_b32_e32 v72, 63, v199
	v_lshrrev_b32_e32 v73, 6, v199
	v_lshlrev_b32_e32 v73, 14, v73
	v_lshl_add_u32 v70, v72, 4, v73
	v_and_b32_e32 v71, 15, v72
	v_lshl_add_u32 v71, v71, 4, v73
	v_bfe_u32 v73, v72, 4, 1
	v_lshl_add_u32 v71, v73, 10, v71
	v_bfe_u32 v73, v72, 5, 1
	v_lshl_add_u32 v71, v73, 8, v71
	ds_write_b128 v70, v[0:3]
	ds_write_b128 v70, v[4:7] offset:1024
	ds_write_b128 v70, v[8:11] offset:2048
	ds_write_b128 v70, v[12:15] offset:3072
	ds_write_b128 v70, v[16:19] offset:4096
	ds_write_b128 v70, v[20:23] offset:5120
	ds_write_b128 v70, v[24:27] offset:6144
	ds_write_b128 v70, v[28:31] offset:7168
	ds_write_b128 v70, v[32:35] offset:8192
	ds_write_b128 v70, v[36:39] offset:9216
	ds_write_b128 v70, v[40:43] offset:10240
	ds_write_b128 v70, v[44:47] offset:11264
	ds_write_b128 v70, v[48:51] offset:12288
	ds_write_b128 v70, v[52:55] offset:13312
	ds_write_b128 v70, v[56:59] offset:14336
	ds_write_b128 v70, v[60:63] offset:15360
	s_waitcnt lgkmcnt(0)
	ds_read_b128 v[48:51], v71
	ds_read_b128 v[52:55], v71 offset:512
	ds_read_b128 v[56:59], v71 offset:8192
	ds_read_b128 v[60:63], v71 offset:8704
	ds_read_b128 v[32:35], v71 offset:2048
	ds_read_b128 v[36:39], v71 offset:2560
	ds_read_b128 v[40:43], v71 offset:10240
	ds_read_b128 v[44:47], v71 offset:10752
	ds_read_b128 v[16:19], v71 offset:4096
	ds_read_b128 v[20:23], v71 offset:4608
	ds_read_b128 v[24:27], v71 offset:12288
	ds_read_b128 v[28:31], v71 offset:12800
	ds_read_b128 v[0:3], v71 offset:6144
	ds_read_b128 v[4:7], v71 offset:6656
	ds_read_b128 v[8:11], v71 offset:14336
	ds_read_b128 v[12:15], v71 offset:14848
	s_waitcnt lgkmcnt(0)
	s_barrier
	s_branch .LBB0_1636
